# GEMM super-phases: k-inner MFMA order plus all s_setprio flips around the MFMA blocks removed
# speedup vs baseline: 1.0108x; 1.0028x over previous
; #define PG8_STAGE(bufoff, gbase, voff) do { _Pragma("unroll") for (int _i = 0; _i < 2; ++_i) \
;         __builtin_amdgcn_global_load_lds((const unsigned*)((const char*)(gbase) + (voff)[_i]), (PG8_LAS unsigned*)(lds + (bufoff) + ldsw + _i * 8192), 16, 0, 0); } while (0)
; #define PG8_LDA(dst, b, h) do { _Pragma("unroll") for (int m = 0; m < 4; ++m) _Pragma("unroll") for (int k = 0; k < 2; ++k) dst[m][k] = *(const PG8_LAS bf16x8*)(lds + PG8_SA(b, h) + aoff + m * 2048 + k * 1024); } while (0)
; #define PG8_LDB(dst, b, h) do { _Pragma("unroll") for (int n = 0; n < 2; ++n) _Pragma("unroll") for (int k = 0; k < 2; ++k) dst[n][k] = *(const PG8_LAS bf16x8*)(lds + PG8_SB(b, h) + boff + n * 2048 + k * 1024); } while (0)
; #define PG8_MMA(ai, bj, At, Bt) do { __builtin_amdgcn_s_setprio(1); _Pragma("unroll") for (int m = 0; m < 4; ++m) _Pragma("unroll") for (int n = 0; n < 2; ++n) _Pragma("unroll") for (int k = 0; k < 2; ++k) \
;         acc[ai][bj][m][n] = __builtin_amdgcn_mfma_f32_16x16x32_bf16(Bt[n][k], At[m][k], acc[ai][bj][m][n], 0, 0, 0); __builtin_amdgcn_s_setprio(0); } while (0)
; #define PG8_WAIT_V(n) asm volatile("s_waitcnt vmcnt(" #n ")" ::: "memory")
; #define PG8_WAIT_L(n) asm volatile("s_waitcnt lgkmcnt(" #n ")" ::: "memory")
; template <class Epi, class Sched, bool ALIGN_EPI = false, bool SP2 = false>
; __device__ __forceinline__ void gemm_phase(PG8_LAS unsigned char* lds, const Gemm g, const Sched& S, const Epi& E, const int tid) {
;     ...
;             const bool last = (t == nt - 2);
;             const char* a1 = cA + (size_t)(t + 1) * kstep;
;             const char* a2 = last ? nA : cA + (size_t)(t + 2) * kstep; const char* b2 = last ? nB : cB + (size_t)(t + 2) * kstep;
;             const char* a3 = a2 + kstep; const char* b3 = b2 + kstep;
;             if (last && has_next) S.a_ready(nxt);
;             if constexpr (SP2) {
;             PG8_LDB(B0, 0, 0); PG8_LDB(B1, 0, 1); PG8_SCHED; PG8_LDA(At, 0, 0); PG8_STAGE(PG8_SA(1, 1), a1 + hstep, voffA);
;             PG8_WAIT_V(8); PG8_WAIT_L(0); PG8_BAR; PG8_MMA(0, 0, At, B0); PG8_MMA(0, 1, At, B1); PG8_BAR; PG8_SCHED;
;             PG8_LDA(At, 0, 1); PG8_STAGE(PG8_SB(0, 0), b2, voffB); PG8_STAGE(PG8_SB(0, 1), b2 + hstep, voffB); PG8_STAGE(PG8_SA(0, 0), a2, voffA);
;             PG8_WAIT_V(8); PG8_WAIT_L(0); PG8_BAR; PG8_MMA(1, 0, At, B0); PG8_MMA(1, 1, At, B1); PG8_BAR; PG8_SCHED;
.LBB0_120:
	ds_read_b128 v[122:125], v191
	ds_read_b128 v[126:129], v192
	ds_read_b128 v[138:141], v193
	ds_read_b128 v[142:145], v194
	ds_read_b128 v[146:149], v195
	ds_read_b128 v[150:153], v196
	ds_read_b128 v[164:167], v197
	ds_read_b128 v[168:171], v198
	s_add_u32 s43, s30, 0xfffc0080
	s_addc_u32 s45, s31, -1
	s_cmp_eq_u32 s27, 12
	s_cselect_b32 s87, s5, s45
	s_cselect_b32 s86, s15, s43
	s_cselect_b32 s85, s20, s26
	s_cselect_b32 s84, s21, s24
	s_mov_b32 m0, s38
	v_lshl_add_u64 v[188:189], s[30:31], 0, v[160:161]
	ds_read_b128 v[172:175], v190
	ds_read_b128 v[176:179], v190 offset:1024
	ds_read_b128 v[180:183], v190 offset:2048
	ds_read_b128 v[184:187], v190 offset:3072
	ds_read_b128 v[214:217], v190 offset:4096
	ds_read_b128 v[218:221], v190 offset:5120
	ds_read_b128 v[222:225], v190 offset:6144
	ds_read_b128 v[226:229], v190 offset:7168
	global_load_lds_dwordx4 v[188:189], off
	v_lshl_add_u64 v[188:189], s[30:31], 0, v[162:163]
	s_mov_b32 m0, s0
	s_nop 0
	global_load_lds_dwordx4 v[188:189], off
	s_waitcnt vmcnt(8)
	s_waitcnt lgkmcnt(0)
	s_barrier
	s_waitcnt lgkmcnt(0)
	v_mfma_f32_16x16x32_bf16 v[134:137], v[122:125], v[172:175], v[134:137]
	v_mfma_f32_16x16x32_bf16 v[134:137], v[126:129], v[176:179], v[134:137]
	v_mfma_f32_16x16x32_bf16 v[130:133], v[138:141], v[172:175], v[130:133]
	v_mfma_f32_16x16x32_bf16 v[130:133], v[142:145], v[176:179], v[130:133]
	v_mfma_f32_16x16x32_bf16 v[118:121], v[122:125], v[180:183], v[118:121]
	v_mfma_f32_16x16x32_bf16 v[118:121], v[126:129], v[184:187], v[118:121]
	v_mfma_f32_16x16x32_bf16 v[114:117], v[138:141], v[180:183], v[114:117]
	v_mfma_f32_16x16x32_bf16 v[114:117], v[142:145], v[184:187], v[114:117]
	v_mfma_f32_16x16x32_bf16 v[110:113], v[122:125], v[214:217], v[110:113]
	v_mfma_f32_16x16x32_bf16 v[110:113], v[126:129], v[218:221], v[110:113]
	v_mfma_f32_16x16x32_bf16 v[106:109], v[138:141], v[214:217], v[106:109]
	v_mfma_f32_16x16x32_bf16 v[106:109], v[142:145], v[218:221], v[106:109]
	v_mfma_f32_16x16x32_bf16 v[102:105], v[122:125], v[222:225], v[102:105]
	v_mfma_f32_16x16x32_bf16 v[102:105], v[126:129], v[226:229], v[102:105]
	v_mfma_f32_16x16x32_bf16 v[98:101], v[138:141], v[222:225], v[98:101]
	v_mfma_f32_16x16x32_bf16 v[98:101], v[142:145], v[226:229], v[98:101]
	v_mfma_f32_16x16x32_bf16 v[62:65], v[146:149], v[172:175], v[62:65]
	v_mfma_f32_16x16x32_bf16 v[62:65], v[150:153], v[176:179], v[62:65]
	v_mfma_f32_16x16x32_bf16 v[58:61], v[164:167], v[172:175], v[58:61]
	v_mfma_f32_16x16x32_bf16 v[58:61], v[168:171], v[176:179], v[58:61]
	v_mfma_f32_16x16x32_bf16 v[54:57], v[146:149], v[180:183], v[54:57]
	v_mfma_f32_16x16x32_bf16 v[54:57], v[150:153], v[184:187], v[54:57]
	v_mfma_f32_16x16x32_bf16 v[50:53], v[164:167], v[180:183], v[50:53]
	v_mfma_f32_16x16x32_bf16 v[50:53], v[168:171], v[184:187], v[50:53]
	v_mfma_f32_16x16x32_bf16 v[46:49], v[146:149], v[214:217], v[46:49]
	v_mfma_f32_16x16x32_bf16 v[46:49], v[150:153], v[218:221], v[46:49]
	v_mfma_f32_16x16x32_bf16 v[42:45], v[164:167], v[214:217], v[42:45]
	v_mfma_f32_16x16x32_bf16 v[42:45], v[168:171], v[218:221], v[42:45]
	v_mfma_f32_16x16x32_bf16 v[38:41], v[146:149], v[222:225], v[38:41]
	v_mfma_f32_16x16x32_bf16 v[38:41], v[150:153], v[226:229], v[38:41]
	v_mfma_f32_16x16x32_bf16 v[34:37], v[164:167], v[222:225], v[34:37]
	v_mfma_f32_16x16x32_bf16 v[34:37], v[168:171], v[226:229], v[34:37]
	s_barrier
	s_mov_b32 m0, s6
	v_lshl_add_u64 v[188:189], s[84:85], 0, v[0:1]
	s_add_u32 s50, s84, 0x40000
	ds_read_b128 v[172:175], v190 offset:16384
	ds_read_b128 v[176:179], v190 offset:17408
	ds_read_b128 v[180:183], v190 offset:18432
	ds_read_b128 v[184:187], v190 offset:19456
	ds_read_b128 v[214:217], v190 offset:20480
	ds_read_b128 v[218:221], v190 offset:21504
	ds_read_b128 v[222:225], v190 offset:22528
	ds_read_b128 v[226:229], v190 offset:23552
	global_load_lds_dwordx4 v[188:189], off
	v_lshl_add_u64 v[208:209], s[84:85], 0, v[154:155]
	s_mov_b32 m0, s8
	s_addc_u32 s51, s85, 0
	global_load_lds_dwordx4 v[208:209], off
	v_lshl_add_u64 v[210:211], s[50:51], 0, v[0:1]
	s_mov_b32 m0, s9
	v_lshl_add_u64 v[212:213], s[86:87], 0, v[156:157]
	global_load_lds_dwordx4 v[210:211], off
	v_lshl_add_u64 v[210:211], s[50:51], 0, v[154:155]
	s_mov_b32 m0, s14
	s_nop 0
	global_load_lds_dwordx4 v[210:211], off
	v_lshl_add_u64 v[210:211], s[86:87], 0, v[158:159]
	s_mov_b32 m0, s17
	s_nop 0
	global_load_lds_dwordx4 v[210:211], off
	s_mov_b32 m0, s34
	s_nop 0
	global_load_lds_dwordx4 v[212:213], off
	s_waitcnt vmcnt(8)
	s_waitcnt lgkmcnt(0)
	s_barrier
	s_waitcnt lgkmcnt(0)
	v_mfma_f32_16x16x32_bf16 v[94:97], v[122:125], v[172:175], v[94:97]
	v_mfma_f32_16x16x32_bf16 v[94:97], v[126:129], v[176:179], v[94:97]
	v_mfma_f32_16x16x32_bf16 v[90:93], v[138:141], v[172:175], v[90:93]
	v_mfma_f32_16x16x32_bf16 v[90:93], v[142:145], v[176:179], v[90:93]
	v_mfma_f32_16x16x32_bf16 v[86:89], v[122:125], v[180:183], v[86:89]
	v_mfma_f32_16x16x32_bf16 v[86:89], v[126:129], v[184:187], v[86:89]
	v_mfma_f32_16x16x32_bf16 v[82:85], v[138:141], v[180:183], v[82:85]
	v_mfma_f32_16x16x32_bf16 v[82:85], v[142:145], v[184:187], v[82:85]
	v_mfma_f32_16x16x32_bf16 v[78:81], v[122:125], v[214:217], v[78:81]
	v_mfma_f32_16x16x32_bf16 v[78:81], v[126:129], v[218:221], v[78:81]
	v_mfma_f32_16x16x32_bf16 v[74:77], v[138:141], v[214:217], v[74:77]
	v_mfma_f32_16x16x32_bf16 v[74:77], v[142:145], v[218:221], v[74:77]
	v_mfma_f32_16x16x32_bf16 v[70:73], v[122:125], v[222:225], v[70:73]
	v_mfma_f32_16x16x32_bf16 v[70:73], v[126:129], v[226:229], v[70:73]
	v_mfma_f32_16x16x32_bf16 v[66:69], v[138:141], v[222:225], v[66:69]
	v_mfma_f32_16x16x32_bf16 v[66:69], v[142:145], v[226:229], v[66:69]
	v_mfma_f32_16x16x32_bf16 v[30:33], v[146:149], v[172:175], v[30:33]
	v_mfma_f32_16x16x32_bf16 v[30:33], v[150:153], v[176:179], v[30:33]
	v_mfma_f32_16x16x32_bf16 v[26:29], v[164:167], v[172:175], v[26:29]
	v_mfma_f32_16x16x32_bf16 v[26:29], v[168:171], v[176:179], v[26:29]
	v_mfma_f32_16x16x32_bf16 v[22:25], v[146:149], v[180:183], v[22:25]
	v_mfma_f32_16x16x32_bf16 v[22:25], v[150:153], v[184:187], v[22:25]
	v_mfma_f32_16x16x32_bf16 v[18:21], v[164:167], v[180:183], v[18:21]
	v_mfma_f32_16x16x32_bf16 v[18:21], v[168:171], v[184:187], v[18:21]
	v_mfma_f32_16x16x32_bf16 v[14:17], v[146:149], v[214:217], v[14:17]
	v_mfma_f32_16x16x32_bf16 v[14:17], v[150:153], v[218:221], v[14:17]
	v_mfma_f32_16x16x32_bf16 v[10:13], v[164:167], v[214:217], v[10:13]
	v_mfma_f32_16x16x32_bf16 v[10:13], v[168:171], v[218:221], v[10:13]
	v_mfma_f32_16x16x32_bf16 v[6:9], v[146:149], v[222:225], v[6:9]
	v_mfma_f32_16x16x32_bf16 v[6:9], v[150:153], v[226:229], v[6:9]
	v_mfma_f32_16x16x32_bf16 v[2:5], v[164:167], v[222:225], v[2:5]
	v_mfma_f32_16x16x32_bf16 v[2:5], v[168:171], v[226:229], v[2:5]
	s_barrier
; #define PG8_STAGE(bufoff, gbase, voff) do { _Pragma("unroll") for (int _i = 0; _i < 2; ++_i) \
;         __builtin_amdgcn_global_load_lds((const unsigned*)((const char*)(gbase) + (voff)[_i]), (PG8_LAS unsigned*)(lds + (bufoff) + ldsw + _i * 8192), 16, 0, 0); } while (0)
; #define PG8_LDA(dst, b, h) do { _Pragma("unroll") for (int m = 0; m < 4; ++m) _Pragma("unroll") for (int k = 0; k < 2; ++k) dst[m][k] = *(const PG8_LAS bf16x8*)(lds + PG8_SA(b, h) + aoff + m * 2048 + k * 1024); } while (0)
; #define PG8_LDB(dst, b, h) do { _Pragma("unroll") for (int n = 0; n < 2; ++n) _Pragma("unroll") for (int k = 0; k < 2; ++k) dst[n][k] = *(const PG8_LAS bf16x8*)(lds + PG8_SB(b, h) + boff + n * 2048 + k * 1024); } while (0)
; #define PG8_MMA(ai, bj, At, Bt) do { __builtin_amdgcn_s_setprio(1); _Pragma("unroll") for (int m = 0; m < 4; ++m) _Pragma("unroll") for (int n = 0; n < 2; ++n) _Pragma("unroll") for (int k = 0; k < 2; ++k) \
;         acc[ai][bj][m][n] = __builtin_amdgcn_mfma_f32_16x16x32_bf16(Bt[n][k], At[m][k], acc[ai][bj][m][n], 0, 0, 0); __builtin_amdgcn_s_setprio(0); } while (0)
; #define PG8_WAIT_V(n) asm volatile("s_waitcnt vmcnt(" #n ")" ::: "memory")
; #define PG8_WAIT_L(n) asm volatile("s_waitcnt lgkmcnt(" #n ")" ::: "memory")
; #define PG8_BAR __builtin_amdgcn_s_barrier()
; #define PG8_SCHED __builtin_amdgcn_sched_barrier(0)
; template <class Epi, class Sched, bool ALIGN_EPI = false, bool SP2 = false>
; __device__ __forceinline__ void gemm_phase(PG8_LAS unsigned char* lds, const Gemm g, const Sched& S, const Epi& E, const int tid) {
;     ...
;             PG8_LDB(B0, 1, 0); PG8_LDB(B1, 1, 1); PG8_SCHED; PG8_LDA(At, 1, 0); PG8_STAGE(PG8_SA(0, 1), a2 + hstep, voffA);
;             PG8_WAIT_V(8); PG8_WAIT_L(0); PG8_BAR; PG8_MMA(0, 0, At, B0); PG8_MMA(0, 1, At, B1); PG8_BAR; PG8_SCHED;
;             PG8_LDA(At, 1, 1); PG8_STAGE(PG8_SB(1, 0), b3, voffB); PG8_STAGE(PG8_SB(1, 1), b3 + hstep, voffB); PG8_STAGE(PG8_SA(1, 0), a3, voffA);
;             PG8_WAIT_V(8); PG8_WAIT_L(0); PG8_BAR; PG8_MMA(1, 0, At, B0); PG8_MMA(1, 1, At, B1); PG8_BAR; PG8_SCHED;
;     ...
;         if constexpr (ALIGN_EPI) { if (wr == 0) PG8_BAR; }
	ds_read_b128 v[122:125], v199
	ds_read_b128 v[126:129], v200
	ds_read_b128 v[138:141], v201
	ds_read_b128 v[142:145], v202
	ds_read_b128 v[146:149], v203
	ds_read_b128 v[150:153], v204
	ds_read_b128 v[164:167], v205
	ds_read_b128 v[168:171], v206
	s_add_u32 s50, s86, 0x40000
	s_addc_u32 s51, s87, 0
	s_mov_b32 m0, s35
	v_lshl_add_u64 v[230:231], s[50:51], 0, v[158:159]
	ds_read_b128 v[172:175], v190 offset:32768
	ds_read_b128 v[176:179], v190 offset:33792
	ds_read_b128 v[180:183], v190 offset:34816
	ds_read_b128 v[184:187], v190 offset:35840
	ds_read_b128 v[214:217], v190 offset:36864
	ds_read_b128 v[218:221], v190 offset:37888
	ds_read_b128 v[222:225], v190 offset:38912
	ds_read_b128 v[226:229], v190 offset:39936
	global_load_lds_dwordx4 v[230:231], off
	v_lshl_add_u64 v[230:231], s[50:51], 0, v[156:157]
	s_mov_b32 m0, s88
	s_nop 0
	global_load_lds_dwordx4 v[230:231], off
	s_waitcnt vmcnt(8)
	s_waitcnt lgkmcnt(0)
	s_barrier
	s_waitcnt lgkmcnt(0)
	v_mfma_f32_16x16x32_bf16 v[134:137], v[122:125], v[172:175], v[134:137]
	v_mfma_f32_16x16x32_bf16 v[134:137], v[126:129], v[176:179], v[134:137]
	v_mfma_f32_16x16x32_bf16 v[130:133], v[138:141], v[172:175], v[130:133]
	v_mfma_f32_16x16x32_bf16 v[130:133], v[142:145], v[176:179], v[130:133]
	v_mfma_f32_16x16x32_bf16 v[118:121], v[122:125], v[180:183], v[118:121]
	v_mfma_f32_16x16x32_bf16 v[118:121], v[126:129], v[184:187], v[118:121]
	v_mfma_f32_16x16x32_bf16 v[114:117], v[138:141], v[180:183], v[114:117]
	v_mfma_f32_16x16x32_bf16 v[114:117], v[142:145], v[184:187], v[114:117]
	v_mfma_f32_16x16x32_bf16 v[110:113], v[122:125], v[214:217], v[110:113]
	v_mfma_f32_16x16x32_bf16 v[110:113], v[126:129], v[218:221], v[110:113]
	v_mfma_f32_16x16x32_bf16 v[106:109], v[138:141], v[214:217], v[106:109]
	v_mfma_f32_16x16x32_bf16 v[106:109], v[142:145], v[218:221], v[106:109]
	v_mfma_f32_16x16x32_bf16 v[102:105], v[122:125], v[222:225], v[102:105]
	v_mfma_f32_16x16x32_bf16 v[102:105], v[126:129], v[226:229], v[102:105]
	v_mfma_f32_16x16x32_bf16 v[98:101], v[138:141], v[222:225], v[98:101]
	v_mfma_f32_16x16x32_bf16 v[98:101], v[142:145], v[226:229], v[98:101]
	v_mfma_f32_16x16x32_bf16 v[62:65], v[146:149], v[172:175], v[62:65]
	v_mfma_f32_16x16x32_bf16 v[62:65], v[150:153], v[176:179], v[62:65]
	v_mfma_f32_16x16x32_bf16 v[58:61], v[164:167], v[172:175], v[58:61]
	v_mfma_f32_16x16x32_bf16 v[58:61], v[168:171], v[176:179], v[58:61]
	v_mfma_f32_16x16x32_bf16 v[54:57], v[146:149], v[180:183], v[54:57]
	v_mfma_f32_16x16x32_bf16 v[54:57], v[150:153], v[184:187], v[54:57]
	v_mfma_f32_16x16x32_bf16 v[50:53], v[164:167], v[180:183], v[50:53]
	v_mfma_f32_16x16x32_bf16 v[50:53], v[168:171], v[184:187], v[50:53]
	v_mfma_f32_16x16x32_bf16 v[46:49], v[146:149], v[214:217], v[46:49]
	v_mfma_f32_16x16x32_bf16 v[46:49], v[150:153], v[218:221], v[46:49]
	v_mfma_f32_16x16x32_bf16 v[42:45], v[164:167], v[214:217], v[42:45]
	v_mfma_f32_16x16x32_bf16 v[42:45], v[168:171], v[218:221], v[42:45]
	v_mfma_f32_16x16x32_bf16 v[38:41], v[146:149], v[222:225], v[38:41]
	v_mfma_f32_16x16x32_bf16 v[38:41], v[150:153], v[226:229], v[38:41]
	v_mfma_f32_16x16x32_bf16 v[34:37], v[164:167], v[222:225], v[34:37]
	v_mfma_f32_16x16x32_bf16 v[34:37], v[168:171], v[226:229], v[34:37]
	s_barrier
	s_mov_b32 m0, s89
	v_lshl_add_u64 v[188:189], v[188:189], 0, s[12:13]
	s_add_u32 s50, s84, 0x40080
	ds_read_b128 v[172:175], v190 offset:49152
	ds_read_b128 v[176:179], v190 offset:50176
	ds_read_b128 v[180:183], v190 offset:51200
	ds_read_b128 v[184:187], v190 offset:52224
	ds_read_b128 v[214:217], v190 offset:53248
	ds_read_b128 v[218:221], v190 offset:54272
	ds_read_b128 v[222:225], v190 offset:55296
	ds_read_b128 v[226:229], v190 offset:56320
	global_load_lds_dwordx4 v[188:189], off
	v_lshl_add_u64 v[188:189], v[208:209], 0, s[12:13]
	s_mov_b32 m0, s90
	s_addc_u32 s51, s85, 0
	global_load_lds_dwordx4 v[188:189], off
	v_lshl_add_u64 v[188:189], s[50:51], 0, v[0:1]
	s_mov_b32 m0, s41
	s_nop 0
	global_load_lds_dwordx4 v[188:189], off
	v_lshl_add_u64 v[188:189], s[50:51], 0, v[154:155]
	s_mov_b32 m0, s40
	s_nop 0
	global_load_lds_dwordx4 v[188:189], off
	v_lshl_add_u64 v[188:189], v[210:211], 0, s[12:13]
	s_mov_b32 m0, s91
	s_nop 0
	global_load_lds_dwordx4 v[188:189], off
	v_lshl_add_u64 v[188:189], v[212:213], 0, s[12:13]
	s_mov_b32 m0, s1
	s_nop 0
	global_load_lds_dwordx4 v[188:189], off
	s_waitcnt vmcnt(8)
	s_waitcnt lgkmcnt(0)
	s_barrier
	s_waitcnt lgkmcnt(0)
	v_mfma_f32_16x16x32_bf16 v[94:97], v[122:125], v[172:175], v[94:97]
	v_mfma_f32_16x16x32_bf16 v[94:97], v[126:129], v[176:179], v[94:97]
	v_mfma_f32_16x16x32_bf16 v[90:93], v[138:141], v[172:175], v[90:93]
	v_mfma_f32_16x16x32_bf16 v[90:93], v[142:145], v[176:179], v[90:93]
	v_mfma_f32_16x16x32_bf16 v[86:89], v[122:125], v[180:183], v[86:89]
	v_mfma_f32_16x16x32_bf16 v[86:89], v[126:129], v[184:187], v[86:89]
	v_mfma_f32_16x16x32_bf16 v[82:85], v[138:141], v[180:183], v[82:85]
	v_mfma_f32_16x16x32_bf16 v[82:85], v[142:145], v[184:187], v[82:85]
	v_mfma_f32_16x16x32_bf16 v[78:81], v[122:125], v[214:217], v[78:81]
	v_mfma_f32_16x16x32_bf16 v[78:81], v[126:129], v[218:221], v[78:81]
	v_mfma_f32_16x16x32_bf16 v[74:77], v[138:141], v[214:217], v[74:77]
	v_mfma_f32_16x16x32_bf16 v[74:77], v[142:145], v[218:221], v[74:77]
	v_mfma_f32_16x16x32_bf16 v[70:73], v[122:125], v[222:225], v[70:73]
	v_mfma_f32_16x16x32_bf16 v[70:73], v[126:129], v[226:229], v[70:73]
	v_mfma_f32_16x16x32_bf16 v[66:69], v[138:141], v[222:225], v[66:69]
	v_mfma_f32_16x16x32_bf16 v[66:69], v[142:145], v[226:229], v[66:69]
	v_mfma_f32_16x16x32_bf16 v[30:33], v[146:149], v[172:175], v[30:33]
	v_mfma_f32_16x16x32_bf16 v[30:33], v[150:153], v[176:179], v[30:33]
	v_mfma_f32_16x16x32_bf16 v[26:29], v[164:167], v[172:175], v[26:29]
	v_mfma_f32_16x16x32_bf16 v[26:29], v[168:171], v[176:179], v[26:29]
	v_mfma_f32_16x16x32_bf16 v[22:25], v[146:149], v[180:183], v[22:25]
	v_mfma_f32_16x16x32_bf16 v[22:25], v[150:153], v[184:187], v[22:25]
	v_mfma_f32_16x16x32_bf16 v[18:21], v[164:167], v[180:183], v[18:21]
	v_mfma_f32_16x16x32_bf16 v[18:21], v[168:171], v[184:187], v[18:21]
	v_mfma_f32_16x16x32_bf16 v[14:17], v[146:149], v[214:217], v[14:17]
	v_mfma_f32_16x16x32_bf16 v[14:17], v[150:153], v[218:221], v[14:17]
	v_mfma_f32_16x16x32_bf16 v[10:13], v[164:167], v[214:217], v[10:13]
	v_mfma_f32_16x16x32_bf16 v[10:13], v[168:171], v[218:221], v[10:13]
	v_mfma_f32_16x16x32_bf16 v[6:9], v[146:149], v[222:225], v[6:9]
	v_mfma_f32_16x16x32_bf16 v[6:9], v[150:153], v[226:229], v[6:9]
	v_mfma_f32_16x16x32_bf16 v[2:5], v[164:167], v[222:225], v[2:5]
	v_mfma_f32_16x16x32_bf16 v[2:5], v[168:171], v[226:229], v[2:5]
	s_barrier
	s_add_i32 s27, s27, 2
	s_add_u32 s30, s30, 0x100
	s_addc_u32 s31, s31, 0
	s_add_u32 s24, s24, 0x100
	s_addc_u32 s26, s26, 0
	s_cmp_gt_u32 s27, 13
	s_cbranch_scc0 .LBB0_120
	v_readlane_b32 s20, v255, 54
	v_readlane_b32 s21, v255, 55
	s_and_b64 vcc, exec, s[20:21]
	s_cbranch_vccz .LBB0_123
	s_barrier

; #define PG8_STAGE(bufoff, gbase, voff) do { _Pragma("unroll") for (int _i = 0; _i < 2; ++_i) \
;         __builtin_amdgcn_global_load_lds((const unsigned*)((const char*)(gbase) + (voff)[_i]), (PG8_LAS unsigned*)(lds + (bufoff) + ldsw + _i * 8192), 16, 0, 0); } while (0)
; #define PG8_LDA(dst, b, h) do { _Pragma("unroll") for (int m = 0; m < 4; ++m) _Pragma("unroll") for (int k = 0; k < 2; ++k) dst[m][k] = *(const PG8_LAS bf16x8*)(lds + PG8_SA(b, h) + aoff + m * 2048 + k * 1024); } while (0)
; #define PG8_LDB(dst, b, h) do { _Pragma("unroll") for (int n = 0; n < 2; ++n) _Pragma("unroll") for (int k = 0; k < 2; ++k) dst[n][k] = *(const PG8_LAS bf16x8*)(lds + PG8_SB(b, h) + boff + n * 2048 + k * 1024); } while (0)
; #define PG8_MMA(ai, bj, At, Bt) do { __builtin_amdgcn_s_setprio(1); _Pragma("unroll") for (int m = 0; m < 4; ++m) _Pragma("unroll") for (int n = 0; n < 2; ++n) _Pragma("unroll") for (int k = 0; k < 2; ++k) \
;         acc[ai][bj][m][n] = __builtin_amdgcn_mfma_f32_16x16x32_bf16(Bt[n][k], At[m][k], acc[ai][bj][m][n], 0, 0, 0); __builtin_amdgcn_s_setprio(0); } while (0)
; #define PG8_WAIT_V(n) asm volatile("s_waitcnt vmcnt(" #n ")" ::: "memory")
; #define PG8_WAIT_L(n) asm volatile("s_waitcnt lgkmcnt(" #n ")" ::: "memory")
; #define PG8_BAR __builtin_amdgcn_s_barrier()
; #define PG8_SCHED __builtin_amdgcn_sched_barrier(0)
; template <class Epi, class Sched, bool ALIGN_EPI = false, bool SP2 = false>
; __device__ __forceinline__ void gemm_phase(PG8_LAS unsigned char* lds, const Gemm g, const Sched& S, const Epi& E, const int tid) {
;     ...
;             const bool last = (t == nt - 2);
;             const char* a1 = cA + (size_t)(t + 1) * kstep;
;             const char* a2 = last ? nA : cA + (size_t)(t + 2) * kstep; const char* b2 = last ? nB : cB + (size_t)(t + 2) * kstep;
;             const char* a3 = a2 + kstep; const char* b3 = b2 + kstep;
;             if (last && has_next) S.a_ready(nxt);
;             if constexpr (SP2) {
;             PG8_LDB(B0, 0, 0); PG8_LDB(B1, 0, 1); PG8_SCHED; PG8_LDA(At, 0, 0); PG8_STAGE(PG8_SA(1, 1), a1 + hstep, voffA);
;             PG8_WAIT_V(8); PG8_WAIT_L(0); PG8_BAR; PG8_MMA(0, 0, At, B0); PG8_MMA(0, 1, At, B1); PG8_BAR; PG8_SCHED;
;             PG8_LDA(At, 0, 1); PG8_STAGE(PG8_SB(0, 0), b2, voffB); PG8_STAGE(PG8_SB(0, 1), b2 + hstep, voffB); PG8_STAGE(PG8_SA(0, 0), a2, voffA);
.LBB0_355:
	v_or_b32_e32 v98, 0x10000, v187
	v_add_u32_e32 v102, 0x10400, v187
	v_add_u32_e32 v130, 0x10800, v187
	v_add_u32_e32 v142, 0x10c00, v187
	v_or_b32_e32 v146, 0x14000, v187
	v_add_u32_e32 v160, 0x14400, v187
	v_add_u32_e32 v164, 0x14800, v187
	v_add_u32_e32 v168, 0x14c00, v187
	ds_read_b128 v[98:101], v98
	ds_read_b128 v[102:105], v102
	ds_read_b128 v[130:133], v130
	ds_read_b128 v[142:145], v142
	ds_read_b128 v[146:149], v146
	ds_read_b128 v[160:163], v160
	ds_read_b128 v[164:167], v164
	ds_read_b128 v[168:171], v168
	s_add_u32 s26, s30, 0xfffc0080
	s_addc_u32 s27, s31, -1
	s_cmp_eq_u32 s24, 12
	s_cselect_b32 s87, s4, s27
	s_cselect_b32 s86, s5, s26
	s_cselect_b32 s85, s15, s21
	s_cselect_b32 s84, s17, s20
	v_lshl_add_u64 v[180:181], s[30:31], 0, v[156:157]
	s_add_i32 m0, s6, 0xc000
	ds_read_b128 v[172:175], v186
	ds_read_b128 v[176:179], v186 offset:1024
	ds_read_b128 v[188:191], v186 offset:2048
	ds_read_b128 v[192:195], v186 offset:3072
	ds_read_b128 v[196:199], v186 offset:4096
	ds_read_b128 v[200:203], v186 offset:5120
	ds_read_b128 v[204:207], v186 offset:6144
	ds_read_b128 v[214:217], v186 offset:7168
	global_load_lds_dwordx4 v[180:181], off
	v_lshl_add_u64 v[180:181], s[30:31], 0, v[158:159]
	s_add_i32 m0, s6, 0xe000
	s_nop 0
	global_load_lds_dwordx4 v[180:181], off
	s_waitcnt vmcnt(8)
	s_waitcnt lgkmcnt(0)
	s_barrier
	s_waitcnt lgkmcnt(0)
	v_mfma_f32_16x16x32_bf16 v[138:141], v[98:101], v[172:175], v[138:141]
	v_mfma_f32_16x16x32_bf16 v[138:141], v[102:105], v[176:179], v[138:141]
	v_mfma_f32_16x16x32_bf16 v[134:137], v[130:133], v[172:175], v[134:137]
	v_mfma_f32_16x16x32_bf16 v[134:137], v[142:145], v[176:179], v[134:137]
	v_mfma_f32_16x16x32_bf16 v[126:129], v[98:101], v[188:191], v[126:129]
	v_mfma_f32_16x16x32_bf16 v[126:129], v[102:105], v[192:195], v[126:129]
	v_mfma_f32_16x16x32_bf16 v[122:125], v[130:133], v[188:191], v[122:125]
	v_mfma_f32_16x16x32_bf16 v[122:125], v[142:145], v[192:195], v[122:125]
	v_mfma_f32_16x16x32_bf16 v[118:121], v[98:101], v[196:199], v[118:121]
	v_mfma_f32_16x16x32_bf16 v[118:121], v[102:105], v[200:203], v[118:121]
	v_mfma_f32_16x16x32_bf16 v[114:117], v[130:133], v[196:199], v[114:117]
	v_mfma_f32_16x16x32_bf16 v[114:117], v[142:145], v[200:203], v[114:117]
	v_mfma_f32_16x16x32_bf16 v[110:113], v[98:101], v[204:207], v[110:113]
	v_mfma_f32_16x16x32_bf16 v[110:113], v[102:105], v[214:217], v[110:113]
	v_mfma_f32_16x16x32_bf16 v[106:109], v[130:133], v[204:207], v[106:109]
	v_mfma_f32_16x16x32_bf16 v[106:109], v[142:145], v[214:217], v[106:109]
	v_mfma_f32_16x16x32_bf16 v[62:65], v[146:149], v[172:175], v[62:65]
	v_mfma_f32_16x16x32_bf16 v[62:65], v[160:163], v[176:179], v[62:65]
	v_mfma_f32_16x16x32_bf16 v[58:61], v[164:167], v[172:175], v[58:61]
	v_mfma_f32_16x16x32_bf16 v[58:61], v[168:171], v[176:179], v[58:61]
	v_mfma_f32_16x16x32_bf16 v[54:57], v[146:149], v[188:191], v[54:57]
	v_mfma_f32_16x16x32_bf16 v[54:57], v[160:163], v[192:195], v[54:57]
	v_mfma_f32_16x16x32_bf16 v[50:53], v[164:167], v[188:191], v[50:53]
	v_mfma_f32_16x16x32_bf16 v[50:53], v[168:171], v[192:195], v[50:53]
	v_mfma_f32_16x16x32_bf16 v[46:49], v[146:149], v[196:199], v[46:49]
	v_mfma_f32_16x16x32_bf16 v[46:49], v[160:163], v[200:203], v[46:49]
	v_mfma_f32_16x16x32_bf16 v[42:45], v[164:167], v[196:199], v[42:45]
	v_mfma_f32_16x16x32_bf16 v[42:45], v[168:171], v[200:203], v[42:45]
	v_mfma_f32_16x16x32_bf16 v[38:41], v[146:149], v[204:207], v[38:41]
	v_mfma_f32_16x16x32_bf16 v[38:41], v[160:163], v[214:217], v[38:41]
	v_mfma_f32_16x16x32_bf16 v[34:37], v[164:167], v[204:207], v[34:37]
	v_mfma_f32_16x16x32_bf16 v[34:37], v[168:171], v[214:217], v[34:37]
	s_barrier
	s_mov_b32 m0, s35
	v_lshl_add_u64 v[180:181], s[84:85], 0, v[0:1]
	s_add_u32 s26, s84, 0x40000
	ds_read_b128 v[172:175], v186 offset:16384
	ds_read_b128 v[176:179], v186 offset:17408
	ds_read_b128 v[188:191], v186 offset:18432
	ds_read_b128 v[192:195], v186 offset:19456
	ds_read_b128 v[196:199], v186 offset:20480
	ds_read_b128 v[200:203], v186 offset:21504
	ds_read_b128 v[204:207], v186 offset:22528
	ds_read_b128 v[214:217], v186 offset:23552
	global_load_lds_dwordx4 v[180:181], off
	v_lshl_add_u64 v[182:183], s[84:85], 0, v[150:151]
	s_mov_b32 m0, s88
	s_addc_u32 s27, s85, 0
	global_load_lds_dwordx4 v[182:183], off
	v_lshl_add_u64 v[184:185], s[26:27], 0, v[0:1]
	s_mov_b32 m0, s89
	v_lshl_add_u64 v[218:219], s[86:87], 0, v[152:153]
	global_load_lds_dwordx4 v[184:185], off
	v_lshl_add_u64 v[184:185], s[26:27], 0, v[150:151]
	s_mov_b32 m0, s90
	s_nop 0
	global_load_lds_dwordx4 v[184:185], off
	v_lshl_add_u64 v[184:185], s[86:87], 0, v[154:155]
	s_mov_b32 m0, s6
	s_nop 0
	global_load_lds_dwordx4 v[184:185], off
	s_mov_b32 m0, s91
	s_nop 0
	global_load_lds_dwordx4 v[218:219], off
	s_waitcnt vmcnt(8)
	s_waitcnt lgkmcnt(0)
	s_barrier
; #define PG8_STAGE(bufoff, gbase, voff) do { _Pragma("unroll") for (int _i = 0; _i < 2; ++_i) \
;         __builtin_amdgcn_global_load_lds((const unsigned*)((const char*)(gbase) + (voff)[_i]), (PG8_LAS unsigned*)(lds + (bufoff) + ldsw + _i * 8192), 16, 0, 0); } while (0)
; #define PG8_LDA(dst, b, h) do { _Pragma("unroll") for (int m = 0; m < 4; ++m) _Pragma("unroll") for (int k = 0; k < 2; ++k) dst[m][k] = *(const PG8_LAS bf16x8*)(lds + PG8_SA(b, h) + aoff + m * 2048 + k * 1024); } while (0)
; #define PG8_LDB(dst, b, h) do { _Pragma("unroll") for (int n = 0; n < 2; ++n) _Pragma("unroll") for (int k = 0; k < 2; ++k) dst[n][k] = *(const PG8_LAS bf16x8*)(lds + PG8_SB(b, h) + boff + n * 2048 + k * 1024); } while (0)
; #define PG8_MMA(ai, bj, At, Bt) do { __builtin_amdgcn_s_setprio(1); _Pragma("unroll") for (int m = 0; m < 4; ++m) _Pragma("unroll") for (int n = 0; n < 2; ++n) _Pragma("unroll") for (int k = 0; k < 2; ++k) \
;         acc[ai][bj][m][n] = __builtin_amdgcn_mfma_f32_16x16x32_bf16(Bt[n][k], At[m][k], acc[ai][bj][m][n], 0, 0, 0); __builtin_amdgcn_s_setprio(0); } while (0)
; #define PG8_WAIT_V(n) asm volatile("s_waitcnt vmcnt(" #n ")" ::: "memory")
; #define PG8_WAIT_L(n) asm volatile("s_waitcnt lgkmcnt(" #n ")" ::: "memory")
; #define PG8_BAR __builtin_amdgcn_s_barrier()
; #define PG8_SCHED __builtin_amdgcn_sched_barrier(0)
; template <class Epi, class Sched, bool ALIGN_EPI = false, bool SP2 = false>
; __device__ __forceinline__ void gemm_phase(PG8_LAS unsigned char* lds, const Gemm g, const Sched& S, const Epi& E, const int tid) {
;     ...
;             PG8_WAIT_V(8); PG8_WAIT_L(0); PG8_BAR; PG8_MMA(1, 0, At, B0); PG8_MMA(1, 1, At, B1); PG8_BAR; PG8_SCHED;
;             PG8_LDB(B0, 1, 0); PG8_LDB(B1, 1, 1); PG8_SCHED; PG8_LDA(At, 1, 0); PG8_STAGE(PG8_SA(0, 1), a2 + hstep, voffA);
;             PG8_WAIT_V(8); PG8_WAIT_L(0); PG8_BAR; PG8_MMA(0, 0, At, B0); PG8_MMA(0, 1, At, B1); PG8_BAR; PG8_SCHED;
	s_waitcnt lgkmcnt(0)
	v_mfma_f32_16x16x32_bf16 v[94:97], v[98:101], v[172:175], v[94:97]
	v_mfma_f32_16x16x32_bf16 v[94:97], v[102:105], v[176:179], v[94:97]
	v_mfma_f32_16x16x32_bf16 v[90:93], v[130:133], v[172:175], v[90:93]
	v_mfma_f32_16x16x32_bf16 v[90:93], v[142:145], v[176:179], v[90:93]
	v_mfma_f32_16x16x32_bf16 v[86:89], v[98:101], v[188:191], v[86:89]
	v_mfma_f32_16x16x32_bf16 v[86:89], v[102:105], v[192:195], v[86:89]
	v_mfma_f32_16x16x32_bf16 v[82:85], v[130:133], v[188:191], v[82:85]
	v_mfma_f32_16x16x32_bf16 v[82:85], v[142:145], v[192:195], v[82:85]
	v_mfma_f32_16x16x32_bf16 v[78:81], v[98:101], v[196:199], v[78:81]
	v_mfma_f32_16x16x32_bf16 v[78:81], v[102:105], v[200:203], v[78:81]
	v_mfma_f32_16x16x32_bf16 v[74:77], v[130:133], v[196:199], v[74:77]
	v_mfma_f32_16x16x32_bf16 v[74:77], v[142:145], v[200:203], v[74:77]
	v_mfma_f32_16x16x32_bf16 v[70:73], v[98:101], v[204:207], v[70:73]
	v_mfma_f32_16x16x32_bf16 v[70:73], v[102:105], v[214:217], v[70:73]
	v_mfma_f32_16x16x32_bf16 v[66:69], v[130:133], v[204:207], v[66:69]
	v_mfma_f32_16x16x32_bf16 v[66:69], v[142:145], v[214:217], v[66:69]
	v_mfma_f32_16x16x32_bf16 v[30:33], v[146:149], v[172:175], v[30:33]
	v_mfma_f32_16x16x32_bf16 v[30:33], v[160:163], v[176:179], v[30:33]
	v_mfma_f32_16x16x32_bf16 v[26:29], v[164:167], v[172:175], v[26:29]
	v_mfma_f32_16x16x32_bf16 v[26:29], v[168:171], v[176:179], v[26:29]
	v_mfma_f32_16x16x32_bf16 v[22:25], v[146:149], v[188:191], v[22:25]
	v_mfma_f32_16x16x32_bf16 v[22:25], v[160:163], v[192:195], v[22:25]
	v_mfma_f32_16x16x32_bf16 v[18:21], v[164:167], v[188:191], v[18:21]
	v_mfma_f32_16x16x32_bf16 v[18:21], v[168:171], v[192:195], v[18:21]
	v_mfma_f32_16x16x32_bf16 v[14:17], v[146:149], v[196:199], v[14:17]
	v_mfma_f32_16x16x32_bf16 v[14:17], v[160:163], v[200:203], v[14:17]
	v_mfma_f32_16x16x32_bf16 v[10:13], v[164:167], v[196:199], v[10:13]
	v_mfma_f32_16x16x32_bf16 v[10:13], v[168:171], v[200:203], v[10:13]
	v_mfma_f32_16x16x32_bf16 v[6:9], v[146:149], v[204:207], v[6:9]
	v_mfma_f32_16x16x32_bf16 v[6:9], v[160:163], v[214:217], v[6:9]
	v_mfma_f32_16x16x32_bf16 v[2:5], v[164:167], v[204:207], v[2:5]
	v_mfma_f32_16x16x32_bf16 v[2:5], v[168:171], v[214:217], v[2:5]
	s_barrier
	v_or_b32_e32 v98, 0x18000, v187
	v_add_u32_e32 v102, 0x18400, v187
	v_add_u32_e32 v130, 0x18800, v187
	v_add_u32_e32 v142, 0x18c00, v187
	v_or_b32_e32 v146, 0x1c000, v187
	v_add_u32_e32 v160, 0x1c400, v187
	v_add_u32_e32 v164, 0x1c800, v187
	v_add_u32_e32 v168, 0x1cc00, v187
	ds_read_b128 v[98:101], v98
	ds_read_b128 v[102:105], v102
	ds_read_b128 v[130:133], v130
	ds_read_b128 v[142:145], v142
	ds_read_b128 v[146:149], v146
	ds_read_b128 v[160:163], v160
	ds_read_b128 v[164:167], v164
	ds_read_b128 v[168:171], v168
	s_add_u32 s26, s86, 0x40000
	s_addc_u32 s27, s87, 0
	s_mov_b32 m0, s42
	v_lshl_add_u64 v[220:221], s[26:27], 0, v[154:155]
	ds_read_b128 v[172:175], v186 offset:32768
	ds_read_b128 v[176:179], v186 offset:33792
	ds_read_b128 v[188:191], v186 offset:34816
	ds_read_b128 v[192:195], v186 offset:35840
	ds_read_b128 v[196:199], v186 offset:36864
	ds_read_b128 v[200:203], v186 offset:37888
	ds_read_b128 v[204:207], v186 offset:38912
	ds_read_b128 v[214:217], v186 offset:39936
	global_load_lds_dwordx4 v[220:221], off
	v_lshl_add_u64 v[220:221], s[26:27], 0, v[152:153]
	s_mov_b32 m0, s43
	s_nop 0
	global_load_lds_dwordx4 v[220:221], off
	s_waitcnt vmcnt(8)
	s_waitcnt lgkmcnt(0)
	s_barrier
	s_waitcnt lgkmcnt(0)
	v_mfma_f32_16x16x32_bf16 v[138:141], v[98:101], v[172:175], v[138:141]
	v_mfma_f32_16x16x32_bf16 v[138:141], v[102:105], v[176:179], v[138:141]
	v_mfma_f32_16x16x32_bf16 v[134:137], v[130:133], v[172:175], v[134:137]
	v_mfma_f32_16x16x32_bf16 v[134:137], v[142:145], v[176:179], v[134:137]
	v_mfma_f32_16x16x32_bf16 v[126:129], v[98:101], v[188:191], v[126:129]
	v_mfma_f32_16x16x32_bf16 v[126:129], v[102:105], v[192:195], v[126:129]
	v_mfma_f32_16x16x32_bf16 v[122:125], v[130:133], v[188:191], v[122:125]
	v_mfma_f32_16x16x32_bf16 v[122:125], v[142:145], v[192:195], v[122:125]
	v_mfma_f32_16x16x32_bf16 v[118:121], v[98:101], v[196:199], v[118:121]
	v_mfma_f32_16x16x32_bf16 v[118:121], v[102:105], v[200:203], v[118:121]
	v_mfma_f32_16x16x32_bf16 v[114:117], v[130:133], v[196:199], v[114:117]
	v_mfma_f32_16x16x32_bf16 v[114:117], v[142:145], v[200:203], v[114:117]
	v_mfma_f32_16x16x32_bf16 v[110:113], v[98:101], v[204:207], v[110:113]
	v_mfma_f32_16x16x32_bf16 v[110:113], v[102:105], v[214:217], v[110:113]
	v_mfma_f32_16x16x32_bf16 v[106:109], v[130:133], v[204:207], v[106:109]
	v_mfma_f32_16x16x32_bf16 v[106:109], v[142:145], v[214:217], v[106:109]
	v_mfma_f32_16x16x32_bf16 v[62:65], v[146:149], v[172:175], v[62:65]
	v_mfma_f32_16x16x32_bf16 v[62:65], v[160:163], v[176:179], v[62:65]
	v_mfma_f32_16x16x32_bf16 v[58:61], v[164:167], v[172:175], v[58:61]
	v_mfma_f32_16x16x32_bf16 v[58:61], v[168:171], v[176:179], v[58:61]
	v_mfma_f32_16x16x32_bf16 v[54:57], v[146:149], v[188:191], v[54:57]
	v_mfma_f32_16x16x32_bf16 v[54:57], v[160:163], v[192:195], v[54:57]
	v_mfma_f32_16x16x32_bf16 v[50:53], v[164:167], v[188:191], v[50:53]
	v_mfma_f32_16x16x32_bf16 v[50:53], v[168:171], v[192:195], v[50:53]
	v_mfma_f32_16x16x32_bf16 v[46:49], v[146:149], v[196:199], v[46:49]
	v_mfma_f32_16x16x32_bf16 v[46:49], v[160:163], v[200:203], v[46:49]
	v_mfma_f32_16x16x32_bf16 v[42:45], v[164:167], v[196:199], v[42:45]
	v_mfma_f32_16x16x32_bf16 v[42:45], v[168:171], v[200:203], v[42:45]
	v_mfma_f32_16x16x32_bf16 v[38:41], v[146:149], v[204:207], v[38:41]
	v_mfma_f32_16x16x32_bf16 v[38:41], v[160:163], v[214:217], v[38:41]
	v_mfma_f32_16x16x32_bf16 v[34:37], v[164:167], v[204:207], v[34:37]
	v_mfma_f32_16x16x32_bf16 v[34:37], v[168:171], v[214:217], v[34:37]
	s_barrier
; #define PG8_STAGE(bufoff, gbase, voff) do { _Pragma("unroll") for (int _i = 0; _i < 2; ++_i) \
;         __builtin_amdgcn_global_load_lds((const unsigned*)((const char*)(gbase) + (voff)[_i]), (PG8_LAS unsigned*)(lds + (bufoff) + ldsw + _i * 8192), 16, 0, 0); } while (0)
; #define PG8_LDA(dst, b, h) do { _Pragma("unroll") for (int m = 0; m < 4; ++m) _Pragma("unroll") for (int k = 0; k < 2; ++k) dst[m][k] = *(const PG8_LAS bf16x8*)(lds + PG8_SA(b, h) + aoff + m * 2048 + k * 1024); } while (0)
; #define PG8_MMA(ai, bj, At, Bt) do { __builtin_amdgcn_s_setprio(1); _Pragma("unroll") for (int m = 0; m < 4; ++m) _Pragma("unroll") for (int n = 0; n < 2; ++n) _Pragma("unroll") for (int k = 0; k < 2; ++k) \
;         acc[ai][bj][m][n] = __builtin_amdgcn_mfma_f32_16x16x32_bf16(Bt[n][k], At[m][k], acc[ai][bj][m][n], 0, 0, 0); __builtin_amdgcn_s_setprio(0); } while (0)
; #define PG8_WAIT_V(n) asm volatile("s_waitcnt vmcnt(" #n ")" ::: "memory")
; #define PG8_WAIT_L(n) asm volatile("s_waitcnt lgkmcnt(" #n ")" ::: "memory")
; #define PG8_BAR __builtin_amdgcn_s_barrier()
; #define PG8_SCHED __builtin_amdgcn_sched_barrier(0)
; template <class Epi, class Sched, bool ALIGN_EPI = false, bool SP2 = false>
; __device__ __forceinline__ void gemm_phase(PG8_LAS unsigned char* lds, const Gemm g, const Sched& S, const Epi& E, const int tid) {
;     ...
;             PG8_LDA(At, 1, 1); PG8_STAGE(PG8_SB(1, 0), b3, voffB); PG8_STAGE(PG8_SB(1, 1), b3 + hstep, voffB); PG8_STAGE(PG8_SA(1, 0), a3, voffA);
;             PG8_WAIT_V(8); PG8_WAIT_L(0); PG8_BAR; PG8_MMA(1, 0, At, B0); PG8_MMA(1, 1, At, B1); PG8_BAR; PG8_SCHED;
;     ...
;         if constexpr (ALIGN_EPI) { if (wr == 0) PG8_BAR; }
	s_mov_b32 m0, s40
	v_lshl_add_u64 v[180:181], v[180:181], 0, s[12:13]
	s_add_u32 s26, s84, 0x40080
	ds_read_b128 v[172:175], v186 offset:49152
	ds_read_b128 v[176:179], v186 offset:50176
	ds_read_b128 v[188:191], v186 offset:51200
	ds_read_b128 v[192:195], v186 offset:52224
	ds_read_b128 v[196:199], v186 offset:53248
	ds_read_b128 v[200:203], v186 offset:54272
	ds_read_b128 v[204:207], v186 offset:55296
	ds_read_b128 v[214:217], v186 offset:56320
	global_load_lds_dwordx4 v[180:181], off
	v_lshl_add_u64 v[180:181], v[182:183], 0, s[12:13]
	s_mov_b32 m0, s41
	s_addc_u32 s27, s85, 0
	global_load_lds_dwordx4 v[180:181], off
	v_lshl_add_u64 v[180:181], s[26:27], 0, v[0:1]
	s_mov_b32 m0, s34
	s_nop 0
	global_load_lds_dwordx4 v[180:181], off
	v_lshl_add_u64 v[180:181], s[26:27], 0, v[150:151]
	s_mov_b32 m0, s8
	s_nop 0
	global_load_lds_dwordx4 v[180:181], off
	v_lshl_add_u64 v[180:181], v[184:185], 0, s[12:13]
	s_mov_b32 m0, s1
	s_nop 0
	global_load_lds_dwordx4 v[180:181], off
	v_lshl_add_u64 v[180:181], v[218:219], 0, s[12:13]
	s_mov_b32 m0, s14
	s_nop 0
	global_load_lds_dwordx4 v[180:181], off
	s_waitcnt vmcnt(8)
	s_waitcnt lgkmcnt(0)
	s_barrier
	s_waitcnt lgkmcnt(0)
	v_mfma_f32_16x16x32_bf16 v[94:97], v[98:101], v[172:175], v[94:97]
	v_mfma_f32_16x16x32_bf16 v[94:97], v[102:105], v[176:179], v[94:97]
	v_mfma_f32_16x16x32_bf16 v[90:93], v[130:133], v[172:175], v[90:93]
	v_mfma_f32_16x16x32_bf16 v[90:93], v[142:145], v[176:179], v[90:93]
	v_mfma_f32_16x16x32_bf16 v[86:89], v[98:101], v[188:191], v[86:89]
	v_mfma_f32_16x16x32_bf16 v[86:89], v[102:105], v[192:195], v[86:89]
	v_mfma_f32_16x16x32_bf16 v[82:85], v[130:133], v[188:191], v[82:85]
	v_mfma_f32_16x16x32_bf16 v[82:85], v[142:145], v[192:195], v[82:85]
	v_mfma_f32_16x16x32_bf16 v[78:81], v[98:101], v[196:199], v[78:81]
	v_mfma_f32_16x16x32_bf16 v[78:81], v[102:105], v[200:203], v[78:81]
	v_mfma_f32_16x16x32_bf16 v[74:77], v[130:133], v[196:199], v[74:77]
	v_mfma_f32_16x16x32_bf16 v[74:77], v[142:145], v[200:203], v[74:77]
	v_mfma_f32_16x16x32_bf16 v[70:73], v[98:101], v[204:207], v[70:73]
	v_mfma_f32_16x16x32_bf16 v[70:73], v[102:105], v[214:217], v[70:73]
	v_mfma_f32_16x16x32_bf16 v[66:69], v[130:133], v[204:207], v[66:69]
	v_mfma_f32_16x16x32_bf16 v[66:69], v[142:145], v[214:217], v[66:69]
	v_mfma_f32_16x16x32_bf16 v[30:33], v[146:149], v[172:175], v[30:33]
	v_mfma_f32_16x16x32_bf16 v[30:33], v[160:163], v[176:179], v[30:33]
	v_mfma_f32_16x16x32_bf16 v[26:29], v[164:167], v[172:175], v[26:29]
	v_mfma_f32_16x16x32_bf16 v[26:29], v[168:171], v[176:179], v[26:29]
	v_mfma_f32_16x16x32_bf16 v[22:25], v[146:149], v[188:191], v[22:25]
	v_mfma_f32_16x16x32_bf16 v[22:25], v[160:163], v[192:195], v[22:25]
	v_mfma_f32_16x16x32_bf16 v[18:21], v[164:167], v[188:191], v[18:21]
	v_mfma_f32_16x16x32_bf16 v[18:21], v[168:171], v[192:195], v[18:21]
	v_mfma_f32_16x16x32_bf16 v[14:17], v[146:149], v[196:199], v[14:17]
	v_mfma_f32_16x16x32_bf16 v[14:17], v[160:163], v[200:203], v[14:17]
	v_mfma_f32_16x16x32_bf16 v[10:13], v[164:167], v[196:199], v[10:13]
	v_mfma_f32_16x16x32_bf16 v[10:13], v[168:171], v[200:203], v[10:13]
	v_mfma_f32_16x16x32_bf16 v[6:9], v[146:149], v[204:207], v[6:9]
	v_mfma_f32_16x16x32_bf16 v[6:9], v[160:163], v[214:217], v[6:9]
	v_mfma_f32_16x16x32_bf16 v[2:5], v[164:167], v[204:207], v[2:5]
	v_mfma_f32_16x16x32_bf16 v[2:5], v[168:171], v[214:217], v[2:5]
	s_barrier
	s_add_i32 s24, s24, 2
	s_add_u32 s30, s30, 0x100
	s_addc_u32 s31, s31, 0
	s_add_u32 s20, s20, 0x100
	s_addc_u32 s21, s21, 0
	s_cmp_gt_u32 s24, 13
	s_cbranch_scc0 .LBB0_355
	v_readlane_b32 s4, v255, 54
	v_readlane_b32 s5, v255, 55
	s_and_b64 vcc, exec, s[4:5]
	s_cbranch_vccz .LBB0_358
	s_barrier

; #define PG8_STAGE(bufoff, gbase, voff) do { _Pragma("unroll") for (int _i = 0; _i < 2; ++_i) \
;         __builtin_amdgcn_global_load_lds((const unsigned*)((const char*)(gbase) + (voff)[_i]), (PG8_LAS unsigned*)(lds + (bufoff) + ldsw + _i * 8192), 16, 0, 0); } while (0)
; #define PG8_LDA(dst, b, h) do { _Pragma("unroll") for (int m = 0; m < 4; ++m) _Pragma("unroll") for (int k = 0; k < 2; ++k) dst[m][k] = *(const PG8_LAS bf16x8*)(lds + PG8_SA(b, h) + aoff + m * 2048 + k * 1024); } while (0)
; #define PG8_LDB(dst, b, h) do { _Pragma("unroll") for (int n = 0; n < 2; ++n) _Pragma("unroll") for (int k = 0; k < 2; ++k) dst[n][k] = *(const PG8_LAS bf16x8*)(lds + PG8_SB(b, h) + boff + n * 2048 + k * 1024); } while (0)
; #define PG8_MMA(ai, bj, At, Bt) do { __builtin_amdgcn_s_setprio(1); _Pragma("unroll") for (int m = 0; m < 4; ++m) _Pragma("unroll") for (int n = 0; n < 2; ++n) _Pragma("unroll") for (int k = 0; k < 2; ++k) \
;         acc[ai][bj][m][n] = __builtin_amdgcn_mfma_f32_16x16x32_bf16(Bt[n][k], At[m][k], acc[ai][bj][m][n], 0, 0, 0); __builtin_amdgcn_s_setprio(0); } while (0)
; #define PG8_WAIT_V(n) asm volatile("s_waitcnt vmcnt(" #n ")" ::: "memory")
; #define PG8_WAIT_L(n) asm volatile("s_waitcnt lgkmcnt(" #n ")" ::: "memory")
; template <class Epi, class Sched, bool ALIGN_EPI = false, bool SP2 = false>
; __device__ __forceinline__ void gemm_phase(PG8_LAS unsigned char* lds, const Gemm g, const Sched& S, const Epi& E, const int tid) {
;     ...
;         const bool has_next = S.next(ui + 1, nxt);
;         const char* nA = has_next ? (const char*)g.A + (size_t)nxt.pm * tstep : cA; const char* nB = has_next ? (const char*)g.Bt + (size_t)nxt.pn * tstep : cB;
;         for (int t = 0; t < nt; t += 2) {
;             const bool last = (t == nt - 2);
;             const char* a1 = cA + (size_t)(t + 1) * kstep;
;             const char* a2 = last ? nA : cA + (size_t)(t + 2) * kstep; const char* b2 = last ? nB : cB + (size_t)(t + 2) * kstep;
;             const char* a3 = a2 + kstep; const char* b3 = b2 + kstep;
;             if (last && has_next) S.a_ready(nxt);
;             if constexpr (SP2) {
;             PG8_LDB(B0, 0, 0); PG8_LDB(B1, 0, 1); PG8_SCHED; PG8_LDA(At, 0, 0); PG8_STAGE(PG8_SA(1, 1), a1 + hstep, voffA);
;             PG8_WAIT_V(8); PG8_WAIT_L(0); PG8_BAR; PG8_MMA(0, 0, At, B0); PG8_MMA(0, 1, At, B1); PG8_BAR; PG8_SCHED;
.LBB0_370:
	s_ashr_i32 s43, s42, 31
	s_lshl_b64 s[44:45], s[42:43], 17
	v_readlane_b32 s41, v253, 63
	s_add_u32 s44, s41, s44
	v_readlane_b32 s41, v254, 0
	s_addc_u32 s45, s41, s45
	s_and_b64 s[46:47], s[36:37], exec
	v_or_b32_e32 v208, 0x10000, v139
	v_add_u32_e32 v210, 0x10800, v139
	v_or_b32_e32 v212, 0x14000, v139
	v_add_u32_e32 v218, 0x14800, v139
	s_cselect_b32 s87, s45, s89
	s_cselect_b32 s86, s44, s88
	s_ashr_i32 s41, s40, 31
	v_add_u32_e32 v209, 0x10400, v139
	ds_read_b128 v[2:5], v208
	ds_read_b128 v[6:9], v209
	v_add_u32_e32 v211, 0x10c00, v139
	ds_read_b128 v[10:13], v210
	ds_read_b128 v[14:17], v211
	v_add_u32_e32 v213, 0x14400, v139
	ds_read_b128 v[18:21], v212
	ds_read_b128 v[22:25], v213
	v_add_u32_e32 v219, 0x14c00, v139
	ds_read_b128 v[26:29], v218
	ds_read_b128 v[30:33], v219
	s_lshl_b64 s[46:47], s[40:41], 17
	v_readlane_b32 s50, v253, 59
	v_readlane_b32 s51, v253, 60
	s_add_u32 s46, s50, s46
	s_addc_u32 s47, s51, s47
	s_and_b64 s[50:51], s[36:37], exec
	s_cselect_b32 s85, s47, s91
	s_cselect_b32 s84, s46, s90
	s_add_u32 s50, s88, 0x10080
	s_addc_u32 s51, s89, 0
	s_add_i32 s43, s0, 0xc000
	v_lshl_add_u64 v[66:67], s[50:51], 0, v[134:135]
	s_mov_b32 m0, s43
	s_add_i32 s41, s0, 0xe000
	ds_read_b128 v[34:37], v138
	ds_read_b128 v[38:41], v138 offset:1024
	ds_read_b128 v[42:45], v138 offset:2048
	ds_read_b128 v[46:49], v138 offset:3072
	ds_read_b128 v[50:53], v138 offset:4096
	ds_read_b128 v[54:57], v138 offset:5120
	ds_read_b128 v[58:61], v138 offset:6144
	ds_read_b128 v[62:65], v138 offset:7168
	global_load_lds_dwordx4 v[66:67], off
	v_lshl_add_u64 v[66:67], s[50:51], 0, v[132:133]
	s_mov_b32 m0, s41
	s_nop 0
	global_load_lds_dwordx4 v[66:67], off
	s_waitcnt vmcnt(8)
	s_waitcnt lgkmcnt(0)
	s_barrier
	s_waitcnt lgkmcnt(0)
	v_mfma_f32_16x16x32_bf16 v[66:69], v[2:5], v[34:37], 0
	v_mfma_f32_16x16x32_bf16 v[70:73], v[10:13], v[34:37], 0
	v_mfma_f32_16x16x32_bf16 v[74:77], v[2:5], v[42:45], 0
	v_mfma_f32_16x16x32_bf16 v[78:81], v[10:13], v[42:45], 0
	v_mfma_f32_16x16x32_bf16 v[82:85], v[2:5], v[50:53], 0
	v_mfma_f32_16x16x32_bf16 v[86:89], v[10:13], v[50:53], 0
	v_mfma_f32_16x16x32_bf16 v[90:93], v[2:5], v[58:61], 0
	v_mfma_f32_16x16x32_bf16 v[94:97], v[10:13], v[58:61], 0
	v_mfma_f32_16x16x32_bf16 v[66:69], v[6:9], v[38:41], v[66:69]
	v_mfma_f32_16x16x32_bf16 v[70:73], v[14:17], v[38:41], v[70:73]
	v_mfma_f32_16x16x32_bf16 v[74:77], v[6:9], v[46:49], v[74:77]
	v_mfma_f32_16x16x32_bf16 v[78:81], v[14:17], v[46:49], v[78:81]
	v_mfma_f32_16x16x32_bf16 v[82:85], v[6:9], v[54:57], v[82:85]
	v_mfma_f32_16x16x32_bf16 v[86:89], v[14:17], v[54:57], v[86:89]
	v_mfma_f32_16x16x32_bf16 v[90:93], v[6:9], v[62:65], v[90:93]
	v_mfma_f32_16x16x32_bf16 v[94:97], v[14:17], v[62:65], v[94:97]
	v_mfma_f32_16x16x32_bf16 v[98:101], v[18:21], v[34:37], 0
	v_mfma_f32_16x16x32_bf16 v[34:37], v[26:29], v[34:37], 0
	v_mfma_f32_16x16x32_bf16 v[98:101], v[22:25], v[38:41], v[98:101]
	v_mfma_f32_16x16x32_bf16 v[34:37], v[30:33], v[38:41], v[34:37]
	v_mfma_f32_16x16x32_bf16 v[38:41], v[18:21], v[42:45], 0
	v_mfma_f32_16x16x32_bf16 v[42:45], v[26:29], v[42:45], 0
	v_mfma_f32_16x16x32_bf16 v[38:41], v[22:25], v[46:49], v[38:41]
	v_mfma_f32_16x16x32_bf16 v[42:45], v[30:33], v[46:49], v[42:45]
	v_mfma_f32_16x16x32_bf16 v[46:49], v[18:21], v[50:53], 0
	v_mfma_f32_16x16x32_bf16 v[50:53], v[26:29], v[50:53], 0
	v_mfma_f32_16x16x32_bf16 v[46:49], v[22:25], v[54:57], v[46:49]
	v_mfma_f32_16x16x32_bf16 v[50:53], v[30:33], v[54:57], v[50:53]
	v_mfma_f32_16x16x32_bf16 v[54:57], v[18:21], v[58:61], 0
	v_mfma_f32_16x16x32_bf16 v[58:61], v[26:29], v[58:61], 0
	v_mfma_f32_16x16x32_bf16 v[54:57], v[22:25], v[62:65], v[54:57]
	v_mfma_f32_16x16x32_bf16 v[58:61], v[30:33], v[62:65], v[58:61]
	s_barrier
	v_lshl_add_u64 v[136:137], s[90:91], 0, v[0:1]
	s_mov_b64 s[92:93], 0x100
	s_mov_b32 m0, s1
	v_lshl_add_u64 v[140:141], v[136:137], 0, s[92:93]
	v_lshl_add_u64 v[180:181], s[90:91], 0, v[130:131]
	s_add_u32 s50, s90, 0x10100
	ds_read_b128 v[62:65], v138 offset:16384
	ds_read_b128 v[102:105], v138 offset:17408
	ds_read_b128 v[106:109], v138 offset:18432
	ds_read_b128 v[110:113], v138 offset:19456
	ds_read_b128 v[114:117], v138 offset:20480
	ds_read_b128 v[118:121], v138 offset:21504
	ds_read_b128 v[122:125], v138 offset:22528
	ds_read_b128 v[126:129], v138 offset:23552
	global_load_lds_dwordx4 v[140:141], off
	v_lshl_add_u64 v[140:141], v[180:181], 0, s[92:93]
	s_mov_b32 m0, s2
	s_addc_u32 s51, s91, 0
	global_load_lds_dwordx4 v[140:141], off
	v_lshl_add_u64 v[140:141], s[50:51], 0, v[0:1]
	s_mov_b32 m0, s4
	v_lshl_add_u64 v[182:183], s[88:89], 0, v[134:135]
	global_load_lds_dwordx4 v[140:141], off
	v_lshl_add_u64 v[140:141], s[50:51], 0, v[130:131]
	s_mov_b32 m0, s5
	v_lshl_add_u64 v[214:215], s[88:89], 0, v[132:133]
	global_load_lds_dwordx4 v[140:141], off
	v_lshl_add_u64 v[140:141], v[182:183], 0, s[92:93]
	s_mov_b32 m0, s0
	s_nop 0
	global_load_lds_dwordx4 v[140:141], off
	v_lshl_add_u64 v[140:141], v[214:215], 0, s[92:93]
	s_mov_b32 m0, s6
	s_nop 0
	global_load_lds_dwordx4 v[140:141], off
	s_waitcnt vmcnt(8)
	s_waitcnt lgkmcnt(0)
	s_barrier
; #define PG8_STAGE(bufoff, gbase, voff) do { _Pragma("unroll") for (int _i = 0; _i < 2; ++_i) \
;         __builtin_amdgcn_global_load_lds((const unsigned*)((const char*)(gbase) + (voff)[_i]), (PG8_LAS unsigned*)(lds + (bufoff) + ldsw + _i * 8192), 16, 0, 0); } while (0)
; #define PG8_LDA(dst, b, h) do { _Pragma("unroll") for (int m = 0; m < 4; ++m) _Pragma("unroll") for (int k = 0; k < 2; ++k) dst[m][k] = *(const PG8_LAS bf16x8*)(lds + PG8_SA(b, h) + aoff + m * 2048 + k * 1024); } while (0)
; #define PG8_LDB(dst, b, h) do { _Pragma("unroll") for (int n = 0; n < 2; ++n) _Pragma("unroll") for (int k = 0; k < 2; ++k) dst[n][k] = *(const PG8_LAS bf16x8*)(lds + PG8_SB(b, h) + boff + n * 2048 + k * 1024); } while (0)
; #define PG8_MMA(ai, bj, At, Bt) do { __builtin_amdgcn_s_setprio(1); _Pragma("unroll") for (int m = 0; m < 4; ++m) _Pragma("unroll") for (int n = 0; n < 2; ++n) _Pragma("unroll") for (int k = 0; k < 2; ++k) \
;         acc[ai][bj][m][n] = __builtin_amdgcn_mfma_f32_16x16x32_bf16(Bt[n][k], At[m][k], acc[ai][bj][m][n], 0, 0, 0); __builtin_amdgcn_s_setprio(0); } while (0)
; #define PG8_WAIT_V(n) asm volatile("s_waitcnt vmcnt(" #n ")" ::: "memory")
; #define PG8_WAIT_L(n) asm volatile("s_waitcnt lgkmcnt(" #n ")" ::: "memory")
; #define PG8_BAR __builtin_amdgcn_s_barrier()
; #define PG8_SCHED __builtin_amdgcn_sched_barrier(0)
; template <class Epi, class Sched, bool ALIGN_EPI = false, bool SP2 = false>
; __device__ __forceinline__ void gemm_phase(PG8_LAS unsigned char* lds, const Gemm g, const Sched& S, const Epi& E, const int tid) {
;     ...
;             PG8_WAIT_V(8); PG8_WAIT_L(0); PG8_BAR; PG8_MMA(0, 0, At, B0); PG8_MMA(0, 1, At, B1); PG8_BAR; PG8_SCHED;
;             PG8_LDA(At, 0, 1); PG8_STAGE(PG8_SB(0, 0), b2, voffB); PG8_STAGE(PG8_SB(0, 1), b2 + hstep, voffB); PG8_STAGE(PG8_SA(0, 0), a2, voffA);
;             PG8_WAIT_V(8); PG8_WAIT_L(0); PG8_BAR; PG8_MMA(1, 0, At, B0); PG8_MMA(1, 1, At, B1); PG8_BAR; PG8_SCHED;
;             PG8_LDB(B0, 1, 0); PG8_LDB(B1, 1, 1); PG8_SCHED; PG8_LDA(At, 1, 0); PG8_STAGE(PG8_SA(0, 1), a2 + hstep, voffA);
;             PG8_WAIT_V(8); PG8_WAIT_L(0); PG8_BAR; PG8_MMA(0, 0, At, B0); PG8_MMA(0, 1, At, B1); PG8_BAR; PG8_SCHED;
	s_waitcnt lgkmcnt(0)
	v_mfma_f32_16x16x32_bf16 v[140:143], v[2:5], v[62:65], 0
	v_mfma_f32_16x16x32_bf16 v[148:151], v[2:5], v[106:109], 0
	v_mfma_f32_16x16x32_bf16 v[156:159], v[2:5], v[114:117], 0
	v_mfma_f32_16x16x32_bf16 v[2:5], v[2:5], v[122:125], 0
	v_mfma_f32_16x16x32_bf16 v[140:143], v[6:9], v[102:105], v[140:143]
	v_mfma_f32_16x16x32_bf16 v[148:151], v[6:9], v[110:113], v[148:151]
	v_mfma_f32_16x16x32_bf16 v[156:159], v[6:9], v[118:121], v[156:159]
	v_mfma_f32_16x16x32_bf16 v[2:5], v[6:9], v[126:129], v[2:5]
	v_mfma_f32_16x16x32_bf16 v[6:9], v[10:13], v[122:125], 0
	v_mfma_f32_16x16x32_bf16 v[144:147], v[10:13], v[62:65], 0
	v_mfma_f32_16x16x32_bf16 v[152:155], v[10:13], v[106:109], 0
	v_mfma_f32_16x16x32_bf16 v[160:163], v[10:13], v[114:117], 0
	v_mfma_f32_16x16x32_bf16 v[6:9], v[14:17], v[126:129], v[6:9]
	v_mfma_f32_16x16x32_bf16 v[144:147], v[14:17], v[102:105], v[144:147]
	v_mfma_f32_16x16x32_bf16 v[152:155], v[14:17], v[110:113], v[152:155]
	v_mfma_f32_16x16x32_bf16 v[160:163], v[14:17], v[118:121], v[160:163]
	v_mfma_f32_16x16x32_bf16 v[10:13], v[18:21], v[62:65], 0
	v_mfma_f32_16x16x32_bf16 v[14:17], v[26:29], v[62:65], 0
	v_mfma_f32_16x16x32_bf16 v[10:13], v[22:25], v[102:105], v[10:13]
	v_mfma_f32_16x16x32_bf16 v[14:17], v[30:33], v[102:105], v[14:17]
	v_mfma_f32_16x16x32_bf16 v[62:65], v[18:21], v[106:109], 0
	v_mfma_f32_16x16x32_bf16 v[102:105], v[26:29], v[106:109], 0
	v_mfma_f32_16x16x32_bf16 v[106:109], v[18:21], v[114:117], 0
	v_mfma_f32_16x16x32_bf16 v[18:21], v[18:21], v[122:125], 0
	v_mfma_f32_16x16x32_bf16 v[62:65], v[22:25], v[110:113], v[62:65]
	v_mfma_f32_16x16x32_bf16 v[102:105], v[30:33], v[110:113], v[102:105]
	v_mfma_f32_16x16x32_bf16 v[106:109], v[22:25], v[118:121], v[106:109]
	v_mfma_f32_16x16x32_bf16 v[110:113], v[26:29], v[114:117], 0
	v_mfma_f32_16x16x32_bf16 v[18:21], v[22:25], v[126:129], v[18:21]
	v_mfma_f32_16x16x32_bf16 v[22:25], v[26:29], v[122:125], 0
	v_mfma_f32_16x16x32_bf16 v[110:113], v[30:33], v[118:121], v[110:113]
	v_mfma_f32_16x16x32_bf16 v[22:25], v[30:33], v[126:129], v[22:25]
	s_barrier
	v_or_b32_e32 v222, 0x18000, v139
	v_add_u32_e32 v224, 0x18800, v139
	v_or_b32_e32 v226, 0x1c000, v139
	v_add_u32_e32 v228, 0x1c800, v139
	v_add_u32_e32 v223, 0x18400, v139
	ds_read_b128 v[26:29], v222
	ds_read_b128 v[30:33], v223
	v_add_u32_e32 v225, 0x18c00, v139
	ds_read_b128 v[114:117], v224
	ds_read_b128 v[118:121], v225
	v_add_u32_e32 v227, 0x1c400, v139
	ds_read_b128 v[122:125], v226
	ds_read_b128 v[126:129], v227
	v_add_u32_e32 v230, 0x1cc00, v139
	ds_read_b128 v[164:167], v228
	ds_read_b128 v[168:171], v230
	s_add_u32 s50, s88, 0x10100
	s_addc_u32 s51, s89, 0
	s_mov_b32 m0, s8
	v_lshl_add_u64 v[216:217], s[50:51], 0, v[134:135]
	ds_read_b128 v[172:175], v138 offset:32768
	ds_read_b128 v[176:179], v138 offset:33792
	ds_read_b128 v[184:187], v138 offset:34816
	ds_read_b128 v[188:191], v138 offset:35840
	ds_read_b128 v[192:195], v138 offset:36864
	ds_read_b128 v[196:199], v138 offset:37888
	ds_read_b128 v[200:203], v138 offset:38912
	ds_read_b128 v[204:207], v138 offset:39936
	global_load_lds_dwordx4 v[216:217], off
	v_lshl_add_u64 v[216:217], s[50:51], 0, v[132:133]
	s_mov_b32 m0, s9
	s_nop 0
	global_load_lds_dwordx4 v[216:217], off
	s_waitcnt vmcnt(8)
	s_waitcnt lgkmcnt(0)
	s_barrier
	s_waitcnt lgkmcnt(0)
	v_mfma_f32_16x16x32_bf16 v[66:69], v[26:29], v[172:175], v[66:69]
	v_mfma_f32_16x16x32_bf16 v[66:69], v[30:33], v[176:179], v[66:69]
	v_mfma_f32_16x16x32_bf16 v[70:73], v[114:117], v[172:175], v[70:73]
	v_mfma_f32_16x16x32_bf16 v[70:73], v[118:121], v[176:179], v[70:73]
	v_mfma_f32_16x16x32_bf16 v[74:77], v[26:29], v[184:187], v[74:77]
	v_mfma_f32_16x16x32_bf16 v[74:77], v[30:33], v[188:191], v[74:77]
	v_mfma_f32_16x16x32_bf16 v[78:81], v[114:117], v[184:187], v[78:81]
	v_mfma_f32_16x16x32_bf16 v[78:81], v[118:121], v[188:191], v[78:81]
	v_mfma_f32_16x16x32_bf16 v[82:85], v[26:29], v[192:195], v[82:85]
	v_mfma_f32_16x16x32_bf16 v[82:85], v[30:33], v[196:199], v[82:85]
	v_mfma_f32_16x16x32_bf16 v[86:89], v[114:117], v[192:195], v[86:89]
	v_mfma_f32_16x16x32_bf16 v[86:89], v[118:121], v[196:199], v[86:89]
	v_mfma_f32_16x16x32_bf16 v[90:93], v[26:29], v[200:203], v[90:93]
	v_mfma_f32_16x16x32_bf16 v[90:93], v[30:33], v[204:207], v[90:93]
	v_mfma_f32_16x16x32_bf16 v[94:97], v[114:117], v[200:203], v[94:97]
	v_mfma_f32_16x16x32_bf16 v[94:97], v[118:121], v[204:207], v[94:97]
	v_mfma_f32_16x16x32_bf16 v[98:101], v[122:125], v[172:175], v[98:101]
	v_mfma_f32_16x16x32_bf16 v[98:101], v[126:129], v[176:179], v[98:101]
	v_mfma_f32_16x16x32_bf16 v[34:37], v[164:167], v[172:175], v[34:37]
	v_mfma_f32_16x16x32_bf16 v[34:37], v[168:171], v[176:179], v[34:37]
	v_mfma_f32_16x16x32_bf16 v[38:41], v[122:125], v[184:187], v[38:41]
	v_mfma_f32_16x16x32_bf16 v[38:41], v[126:129], v[188:191], v[38:41]
	v_mfma_f32_16x16x32_bf16 v[42:45], v[164:167], v[184:187], v[42:45]
	v_mfma_f32_16x16x32_bf16 v[42:45], v[168:171], v[188:191], v[42:45]
	v_mfma_f32_16x16x32_bf16 v[46:49], v[122:125], v[192:195], v[46:49]
	v_mfma_f32_16x16x32_bf16 v[46:49], v[126:129], v[196:199], v[46:49]
	v_mfma_f32_16x16x32_bf16 v[50:53], v[164:167], v[192:195], v[50:53]
	v_mfma_f32_16x16x32_bf16 v[50:53], v[168:171], v[196:199], v[50:53]
	v_mfma_f32_16x16x32_bf16 v[54:57], v[122:125], v[200:203], v[54:57]
	v_mfma_f32_16x16x32_bf16 v[54:57], v[126:129], v[204:207], v[54:57]
	v_mfma_f32_16x16x32_bf16 v[58:61], v[164:167], v[200:203], v[58:61]
	v_mfma_f32_16x16x32_bf16 v[58:61], v[168:171], v[204:207], v[58:61]
	s_barrier
; #define PG8_STAGE(bufoff, gbase, voff) do { _Pragma("unroll") for (int _i = 0; _i < 2; ++_i) \
;         __builtin_amdgcn_global_load_lds((const unsigned*)((const char*)(gbase) + (voff)[_i]), (PG8_LAS unsigned*)(lds + (bufoff) + ldsw + _i * 8192), 16, 0, 0); } while (0)
; #define PG8_LDA(dst, b, h) do { _Pragma("unroll") for (int m = 0; m < 4; ++m) _Pragma("unroll") for (int k = 0; k < 2; ++k) dst[m][k] = *(const PG8_LAS bf16x8*)(lds + PG8_SA(b, h) + aoff + m * 2048 + k * 1024); } while (0)
; #define PG8_LDB(dst, b, h) do { _Pragma("unroll") for (int n = 0; n < 2; ++n) _Pragma("unroll") for (int k = 0; k < 2; ++k) dst[n][k] = *(const PG8_LAS bf16x8*)(lds + PG8_SB(b, h) + boff + n * 2048 + k * 1024); } while (0)
; #define PG8_MMA(ai, bj, At, Bt) do { __builtin_amdgcn_s_setprio(1); _Pragma("unroll") for (int m = 0; m < 4; ++m) _Pragma("unroll") for (int n = 0; n < 2; ++n) _Pragma("unroll") for (int k = 0; k < 2; ++k) \
;         acc[ai][bj][m][n] = __builtin_amdgcn_mfma_f32_16x16x32_bf16(Bt[n][k], At[m][k], acc[ai][bj][m][n], 0, 0, 0); __builtin_amdgcn_s_setprio(0); } while (0)
; #define PG8_BAR __builtin_amdgcn_s_barrier()
; template <class Epi, class Sched, bool ALIGN_EPI = false, bool SP2 = false>
; __device__ __forceinline__ void gemm_phase(PG8_LAS unsigned char* lds, const Gemm g, const Sched& S, const Epi& E, const int tid) {
;     ...
;             PG8_LDB(B0, 0, 0); PG8_LDB(B1, 0, 1); PG8_SCHED; PG8_LDA(At, 0, 0); PG8_STAGE(PG8_SA(1, 1), a1 + hstep, voffA);
;             PG8_WAIT_V(8); PG8_WAIT_L(0); PG8_BAR; PG8_MMA(0, 0, At, B0); PG8_MMA(0, 1, At, B1); PG8_BAR; PG8_SCHED;
;             PG8_LDA(At, 0, 1); PG8_STAGE(PG8_SB(0, 0), b2, voffB); PG8_STAGE(PG8_SB(0, 1), b2 + hstep, voffB); PG8_STAGE(PG8_SA(0, 0), a2, voffA);
;             PG8_WAIT_V(8); PG8_WAIT_L(0); PG8_BAR; PG8_MMA(1, 0, At, B0); PG8_MMA(1, 1, At, B1); PG8_BAR; PG8_SCHED;
;             PG8_LDB(B0, 1, 0); PG8_LDB(B1, 1, 1); PG8_SCHED; PG8_LDA(At, 1, 0); PG8_STAGE(PG8_SA(0, 1), a2 + hstep, voffA);
;             PG8_WAIT_V(8); PG8_WAIT_L(0); PG8_BAR; PG8_MMA(0, 0, At, B0); PG8_MMA(0, 1, At, B1); PG8_BAR; PG8_SCHED;
;             PG8_LDA(At, 1, 1); PG8_STAGE(PG8_SB(1, 0), b3, voffB); PG8_STAGE(PG8_SB(1, 1), b3 + hstep, voffB); PG8_STAGE(PG8_SA(1, 0), a3, voffA);
;             PG8_WAIT_V(8); PG8_WAIT_L(0); PG8_BAR; PG8_MMA(1, 0, At, B0); PG8_MMA(1, 1, At, B1); PG8_BAR; PG8_SCHED;
	s_mov_b64 s[92:93], 0x180
	s_mov_b32 m0, s17
	v_lshl_add_u64 v[136:137], v[136:137], 0, s[92:93]
	s_add_u32 s50, s90, 0x10180
	ds_read_b128 v[172:175], v138 offset:49152
	ds_read_b128 v[176:179], v138 offset:50176
	ds_read_b128 v[184:187], v138 offset:51200
	ds_read_b128 v[188:191], v138 offset:52224
	ds_read_b128 v[192:195], v138 offset:53248
	ds_read_b128 v[196:199], v138 offset:54272
	ds_read_b128 v[200:203], v138 offset:55296
	ds_read_b128 v[204:207], v138 offset:56320
	global_load_lds_dwordx4 v[136:137], off
	v_lshl_add_u64 v[136:137], v[180:181], 0, s[92:93]
	s_mov_b32 m0, s20
	s_addc_u32 s51, s91, 0
	global_load_lds_dwordx4 v[136:137], off
	v_lshl_add_u64 v[136:137], s[50:51], 0, v[0:1]
	s_mov_b32 m0, s26
	s_nop 0
	global_load_lds_dwordx4 v[136:137], off
	v_lshl_add_u64 v[136:137], s[50:51], 0, v[130:131]
	s_mov_b32 m0, s27
	s_nop 0
	global_load_lds_dwordx4 v[136:137], off
	v_lshl_add_u64 v[136:137], v[182:183], 0, s[92:93]
	s_mov_b32 m0, s21
	s_nop 0
	global_load_lds_dwordx4 v[136:137], off
	v_lshl_add_u64 v[136:137], v[214:215], 0, s[92:93]
	s_mov_b32 m0, s24
	s_nop 0
	global_load_lds_dwordx4 v[136:137], off
	s_waitcnt vmcnt(8)
	s_waitcnt lgkmcnt(0)
	s_barrier
	s_waitcnt lgkmcnt(0)
	v_mfma_f32_16x16x32_bf16 v[2:5], v[26:29], v[200:203], v[2:5]
	v_mfma_f32_16x16x32_bf16 v[2:5], v[30:33], v[204:207], v[2:5]
	v_mfma_f32_16x16x32_bf16 v[6:9], v[114:117], v[200:203], v[6:9]
	v_mfma_f32_16x16x32_bf16 v[6:9], v[118:121], v[204:207], v[6:9]
	v_mfma_f32_16x16x32_bf16 v[140:143], v[26:29], v[172:175], v[140:143]
	v_mfma_f32_16x16x32_bf16 v[140:143], v[30:33], v[176:179], v[140:143]
	v_mfma_f32_16x16x32_bf16 v[144:147], v[114:117], v[172:175], v[144:147]
	v_mfma_f32_16x16x32_bf16 v[144:147], v[118:121], v[176:179], v[144:147]
	v_mfma_f32_16x16x32_bf16 v[148:151], v[26:29], v[184:187], v[148:151]
	v_mfma_f32_16x16x32_bf16 v[148:151], v[30:33], v[188:191], v[148:151]
	v_mfma_f32_16x16x32_bf16 v[152:155], v[114:117], v[184:187], v[152:155]
	v_mfma_f32_16x16x32_bf16 v[152:155], v[118:121], v[188:191], v[152:155]
	v_mfma_f32_16x16x32_bf16 v[156:159], v[26:29], v[192:195], v[156:159]
	v_mfma_f32_16x16x32_bf16 v[156:159], v[30:33], v[196:199], v[156:159]
	v_mfma_f32_16x16x32_bf16 v[160:163], v[114:117], v[192:195], v[160:163]
	v_mfma_f32_16x16x32_bf16 v[160:163], v[118:121], v[196:199], v[160:163]
	v_mfma_f32_16x16x32_bf16 v[10:13], v[122:125], v[172:175], v[10:13]
	v_mfma_f32_16x16x32_bf16 v[14:17], v[164:167], v[172:175], v[14:17]
	v_mfma_f32_16x16x32_bf16 v[26:29], v[122:125], v[184:187], v[62:65]
	v_mfma_f32_16x16x32_bf16 v[30:33], v[164:167], v[184:187], v[102:105]
	v_mfma_f32_16x16x32_bf16 v[62:65], v[122:125], v[192:195], v[106:109]
	v_mfma_f32_16x16x32_bf16 v[102:105], v[164:167], v[192:195], v[110:113]
	v_mfma_f32_16x16x32_bf16 v[18:21], v[122:125], v[200:203], v[18:21]
	v_mfma_f32_16x16x32_bf16 v[22:25], v[164:167], v[200:203], v[22:25]
	v_mfma_f32_16x16x32_bf16 v[10:13], v[126:129], v[176:179], v[10:13]
	v_mfma_f32_16x16x32_bf16 v[14:17], v[168:171], v[176:179], v[14:17]
	v_mfma_f32_16x16x32_bf16 v[26:29], v[126:129], v[188:191], v[26:29]
	v_mfma_f32_16x16x32_bf16 v[30:33], v[168:171], v[188:191], v[30:33]
	v_mfma_f32_16x16x32_bf16 v[62:65], v[126:129], v[196:199], v[62:65]
	v_mfma_f32_16x16x32_bf16 v[102:105], v[168:171], v[196:199], v[102:105]
	v_mfma_f32_16x16x32_bf16 v[18:21], v[126:129], v[204:207], v[18:21]
	v_mfma_f32_16x16x32_bf16 v[22:25], v[168:171], v[204:207], v[22:25]
	s_barrier
	ds_read_b128 v[106:109], v208
	ds_read_b128 v[110:113], v209
	ds_read_b128 v[114:117], v210
	ds_read_b128 v[118:121], v211
	ds_read_b128 v[122:125], v212
	ds_read_b128 v[126:129], v213
	ds_read_b128 v[164:167], v218
	ds_read_b128 v[168:171], v219
	s_add_u32 s50, s88, 0x10180
	s_addc_u32 s51, s89, 0
	s_mov_b32 m0, s43
	v_lshl_add_u64 v[136:137], s[50:51], 0, v[134:135]
	ds_read_b128 v[172:175], v138
	ds_read_b128 v[176:179], v138 offset:1024
	ds_read_b128 v[184:187], v138 offset:2048
	ds_read_b128 v[188:191], v138 offset:3072
	ds_read_b128 v[192:195], v138 offset:4096
	ds_read_b128 v[196:199], v138 offset:5120
	ds_read_b128 v[200:203], v138 offset:6144
	ds_read_b128 v[204:207], v138 offset:7168
	global_load_lds_dwordx4 v[136:137], off
	v_lshl_add_u64 v[136:137], s[50:51], 0, v[132:133]
	s_mov_b32 m0, s41
	s_nop 0
	global_load_lds_dwordx4 v[136:137], off
	s_waitcnt vmcnt(8)
	s_waitcnt lgkmcnt(0)
	s_barrier
	s_waitcnt lgkmcnt(0)
	v_mfma_f32_16x16x32_bf16 v[66:69], v[106:109], v[172:175], v[66:69]
	v_mfma_f32_16x16x32_bf16 v[70:73], v[114:117], v[172:175], v[70:73]
	v_mfma_f32_16x16x32_bf16 v[74:77], v[106:109], v[184:187], v[74:77]
	v_mfma_f32_16x16x32_bf16 v[78:81], v[114:117], v[184:187], v[78:81]
	v_mfma_f32_16x16x32_bf16 v[82:85], v[106:109], v[192:195], v[82:85]
	v_mfma_f32_16x16x32_bf16 v[86:89], v[114:117], v[192:195], v[86:89]
	v_mfma_f32_16x16x32_bf16 v[90:93], v[106:109], v[200:203], v[90:93]
	v_mfma_f32_16x16x32_bf16 v[66:69], v[110:113], v[176:179], v[66:69]
	v_mfma_f32_16x16x32_bf16 v[70:73], v[118:121], v[176:179], v[70:73]
	v_mfma_f32_16x16x32_bf16 v[74:77], v[110:113], v[188:191], v[74:77]
	v_mfma_f32_16x16x32_bf16 v[78:81], v[118:121], v[188:191], v[78:81]
	v_mfma_f32_16x16x32_bf16 v[82:85], v[110:113], v[196:199], v[82:85]
	v_mfma_f32_16x16x32_bf16 v[86:89], v[118:121], v[196:199], v[86:89]
	v_mfma_f32_16x16x32_bf16 v[90:93], v[110:113], v[204:207], v[90:93]
	v_mfma_f32_16x16x32_bf16 v[94:97], v[114:117], v[200:203], v[94:97]
	v_mfma_f32_16x16x32_bf16 v[214:217], v[118:121], v[204:207], v[94:97]
	v_mfma_f32_16x16x32_bf16 v[94:97], v[122:125], v[172:175], v[98:101]
	v_mfma_f32_16x16x32_bf16 v[34:37], v[164:167], v[172:175], v[34:37]
	v_mfma_f32_16x16x32_bf16 v[38:41], v[122:125], v[184:187], v[38:41]
	v_mfma_f32_16x16x32_bf16 v[42:45], v[164:167], v[184:187], v[42:45]
	v_mfma_f32_16x16x32_bf16 v[46:49], v[122:125], v[192:195], v[46:49]
	v_mfma_f32_16x16x32_bf16 v[50:53], v[164:167], v[192:195], v[50:53]
	v_mfma_f32_16x16x32_bf16 v[54:57], v[122:125], v[200:203], v[54:57]
	v_mfma_f32_16x16x32_bf16 v[98:101], v[126:129], v[176:179], v[94:97]
	v_mfma_f32_16x16x32_bf16 v[34:37], v[168:171], v[176:179], v[34:37]
	v_mfma_f32_16x16x32_bf16 v[38:41], v[126:129], v[188:191], v[38:41]
	v_mfma_f32_16x16x32_bf16 v[42:45], v[168:171], v[188:191], v[42:45]
	v_mfma_f32_16x16x32_bf16 v[46:49], v[126:129], v[196:199], v[46:49]
	v_mfma_f32_16x16x32_bf16 v[50:53], v[168:171], v[196:199], v[50:53]
	v_mfma_f32_16x16x32_bf16 v[172:175], v[126:129], v[204:207], v[54:57]
	v_mfma_f32_16x16x32_bf16 v[54:57], v[164:167], v[200:203], v[58:61]
	v_mfma_f32_16x16x32_bf16 v[176:179], v[168:171], v[204:207], v[54:57]
	s_barrier
; #define PG8_STAGE(bufoff, gbase, voff) do { _Pragma("unroll") for (int _i = 0; _i < 2; ++_i) \
;         __builtin_amdgcn_global_load_lds((const unsigned*)((const char*)(gbase) + (voff)[_i]), (PG8_LAS unsigned*)(lds + (bufoff) + ldsw + _i * 8192), 16, 0, 0); } while (0)
; #define PG8_LDA(dst, b, h) do { _Pragma("unroll") for (int m = 0; m < 4; ++m) _Pragma("unroll") for (int k = 0; k < 2; ++k) dst[m][k] = *(const PG8_LAS bf16x8*)(lds + PG8_SA(b, h) + aoff + m * 2048 + k * 1024); } while (0)
; #define PG8_LDB(dst, b, h) do { _Pragma("unroll") for (int n = 0; n < 2; ++n) _Pragma("unroll") for (int k = 0; k < 2; ++k) dst[n][k] = *(const PG8_LAS bf16x8*)(lds + PG8_SB(b, h) + boff + n * 2048 + k * 1024); } while (0)
; #define PG8_MMA(ai, bj, At, Bt) do { __builtin_amdgcn_s_setprio(1); _Pragma("unroll") for (int m = 0; m < 4; ++m) _Pragma("unroll") for (int n = 0; n < 2; ++n) _Pragma("unroll") for (int k = 0; k < 2; ++k) \
;         acc[ai][bj][m][n] = __builtin_amdgcn_mfma_f32_16x16x32_bf16(Bt[n][k], At[m][k], acc[ai][bj][m][n], 0, 0, 0); __builtin_amdgcn_s_setprio(0); } while (0)
; #define PG8_WAIT_V(n) asm volatile("s_waitcnt vmcnt(" #n ")" ::: "memory")
; #define PG8_WAIT_L(n) asm volatile("s_waitcnt lgkmcnt(" #n ")" ::: "memory")
; #define PG8_BAR __builtin_amdgcn_s_barrier()
; #define PG8_SCHED __builtin_amdgcn_sched_barrier(0)
; template <class Epi, class Sched, bool ALIGN_EPI = false, bool SP2 = false>
; __device__ __forceinline__ void gemm_phase(PG8_LAS unsigned char* lds, const Gemm g, const Sched& S, const Epi& E, const int tid) {
;     ...
;             PG8_LDA(At, 0, 1); PG8_STAGE(PG8_SB(0, 0), b2, voffB); PG8_STAGE(PG8_SB(0, 1), b2 + hstep, voffB); PG8_STAGE(PG8_SA(0, 0), a2, voffA);
;             PG8_WAIT_V(8); PG8_WAIT_L(0); PG8_BAR; PG8_MMA(1, 0, At, B0); PG8_MMA(1, 1, At, B1); PG8_BAR; PG8_SCHED;
;             PG8_LDB(B0, 1, 0); PG8_LDB(B1, 1, 1); PG8_SCHED; PG8_LDA(At, 1, 0); PG8_STAGE(PG8_SA(0, 1), a2 + hstep, voffA);
	s_mov_b32 m0, s1
	v_lshl_add_u64 v[136:137], s[84:85], 0, v[0:1]
	s_add_u32 s50, s84, 0x10000
	s_nop 1
	ds_read_b128 v[54:57], v138 offset:16384
	ds_read_b128 v[58:61], v138 offset:17408
	ds_read_b128 v[94:97], v138 offset:18432
	ds_read_b128 v[184:187], v138 offset:19456
	ds_read_b128 v[188:191], v138 offset:20480
	ds_read_b128 v[192:195], v138 offset:21504
	ds_read_b128 v[196:199], v138 offset:22528
	ds_read_b128 v[200:203], v138 offset:23552
	global_load_lds_dwordx4 v[136:137], off
	v_lshl_add_u64 v[208:209], s[84:85], 0, v[130:131]
	s_mov_b32 m0, s2
	s_addc_u32 s51, s85, 0
	global_load_lds_dwordx4 v[208:209], off
	v_lshl_add_u64 v[180:181], s[50:51], 0, v[0:1]
	s_mov_b32 m0, s4
	v_lshl_add_u64 v[210:211], s[86:87], 0, v[134:135]
	global_load_lds_dwordx4 v[180:181], off
	v_lshl_add_u64 v[180:181], s[50:51], 0, v[130:131]
	s_mov_b32 m0, s5
	v_lshl_add_u64 v[212:213], s[86:87], 0, v[132:133]
	global_load_lds_dwordx4 v[180:181], off
	s_mov_b32 m0, s0
	s_nop 0
	global_load_lds_dwordx4 v[210:211], off
	s_mov_b32 m0, s6
	s_nop 0
	global_load_lds_dwordx4 v[212:213], off
	s_waitcnt vmcnt(8)
	s_waitcnt lgkmcnt(0)
	s_barrier
	s_waitcnt lgkmcnt(0)
	v_mfma_f32_16x16x32_bf16 v[2:5], v[106:109], v[196:199], v[2:5]
	v_mfma_f32_16x16x32_bf16 v[2:5], v[110:113], v[200:203], v[2:5]
	v_mfma_f32_16x16x32_bf16 v[6:9], v[114:117], v[196:199], v[6:9]
	v_mfma_f32_16x16x32_bf16 v[6:9], v[118:121], v[200:203], v[6:9]
	v_mfma_f32_16x16x32_bf16 v[140:143], v[106:109], v[54:57], v[140:143]
	v_mfma_f32_16x16x32_bf16 v[140:143], v[110:113], v[58:61], v[140:143]
	v_mfma_f32_16x16x32_bf16 v[144:147], v[114:117], v[54:57], v[144:147]
	v_mfma_f32_16x16x32_bf16 v[144:147], v[118:121], v[58:61], v[144:147]
	v_mfma_f32_16x16x32_bf16 v[148:151], v[106:109], v[94:97], v[148:151]
	v_mfma_f32_16x16x32_bf16 v[148:151], v[110:113], v[184:187], v[148:151]
	v_mfma_f32_16x16x32_bf16 v[152:155], v[114:117], v[94:97], v[152:155]
	v_mfma_f32_16x16x32_bf16 v[152:155], v[118:121], v[184:187], v[152:155]
	v_mfma_f32_16x16x32_bf16 v[156:159], v[106:109], v[188:191], v[156:159]
	v_mfma_f32_16x16x32_bf16 v[156:159], v[110:113], v[192:195], v[156:159]
	v_mfma_f32_16x16x32_bf16 v[160:163], v[114:117], v[188:191], v[160:163]
	v_mfma_f32_16x16x32_bf16 v[160:163], v[118:121], v[192:195], v[160:163]
	v_mfma_f32_16x16x32_bf16 v[14:17], v[164:167], v[54:57], v[14:17]
	v_mfma_f32_16x16x32_bf16 v[204:207], v[168:171], v[58:61], v[14:17]
	v_mfma_f32_16x16x32_bf16 v[14:17], v[122:125], v[94:97], v[26:29]
	v_mfma_f32_16x16x32_bf16 v[26:29], v[126:129], v[184:187], v[14:17]
	v_mfma_f32_16x16x32_bf16 v[14:17], v[164:167], v[94:97], v[30:33]
	v_mfma_f32_16x16x32_bf16 v[184:187], v[168:171], v[184:187], v[14:17]
	v_mfma_f32_16x16x32_bf16 v[14:17], v[122:125], v[188:191], v[62:65]
	v_mfma_f32_16x16x32_bf16 v[218:221], v[126:129], v[192:195], v[14:17]
	v_mfma_f32_16x16x32_bf16 v[14:17], v[164:167], v[188:191], v[102:105]
	v_mfma_f32_16x16x32_bf16 v[10:13], v[122:125], v[54:57], v[10:13]
	v_mfma_f32_16x16x32_bf16 v[188:191], v[168:171], v[192:195], v[14:17]
	v_mfma_f32_16x16x32_bf16 v[14:17], v[122:125], v[196:199], v[18:21]
	v_mfma_f32_16x16x32_bf16 v[10:13], v[126:129], v[58:61], v[10:13]
	v_mfma_f32_16x16x32_bf16 v[192:195], v[126:129], v[200:203], v[14:17]
	v_mfma_f32_16x16x32_bf16 v[14:17], v[164:167], v[196:199], v[22:25]
	v_mfma_f32_16x16x32_bf16 v[164:167], v[168:171], v[200:203], v[14:17]
	s_barrier
	s_nop 4
	ds_read_b128 v[14:17], v222
	ds_read_b128 v[18:21], v223
	ds_read_b128 v[168:171], v224
	ds_read_b128 v[196:199], v225
	ds_read_b128 v[200:203], v226
	ds_read_b128 v[222:225], v227
	ds_read_b128 v[226:229], v228
	ds_read_b128 v[230:233], v230
	s_add_u32 s50, s86, 0x10000
	s_addc_u32 s51, s87, 0
	s_mov_b32 m0, s8
	v_lshl_add_u64 v[54:55], s[50:51], 0, v[134:135]
	ds_read_b128 v[22:25], v138 offset:32768
	ds_read_b128 v[30:33], v138 offset:33792
	ds_read_b128 v[58:61], v138 offset:34816
	ds_read_b128 v[234:237], v138 offset:35840
	ds_read_b128 v[238:241], v138 offset:36864
	ds_read_b128 v[242:245], v138 offset:37888
	ds_read_b128 v[246:249], v138 offset:38912
	ds_read_b128 v[180:183], v138 offset:39936
	global_load_lds_dwordx4 v[54:55], off
	v_lshl_add_u64 v[54:55], s[50:51], 0, v[132:133]
	s_mov_b32 m0, s9
	s_nop 0
	global_load_lds_dwordx4 v[54:55], off
	s_waitcnt vmcnt(8)
	s_waitcnt lgkmcnt(0)
	s_barrier
; #define PG8_STAGE(bufoff, gbase, voff) do { _Pragma("unroll") for (int _i = 0; _i < 2; ++_i) \
;         __builtin_amdgcn_global_load_lds((const unsigned*)((const char*)(gbase) + (voff)[_i]), (PG8_LAS unsigned*)(lds + (bufoff) + ldsw + _i * 8192), 16, 0, 0); } while (0)
; #define PG8_LDA(dst, b, h) do { _Pragma("unroll") for (int m = 0; m < 4; ++m) _Pragma("unroll") for (int k = 0; k < 2; ++k) dst[m][k] = *(const PG8_LAS bf16x8*)(lds + PG8_SA(b, h) + aoff + m * 2048 + k * 1024); } while (0)
; #define PG8_MMA(ai, bj, At, Bt) do { __builtin_amdgcn_s_setprio(1); _Pragma("unroll") for (int m = 0; m < 4; ++m) _Pragma("unroll") for (int n = 0; n < 2; ++n) _Pragma("unroll") for (int k = 0; k < 2; ++k) \
;         acc[ai][bj][m][n] = __builtin_amdgcn_mfma_f32_16x16x32_bf16(Bt[n][k], At[m][k], acc[ai][bj][m][n], 0, 0, 0); __builtin_amdgcn_s_setprio(0); } while (0)
; #define PG8_WAIT_V(n) asm volatile("s_waitcnt vmcnt(" #n ")" ::: "memory")
; #define PG8_WAIT_L(n) asm volatile("s_waitcnt lgkmcnt(" #n ")" ::: "memory")
; #define PG8_BAR __builtin_amdgcn_s_barrier()
; #define PG8_SCHED __builtin_amdgcn_sched_barrier(0)
; template <class Epi, class Sched, bool ALIGN_EPI = false, bool SP2 = false>
; __device__ __forceinline__ void gemm_phase(PG8_LAS unsigned char* lds, const Gemm g, const Sched& S, const Epi& E, const int tid) {
;     ...
;             PG8_WAIT_V(8); PG8_WAIT_L(0); PG8_BAR; PG8_MMA(0, 0, At, B0); PG8_MMA(0, 1, At, B1); PG8_BAR; PG8_SCHED;
;             PG8_LDA(At, 1, 1); PG8_STAGE(PG8_SB(1, 0), b3, voffB); PG8_STAGE(PG8_SB(1, 1), b3 + hstep, voffB); PG8_STAGE(PG8_SA(1, 0), a3, voffA);
;             PG8_WAIT_V(8); PG8_WAIT_L(0); PG8_BAR; PG8_MMA(1, 0, At, B0); PG8_MMA(1, 1, At, B1); PG8_BAR; PG8_SCHED;
;     ...
;         if constexpr (ALIGN_EPI) { if (wr == 0) PG8_BAR; }
	s_waitcnt lgkmcnt(0)
	v_mfma_f32_16x16x32_bf16 v[54:57], v[14:17], v[22:25], v[66:69]
	v_mfma_f32_16x16x32_bf16 v[122:125], v[18:21], v[30:33], v[54:57]
	v_mfma_f32_16x16x32_bf16 v[54:57], v[168:171], v[22:25], v[70:73]
	v_mfma_f32_16x16x32_bf16 v[114:117], v[196:199], v[30:33], v[54:57]
	v_mfma_f32_16x16x32_bf16 v[54:57], v[14:17], v[58:61], v[74:77]
	v_mfma_f32_16x16x32_bf16 v[110:113], v[18:21], v[234:237], v[54:57]
	v_mfma_f32_16x16x32_bf16 v[54:57], v[168:171], v[58:61], v[78:81]
	v_mfma_f32_16x16x32_bf16 v[102:105], v[196:199], v[234:237], v[54:57]
	v_mfma_f32_16x16x32_bf16 v[54:57], v[14:17], v[238:241], v[82:85]
	v_mfma_f32_16x16x32_bf16 v[94:97], v[18:21], v[242:245], v[54:57]
	v_mfma_f32_16x16x32_bf16 v[54:57], v[168:171], v[238:241], v[86:89]
	v_mfma_f32_16x16x32_bf16 v[86:89], v[196:199], v[242:245], v[54:57]
	v_mfma_f32_16x16x32_bf16 v[54:57], v[14:17], v[246:249], v[90:93]
	v_mfma_f32_16x16x32_bf16 v[62:65], v[18:21], v[180:183], v[54:57]
	v_mfma_f32_16x16x32_bf16 v[54:57], v[168:171], v[246:249], v[214:217]
	v_mfma_f32_16x16x32_bf16 v[54:57], v[196:199], v[180:183], v[54:57]
	v_mfma_f32_16x16x32_bf16 v[66:69], v[200:203], v[22:25], v[98:101]
	v_mfma_f32_16x16x32_bf16 v[22:25], v[226:229], v[22:25], v[34:37]
	v_mfma_f32_16x16x32_bf16 v[118:121], v[230:233], v[30:33], v[22:25]
	v_mfma_f32_16x16x32_bf16 v[22:25], v[200:203], v[58:61], v[38:41]
	v_mfma_f32_16x16x32_bf16 v[106:109], v[222:225], v[234:237], v[22:25]
	v_mfma_f32_16x16x32_bf16 v[22:25], v[226:229], v[58:61], v[42:45]
	v_mfma_f32_16x16x32_bf16 v[98:101], v[230:233], v[234:237], v[22:25]
	v_mfma_f32_16x16x32_bf16 v[22:25], v[200:203], v[238:241], v[46:49]
	v_mfma_f32_16x16x32_bf16 v[90:93], v[222:225], v[242:245], v[22:25]
	v_mfma_f32_16x16x32_bf16 v[22:25], v[226:229], v[238:241], v[50:53]
	v_mfma_f32_16x16x32_bf16 v[82:85], v[230:233], v[242:245], v[22:25]
	v_mfma_f32_16x16x32_bf16 v[22:25], v[200:203], v[246:249], v[172:175]
	v_mfma_f32_16x16x32_bf16 v[58:61], v[222:225], v[180:183], v[22:25]
	v_mfma_f32_16x16x32_bf16 v[22:25], v[226:229], v[246:249], v[176:179]
	v_mfma_f32_16x16x32_bf16 v[126:129], v[222:225], v[30:33], v[66:69]
	v_mfma_f32_16x16x32_bf16 v[50:53], v[230:233], v[180:183], v[22:25]
	s_barrier
	s_mov_b32 m0, s17
	s_nop 2
	v_lshl_add_u64 v[22:23], v[136:137], 0, s[12:13]
	s_add_u32 s50, s84, 0x10080
	ds_read_b128 v[34:37], v138 offset:49152
	ds_read_b128 v[42:45], v138 offset:50176
	ds_read_b128 v[172:175], v138 offset:51200
	ds_read_b128 v[176:179], v138 offset:52224
	ds_read_b128 v[180:183], v138 offset:53248
	ds_read_b128 v[214:217], v138 offset:54272
	ds_read_b128 v[234:237], v138 offset:55296
	ds_read_b128 v[238:241], v138 offset:56320
	global_load_lds_dwordx4 v[22:23], off
	v_lshl_add_u64 v[22:23], v[208:209], 0, s[12:13]
	s_mov_b32 m0, s20
	s_addc_u32 s51, s85, 0
	global_load_lds_dwordx4 v[22:23], off
	v_lshl_add_u64 v[22:23], s[50:51], 0, v[0:1]
	s_mov_b32 m0, s26
	s_nop 0
	global_load_lds_dwordx4 v[22:23], off
	v_lshl_add_u64 v[22:23], s[50:51], 0, v[130:131]
	s_mov_b32 m0, s27
	s_nop 0
	global_load_lds_dwordx4 v[22:23], off
	v_lshl_add_u64 v[22:23], v[210:211], 0, s[12:13]
	s_mov_b32 m0, s21
	s_nop 0
	global_load_lds_dwordx4 v[22:23], off
	v_lshl_add_u64 v[22:23], v[212:213], 0, s[12:13]
	s_mov_b32 m0, s24
	s_nop 0
	global_load_lds_dwordx4 v[22:23], off
	s_waitcnt vmcnt(8)
	s_waitcnt lgkmcnt(0)
	s_barrier
	s_waitcnt lgkmcnt(0)
	v_mfma_f32_16x16x32_bf16 v[22:25], v[14:17], v[34:37], v[140:143]
	v_mfma_f32_16x16x32_bf16 v[78:81], v[18:21], v[42:45], v[22:25]
	v_mfma_f32_16x16x32_bf16 v[22:25], v[168:171], v[34:37], v[144:147]
	v_mfma_f32_16x16x32_bf16 v[70:73], v[196:199], v[42:45], v[22:25]
	v_mfma_f32_16x16x32_bf16 v[22:25], v[14:17], v[172:175], v[148:151]
	v_mfma_f32_16x16x32_bf16 v[46:49], v[18:21], v[176:179], v[22:25]
	v_mfma_f32_16x16x32_bf16 v[22:25], v[168:171], v[172:175], v[152:155]
	v_mfma_f32_16x16x32_bf16 v[38:41], v[196:199], v[176:179], v[22:25]
	v_mfma_f32_16x16x32_bf16 v[22:25], v[14:17], v[180:183], v[156:159]
	v_mfma_f32_16x16x32_bf16 v[2:5], v[14:17], v[234:237], v[2:5]
	v_mfma_f32_16x16x32_bf16 v[30:33], v[18:21], v[214:217], v[22:25]
	v_mfma_f32_16x16x32_bf16 v[22:25], v[168:171], v[180:183], v[160:163]
	v_mfma_f32_16x16x32_bf16 v[14:17], v[18:21], v[238:241], v[2:5]
	v_mfma_f32_16x16x32_bf16 v[2:5], v[168:171], v[234:237], v[6:9]
	v_mfma_f32_16x16x32_bf16 v[22:25], v[196:199], v[214:217], v[22:25]
	v_mfma_f32_16x16x32_bf16 v[6:9], v[196:199], v[238:241], v[2:5]
	v_mfma_f32_16x16x32_bf16 v[2:5], v[200:203], v[34:37], v[10:13]
	v_mfma_f32_16x16x32_bf16 v[74:77], v[222:225], v[42:45], v[2:5]
	v_mfma_f32_16x16x32_bf16 v[2:5], v[226:229], v[34:37], v[204:207]
	v_mfma_f32_16x16x32_bf16 v[66:69], v[230:233], v[42:45], v[2:5]
	v_mfma_f32_16x16x32_bf16 v[2:5], v[200:203], v[172:175], v[26:29]
	v_mfma_f32_16x16x32_bf16 v[42:45], v[222:225], v[176:179], v[2:5]
	v_mfma_f32_16x16x32_bf16 v[2:5], v[226:229], v[172:175], v[184:187]
	v_mfma_f32_16x16x32_bf16 v[34:37], v[230:233], v[176:179], v[2:5]
	v_mfma_f32_16x16x32_bf16 v[2:5], v[200:203], v[180:183], v[218:221]
	v_mfma_f32_16x16x32_bf16 v[26:29], v[222:225], v[214:217], v[2:5]
	v_mfma_f32_16x16x32_bf16 v[2:5], v[226:229], v[180:183], v[188:191]
	v_mfma_f32_16x16x32_bf16 v[18:21], v[230:233], v[214:217], v[2:5]
	v_mfma_f32_16x16x32_bf16 v[2:5], v[200:203], v[234:237], v[192:195]
	v_mfma_f32_16x16x32_bf16 v[10:13], v[222:225], v[238:241], v[2:5]
	v_mfma_f32_16x16x32_bf16 v[2:5], v[226:229], v[234:237], v[164:167]
	v_mfma_f32_16x16x32_bf16 v[2:5], v[230:233], v[238:241], v[2:5]
	s_barrier
	s_andn2_b64 vcc, exec, s[30:31]
	s_cbranch_vccnz .LBB0_372
	s_barrier

; #define PG8_STAGE(bufoff, gbase, voff) do { _Pragma("unroll") for (int _i = 0; _i < 2; ++_i) \
;         __builtin_amdgcn_global_load_lds((const unsigned*)((const char*)(gbase) + (voff)[_i]), (PG8_LAS unsigned*)(lds + (bufoff) + ldsw + _i * 8192), 16, 0, 0); } while (0)
; #define PG8_LDA(dst, b, h) do { _Pragma("unroll") for (int m = 0; m < 4; ++m) _Pragma("unroll") for (int k = 0; k < 2; ++k) dst[m][k] = *(const PG8_LAS bf16x8*)(lds + PG8_SA(b, h) + aoff + m * 2048 + k * 1024); } while (0)
; #define PG8_LDB(dst, b, h) do { _Pragma("unroll") for (int n = 0; n < 2; ++n) _Pragma("unroll") for (int k = 0; k < 2; ++k) dst[n][k] = *(const PG8_LAS bf16x8*)(lds + PG8_SB(b, h) + boff + n * 2048 + k * 1024); } while (0)
; #define PG8_MMA(ai, bj, At, Bt) do { __builtin_amdgcn_s_setprio(1); _Pragma("unroll") for (int m = 0; m < 4; ++m) _Pragma("unroll") for (int n = 0; n < 2; ++n) _Pragma("unroll") for (int k = 0; k < 2; ++k) \
;         acc[ai][bj][m][n] = __builtin_amdgcn_mfma_f32_16x16x32_bf16(Bt[n][k], At[m][k], acc[ai][bj][m][n], 0, 0, 0); __builtin_amdgcn_s_setprio(0); } while (0)
; #define PG8_WAIT_V(n) asm volatile("s_waitcnt vmcnt(" #n ")" ::: "memory")
; #define PG8_WAIT_L(n) asm volatile("s_waitcnt lgkmcnt(" #n ")" ::: "memory")
; #define PG8_BAR __builtin_amdgcn_s_barrier()
; #define PG8_SCHED __builtin_amdgcn_sched_barrier(0)
; template <class Epi, class Sched, bool ALIGN_EPI = false, bool SP2 = false>
; __device__ __forceinline__ void gemm_phase(PG8_LAS unsigned char* lds, const Gemm g, const Sched& S, const Epi& E, const int tid) {
;     ...
;             PG8_LDB(B0, 0, 0); PG8_LDB(B1, 0, 1); PG8_SCHED; PG8_LDA(At, 0, 0); PG8_STAGE(PG8_SA(1, 1), a1 + hstep, voffA);
;             PG8_WAIT_V(8); PG8_WAIT_L(0); PG8_BAR; PG8_MMA(0, 0, At, B0); PG8_MMA(0, 1, At, B1); PG8_BAR; PG8_SCHED;
;             PG8_LDA(At, 0, 1); PG8_STAGE(PG8_SB(0, 0), b2, voffB); PG8_STAGE(PG8_SB(0, 1), b2 + hstep, voffB); PG8_STAGE(PG8_SA(0, 0), a2, voffA);
;             PG8_WAIT_V(8); PG8_WAIT_L(0); PG8_BAR; PG8_MMA(1, 0, At, B0); PG8_MMA(1, 1, At, B1); PG8_BAR; PG8_SCHED;
.LBB0_388:
	v_or_b32_e32 v0, 0x10000, v179
	v_add_u32_e32 v11, 0x10800, v179
	v_or_b32_e32 v13, 0x14000, v179
	v_add_u32_e32 v15, 0x14800, v179
	v_add_u32_e32 v10, 0x10400, v179
	ds_read_b128 v[18:21], v0
	ds_read_b128 v[22:25], v10
	v_add_u32_e32 v12, 0x10c00, v179
	ds_read_b128 v[26:29], v11
	ds_read_b128 v[30:33], v12
	v_add_u32_e32 v14, 0x14400, v179
	ds_read_b128 v[34:37], v13
	ds_read_b128 v[38:41], v14
	v_add_u32_e32 v16, 0x14c00, v179
	ds_read_b128 v[42:45], v15
	ds_read_b128 v[46:49], v16
	s_add_u32 s20, s30, 0x18080
	s_addc_u32 s21, s31, 0
	s_add_i32 s5, s1, 0xc000
	v_lshl_add_u64 v[74:75], s[20:21], 0, v[168:169]
	s_mov_b32 m0, s5
	s_add_i32 s4, s1, 0xe000
	ds_read_b128 v[2:5], v178
	ds_read_b128 v[6:9], v178 offset:1024
	ds_read_b128 v[50:53], v178 offset:2048
	ds_read_b128 v[54:57], v178 offset:3072
	ds_read_b128 v[58:61], v178 offset:4096
	ds_read_b128 v[62:65], v178 offset:5120
	ds_read_b128 v[66:69], v178 offset:6144
	ds_read_b128 v[70:73], v178 offset:7168
	global_load_lds_dwordx4 v[74:75], off
	v_lshl_add_u64 v[74:75], s[20:21], 0, v[164:165]
	s_mov_b32 m0, s4
	s_nop 0
	global_load_lds_dwordx4 v[74:75], off
	s_waitcnt vmcnt(8)
	s_waitcnt lgkmcnt(0)
	s_barrier
	s_waitcnt lgkmcnt(0)
	v_mfma_f32_16x16x32_bf16 v[74:77], v[18:21], v[2:5], 0
	v_mfma_f32_16x16x32_bf16 v[78:81], v[26:29], v[2:5], 0
	v_mfma_f32_16x16x32_bf16 v[82:85], v[18:21], v[50:53], 0
	v_mfma_f32_16x16x32_bf16 v[86:89], v[26:29], v[50:53], 0
	v_mfma_f32_16x16x32_bf16 v[90:93], v[18:21], v[58:61], 0
	v_mfma_f32_16x16x32_bf16 v[94:97], v[26:29], v[58:61], 0
	v_mfma_f32_16x16x32_bf16 v[98:101], v[18:21], v[66:69], 0
	v_mfma_f32_16x16x32_bf16 v[102:105], v[26:29], v[66:69], 0
	v_mfma_f32_16x16x32_bf16 v[74:77], v[22:25], v[6:9], v[74:77]
	v_mfma_f32_16x16x32_bf16 v[78:81], v[30:33], v[6:9], v[78:81]
	v_mfma_f32_16x16x32_bf16 v[82:85], v[22:25], v[54:57], v[82:85]
	v_mfma_f32_16x16x32_bf16 v[86:89], v[30:33], v[54:57], v[86:89]
	v_mfma_f32_16x16x32_bf16 v[90:93], v[22:25], v[62:65], v[90:93]
	v_mfma_f32_16x16x32_bf16 v[94:97], v[30:33], v[62:65], v[94:97]
	v_mfma_f32_16x16x32_bf16 v[98:101], v[22:25], v[70:73], v[98:101]
	v_mfma_f32_16x16x32_bf16 v[102:105], v[30:33], v[70:73], v[102:105]
	v_mfma_f32_16x16x32_bf16 v[106:109], v[34:37], v[2:5], 0
	v_mfma_f32_16x16x32_bf16 v[2:5], v[42:45], v[2:5], 0
	v_mfma_f32_16x16x32_bf16 v[110:113], v[46:49], v[6:9], v[2:5]
	v_mfma_f32_16x16x32_bf16 v[2:5], v[34:37], v[50:53], 0
	v_mfma_f32_16x16x32_bf16 v[114:117], v[38:41], v[54:57], v[2:5]
	v_mfma_f32_16x16x32_bf16 v[2:5], v[42:45], v[50:53], 0
	v_mfma_f32_16x16x32_bf16 v[50:53], v[46:49], v[54:57], v[2:5]
	v_mfma_f32_16x16x32_bf16 v[2:5], v[34:37], v[58:61], 0
	v_mfma_f32_16x16x32_bf16 v[54:57], v[38:41], v[62:65], v[2:5]
	v_mfma_f32_16x16x32_bf16 v[2:5], v[42:45], v[58:61], 0
	v_mfma_f32_16x16x32_bf16 v[58:61], v[46:49], v[62:65], v[2:5]
	v_mfma_f32_16x16x32_bf16 v[2:5], v[34:37], v[66:69], 0
	v_mfma_f32_16x16x32_bf16 v[62:65], v[38:41], v[70:73], v[2:5]
	v_mfma_f32_16x16x32_bf16 v[2:5], v[42:45], v[66:69], 0
	v_mfma_f32_16x16x32_bf16 v[106:109], v[38:41], v[6:9], v[106:109]
	v_mfma_f32_16x16x32_bf16 v[66:69], v[46:49], v[70:73], v[2:5]
	s_barrier
	s_nop 3
	v_lshl_add_u64 v[2:3], s[46:47], 0, v[166:167]
	s_mov_b64 s[26:27], 0x100
	s_mov_b32 m0, s8
	v_lshl_add_u64 v[4:5], v[2:3], 0, s[26:27]
	ds_read_b128 v[70:73], v178 offset:16384
	ds_read_b128 v[118:121], v178 offset:17408
	ds_read_b128 v[122:125], v178 offset:18432
	ds_read_b128 v[126:129], v178 offset:19456
	ds_read_b128 v[130:133], v178 offset:20480
	ds_read_b128 v[134:137], v178 offset:21504
	ds_read_b128 v[138:141], v178 offset:22528
	ds_read_b128 v[142:145], v178 offset:23552
	global_load_lds_dwordx4 v[4:5], off
	v_lshl_add_u64 v[4:5], s[46:47], 0, v[162:163]
	s_add_u32 s20, s46, 0x18100
	v_lshl_add_u64 v[6:7], v[4:5], 0, s[26:27]
	s_mov_b32 m0, s9
	s_addc_u32 s21, s47, 0
	global_load_lds_dwordx4 v[6:7], off
	v_lshl_add_u64 v[6:7], s[20:21], 0, v[166:167]
	s_mov_b32 m0, s14
	s_nop 0
	global_load_lds_dwordx4 v[6:7], off
	v_lshl_add_u64 v[6:7], s[20:21], 0, v[162:163]
	s_mov_b32 m0, s34
	s_nop 0
	global_load_lds_dwordx4 v[6:7], off
	v_lshl_add_u64 v[6:7], s[30:31], 0, v[168:169]
	v_lshl_add_u64 v[8:9], v[6:7], 0, s[26:27]
	s_mov_b32 m0, s1
	s_nop 0
	global_load_lds_dwordx4 v[8:9], off
	v_lshl_add_u64 v[8:9], s[30:31], 0, v[164:165]
	v_lshl_add_u64 v[146:147], v[8:9], 0, s[26:27]
	s_mov_b32 m0, s35
	s_nop 0
	global_load_lds_dwordx4 v[146:147], off
	s_waitcnt vmcnt(8)
	s_waitcnt lgkmcnt(0)
	s_barrier
	s_waitcnt lgkmcnt(0)
	v_mfma_f32_16x16x32_bf16 v[146:149], v[18:21], v[70:73], 0
	v_mfma_f32_16x16x32_bf16 v[154:157], v[18:21], v[122:125], 0
	v_mfma_f32_16x16x32_bf16 v[170:173], v[18:21], v[130:133], 0
	v_mfma_f32_16x16x32_bf16 v[18:21], v[18:21], v[138:141], 0
	v_mfma_f32_16x16x32_bf16 v[180:183], v[22:25], v[142:145], v[18:21]
	v_mfma_f32_16x16x32_bf16 v[18:21], v[26:29], v[138:141], 0
	v_mfma_f32_16x16x32_bf16 v[150:153], v[26:29], v[70:73], 0
	v_mfma_f32_16x16x32_bf16 v[158:161], v[26:29], v[122:125], 0
	v_mfma_f32_16x16x32_bf16 v[174:177], v[26:29], v[130:133], 0
	v_mfma_f32_16x16x32_bf16 v[26:29], v[30:33], v[142:145], v[18:21]
	v_mfma_f32_16x16x32_bf16 v[146:149], v[22:25], v[118:121], v[146:149]
	v_mfma_f32_16x16x32_bf16 v[150:153], v[30:33], v[118:121], v[150:153]
	v_mfma_f32_16x16x32_bf16 v[154:157], v[22:25], v[126:129], v[154:157]
	v_mfma_f32_16x16x32_bf16 v[158:161], v[30:33], v[126:129], v[158:161]
	v_mfma_f32_16x16x32_bf16 v[170:173], v[22:25], v[134:137], v[170:173]
	v_mfma_f32_16x16x32_bf16 v[174:177], v[30:33], v[134:137], v[174:177]
	v_mfma_f32_16x16x32_bf16 v[18:21], v[34:37], v[70:73], 0
	v_mfma_f32_16x16x32_bf16 v[30:33], v[38:41], v[118:121], v[18:21]
	v_mfma_f32_16x16x32_bf16 v[18:21], v[42:45], v[70:73], 0
	v_mfma_f32_16x16x32_bf16 v[70:73], v[46:49], v[118:121], v[18:21]
	v_mfma_f32_16x16x32_bf16 v[18:21], v[34:37], v[122:125], 0
	v_mfma_f32_16x16x32_bf16 v[118:121], v[38:41], v[126:129], v[18:21]
	v_mfma_f32_16x16x32_bf16 v[18:21], v[42:45], v[122:125], 0
	v_mfma_f32_16x16x32_bf16 v[122:125], v[46:49], v[126:129], v[18:21]
	v_mfma_f32_16x16x32_bf16 v[18:21], v[34:37], v[130:133], 0
	v_mfma_f32_16x16x32_bf16 v[126:129], v[38:41], v[134:137], v[18:21]
	v_mfma_f32_16x16x32_bf16 v[18:21], v[42:45], v[130:133], 0
	v_mfma_f32_16x16x32_bf16 v[130:133], v[46:49], v[134:137], v[18:21]
	v_mfma_f32_16x16x32_bf16 v[18:21], v[34:37], v[138:141], 0
	v_mfma_f32_16x16x32_bf16 v[34:37], v[38:41], v[142:145], v[18:21]
	v_mfma_f32_16x16x32_bf16 v[18:21], v[42:45], v[138:141], 0
	v_mfma_f32_16x16x32_bf16 v[38:41], v[46:49], v[142:145], v[18:21]
	s_barrier
; #define PG8_STAGE(bufoff, gbase, voff) do { _Pragma("unroll") for (int _i = 0; _i < 2; ++_i) \
;         __builtin_amdgcn_global_load_lds((const unsigned*)((const char*)(gbase) + (voff)[_i]), (PG8_LAS unsigned*)(lds + (bufoff) + ldsw + _i * 8192), 16, 0, 0); } while (0)
; #define PG8_LDA(dst, b, h) do { _Pragma("unroll") for (int m = 0; m < 4; ++m) _Pragma("unroll") for (int k = 0; k < 2; ++k) dst[m][k] = *(const PG8_LAS bf16x8*)(lds + PG8_SA(b, h) + aoff + m * 2048 + k * 1024); } while (0)
; #define PG8_LDB(dst, b, h) do { _Pragma("unroll") for (int n = 0; n < 2; ++n) _Pragma("unroll") for (int k = 0; k < 2; ++k) dst[n][k] = *(const PG8_LAS bf16x8*)(lds + PG8_SB(b, h) + boff + n * 2048 + k * 1024); } while (0)
; #define PG8_MMA(ai, bj, At, Bt) do { __builtin_amdgcn_s_setprio(1); _Pragma("unroll") for (int m = 0; m < 4; ++m) _Pragma("unroll") for (int n = 0; n < 2; ++n) _Pragma("unroll") for (int k = 0; k < 2; ++k) \
;         acc[ai][bj][m][n] = __builtin_amdgcn_mfma_f32_16x16x32_bf16(Bt[n][k], At[m][k], acc[ai][bj][m][n], 0, 0, 0); __builtin_amdgcn_s_setprio(0); } while (0)
; #define PG8_WAIT_V(n) asm volatile("s_waitcnt vmcnt(" #n ")" ::: "memory")
; #define PG8_WAIT_L(n) asm volatile("s_waitcnt lgkmcnt(" #n ")" ::: "memory")
; #define PG8_BAR __builtin_amdgcn_s_barrier()
; #define PG8_SCHED __builtin_amdgcn_sched_barrier(0)
; template <class Epi, class Sched, bool ALIGN_EPI = false, bool SP2 = false>
; __device__ __forceinline__ void gemm_phase(PG8_LAS unsigned char* lds, const Gemm g, const Sched& S, const Epi& E, const int tid) {
;     ...
;             PG8_LDB(B0, 1, 0); PG8_LDB(B1, 1, 1); PG8_SCHED; PG8_LDA(At, 1, 0); PG8_STAGE(PG8_SA(0, 1), a2 + hstep, voffA);
;             PG8_WAIT_V(8); PG8_WAIT_L(0); PG8_BAR; PG8_MMA(0, 0, At, B0); PG8_MMA(0, 1, At, B1); PG8_BAR; PG8_SCHED;
;             PG8_LDA(At, 1, 1); PG8_STAGE(PG8_SB(1, 0), b3, voffB); PG8_STAGE(PG8_SB(1, 1), b3 + hstep, voffB); PG8_STAGE(PG8_SA(1, 0), a3, voffA);
	v_or_b32_e32 v17, 0x18000, v179
	s_nop 3
	v_add_u32_e32 v19, 0x18800, v179
	v_or_b32_e32 v21, 0x1c000, v179
	v_add_u32_e32 v23, 0x1c800, v179
	v_add_u32_e32 v18, 0x18400, v179
	ds_read_b128 v[42:45], v17
	ds_read_b128 v[46:49], v18
	v_add_u32_e32 v20, 0x18c00, v179
	ds_read_b128 v[134:137], v19
	ds_read_b128 v[138:141], v20
	v_add_u32_e32 v22, 0x1c400, v179
	ds_read_b128 v[142:145], v21
	ds_read_b128 v[184:187], v22
	v_add_u32_e32 v24, 0x1cc00, v179
	ds_read_b128 v[188:191], v23
	ds_read_b128 v[192:195], v24
	s_add_u32 s20, s30, 0x18100
	s_addc_u32 s21, s31, 0
	s_mov_b32 m0, s84
	v_lshl_add_u64 v[208:209], s[20:21], 0, v[168:169]
	ds_read_b128 v[196:199], v178 offset:32768
	ds_read_b128 v[200:203], v178 offset:33792
	ds_read_b128 v[204:207], v178 offset:34816
	ds_read_b128 v[214:217], v178 offset:35840
	ds_read_b128 v[218:221], v178 offset:36864
	ds_read_b128 v[222:225], v178 offset:37888
	ds_read_b128 v[226:229], v178 offset:38912
	ds_read_b128 v[230:233], v178 offset:39936
	global_load_lds_dwordx4 v[208:209], off
	v_lshl_add_u64 v[208:209], s[20:21], 0, v[164:165]
	s_mov_b32 m0, s85
	s_nop 0
	global_load_lds_dwordx4 v[208:209], off
	s_waitcnt vmcnt(8)
	s_waitcnt lgkmcnt(0)
	s_barrier
	s_waitcnt lgkmcnt(0)
	v_mfma_f32_16x16x32_bf16 v[74:77], v[42:45], v[196:199], v[74:77]
	v_mfma_f32_16x16x32_bf16 v[74:77], v[46:49], v[200:203], v[74:77]
	v_mfma_f32_16x16x32_bf16 v[78:81], v[134:137], v[196:199], v[78:81]
	v_mfma_f32_16x16x32_bf16 v[78:81], v[138:141], v[200:203], v[78:81]
	v_mfma_f32_16x16x32_bf16 v[82:85], v[42:45], v[204:207], v[82:85]
	v_mfma_f32_16x16x32_bf16 v[82:85], v[46:49], v[214:217], v[82:85]
	v_mfma_f32_16x16x32_bf16 v[86:89], v[134:137], v[204:207], v[86:89]
	v_mfma_f32_16x16x32_bf16 v[86:89], v[138:141], v[214:217], v[86:89]
	v_mfma_f32_16x16x32_bf16 v[90:93], v[42:45], v[218:221], v[90:93]
	v_mfma_f32_16x16x32_bf16 v[90:93], v[46:49], v[222:225], v[90:93]
	v_mfma_f32_16x16x32_bf16 v[94:97], v[134:137], v[218:221], v[94:97]
	v_mfma_f32_16x16x32_bf16 v[94:97], v[138:141], v[222:225], v[94:97]
	v_mfma_f32_16x16x32_bf16 v[98:101], v[42:45], v[226:229], v[98:101]
	v_mfma_f32_16x16x32_bf16 v[98:101], v[46:49], v[230:233], v[98:101]
	v_mfma_f32_16x16x32_bf16 v[102:105], v[134:137], v[226:229], v[102:105]
	v_mfma_f32_16x16x32_bf16 v[102:105], v[138:141], v[230:233], v[102:105]
	v_mfma_f32_16x16x32_bf16 v[106:109], v[142:145], v[196:199], v[106:109]
	v_mfma_f32_16x16x32_bf16 v[106:109], v[184:187], v[200:203], v[106:109]
	v_mfma_f32_16x16x32_bf16 v[110:113], v[188:191], v[196:199], v[110:113]
	v_mfma_f32_16x16x32_bf16 v[110:113], v[192:195], v[200:203], v[110:113]
	v_mfma_f32_16x16x32_bf16 v[114:117], v[142:145], v[204:207], v[114:117]
	v_mfma_f32_16x16x32_bf16 v[114:117], v[184:187], v[214:217], v[114:117]
	v_mfma_f32_16x16x32_bf16 v[50:53], v[188:191], v[204:207], v[50:53]
	v_mfma_f32_16x16x32_bf16 v[50:53], v[192:195], v[214:217], v[50:53]
	v_mfma_f32_16x16x32_bf16 v[54:57], v[142:145], v[218:221], v[54:57]
	v_mfma_f32_16x16x32_bf16 v[54:57], v[184:187], v[222:225], v[54:57]
	v_mfma_f32_16x16x32_bf16 v[58:61], v[188:191], v[218:221], v[58:61]
	v_mfma_f32_16x16x32_bf16 v[58:61], v[192:195], v[222:225], v[58:61]
	v_mfma_f32_16x16x32_bf16 v[62:65], v[142:145], v[226:229], v[62:65]
	v_mfma_f32_16x16x32_bf16 v[62:65], v[184:187], v[230:233], v[62:65]
	v_mfma_f32_16x16x32_bf16 v[66:69], v[188:191], v[226:229], v[66:69]
	v_mfma_f32_16x16x32_bf16 v[66:69], v[192:195], v[230:233], v[66:69]
	s_barrier
	s_mov_b64 s[26:27], 0x180
	s_mov_b32 m0, s88
	v_lshl_add_u64 v[208:209], v[2:3], 0, s[26:27]
	s_add_u32 s20, s46, 0x18180
	ds_read_b128 v[196:199], v178 offset:49152
	ds_read_b128 v[200:203], v178 offset:50176
	ds_read_b128 v[204:207], v178 offset:51200
	ds_read_b128 v[214:217], v178 offset:52224
	ds_read_b128 v[218:221], v178 offset:53248
	ds_read_b128 v[222:225], v178 offset:54272
	ds_read_b128 v[226:229], v178 offset:55296
	ds_read_b128 v[230:233], v178 offset:56320
	global_load_lds_dwordx4 v[208:209], off
	v_lshl_add_u64 v[208:209], v[4:5], 0, s[26:27]
	s_mov_b32 m0, s89
	s_addc_u32 s21, s47, 0
	global_load_lds_dwordx4 v[208:209], off
	v_lshl_add_u64 v[208:209], s[20:21], 0, v[166:167]
	s_mov_b32 m0, s28
	s_nop 0
	global_load_lds_dwordx4 v[208:209], off
	v_lshl_add_u64 v[208:209], s[20:21], 0, v[162:163]
	s_mov_b32 m0, s29
	s_nop 0
	global_load_lds_dwordx4 v[208:209], off
	v_lshl_add_u64 v[208:209], v[6:7], 0, s[26:27]
	s_mov_b32 m0, s90
	s_nop 0
	global_load_lds_dwordx4 v[208:209], off
	v_lshl_add_u64 v[208:209], v[8:9], 0, s[26:27]
	s_mov_b32 m0, s91
	s_nop 0
	global_load_lds_dwordx4 v[208:209], off
	s_waitcnt vmcnt(8)
	s_waitcnt lgkmcnt(0)
	s_barrier
; #define PG8_STAGE(bufoff, gbase, voff) do { _Pragma("unroll") for (int _i = 0; _i < 2; ++_i) \
;         __builtin_amdgcn_global_load_lds((const unsigned*)((const char*)(gbase) + (voff)[_i]), (PG8_LAS unsigned*)(lds + (bufoff) + ldsw + _i * 8192), 16, 0, 0); } while (0)
; #define PG8_LDA(dst, b, h) do { _Pragma("unroll") for (int m = 0; m < 4; ++m) _Pragma("unroll") for (int k = 0; k < 2; ++k) dst[m][k] = *(const PG8_LAS bf16x8*)(lds + PG8_SA(b, h) + aoff + m * 2048 + k * 1024); } while (0)
; #define PG8_LDB(dst, b, h) do { _Pragma("unroll") for (int n = 0; n < 2; ++n) _Pragma("unroll") for (int k = 0; k < 2; ++k) dst[n][k] = *(const PG8_LAS bf16x8*)(lds + PG8_SB(b, h) + boff + n * 2048 + k * 1024); } while (0)
; #define PG8_MMA(ai, bj, At, Bt) do { __builtin_amdgcn_s_setprio(1); _Pragma("unroll") for (int m = 0; m < 4; ++m) _Pragma("unroll") for (int n = 0; n < 2; ++n) _Pragma("unroll") for (int k = 0; k < 2; ++k) \
;         acc[ai][bj][m][n] = __builtin_amdgcn_mfma_f32_16x16x32_bf16(Bt[n][k], At[m][k], acc[ai][bj][m][n], 0, 0, 0); __builtin_amdgcn_s_setprio(0); } while (0)
; #define PG8_BAR __builtin_amdgcn_s_barrier()
; template <class Epi, class Sched, bool ALIGN_EPI = false, bool SP2 = false>
; __device__ __forceinline__ void gemm_phase(PG8_LAS unsigned char* lds, const Gemm g, const Sched& S, const Epi& E, const int tid) {
;     ...
;             PG8_LDB(B0, 0, 0); PG8_LDB(B1, 0, 1); PG8_SCHED; PG8_LDA(At, 0, 0); PG8_STAGE(PG8_SA(1, 1), a1 + hstep, voffA);
;             PG8_WAIT_V(8); PG8_WAIT_L(0); PG8_BAR; PG8_MMA(0, 0, At, B0); PG8_MMA(0, 1, At, B1); PG8_BAR; PG8_SCHED;
;             PG8_LDA(At, 0, 1); PG8_STAGE(PG8_SB(0, 0), b2, voffB); PG8_STAGE(PG8_SB(0, 1), b2 + hstep, voffB); PG8_STAGE(PG8_SA(0, 0), a2, voffA);
;             PG8_WAIT_V(8); PG8_WAIT_L(0); PG8_BAR; PG8_MMA(1, 0, At, B0); PG8_MMA(1, 1, At, B1); PG8_BAR; PG8_SCHED;
;             PG8_LDB(B0, 1, 0); PG8_LDB(B1, 1, 1); PG8_SCHED; PG8_LDA(At, 1, 0); PG8_STAGE(PG8_SA(0, 1), a2 + hstep, voffA);
;             PG8_WAIT_V(8); PG8_WAIT_L(0); PG8_BAR; PG8_MMA(0, 0, At, B0); PG8_MMA(0, 1, At, B1); PG8_BAR; PG8_SCHED;
;             PG8_LDA(At, 1, 1); PG8_STAGE(PG8_SB(1, 0), b3, voffB); PG8_STAGE(PG8_SB(1, 1), b3 + hstep, voffB); PG8_STAGE(PG8_SA(1, 0), a3, voffA);
;             PG8_WAIT_V(8); PG8_WAIT_L(0); PG8_BAR; PG8_MMA(1, 0, At, B0); PG8_MMA(1, 1, At, B1); PG8_BAR; PG8_SCHED;
	s_waitcnt lgkmcnt(0)
	v_mfma_f32_16x16x32_bf16 v[146:149], v[42:45], v[196:199], v[146:149]
	v_mfma_f32_16x16x32_bf16 v[154:157], v[42:45], v[204:207], v[154:157]
	v_mfma_f32_16x16x32_bf16 v[170:173], v[42:45], v[218:221], v[170:173]
	v_mfma_f32_16x16x32_bf16 v[42:45], v[42:45], v[226:229], v[180:183]
	v_mfma_f32_16x16x32_bf16 v[26:29], v[134:137], v[226:229], v[26:29]
	v_mfma_f32_16x16x32_bf16 v[150:153], v[134:137], v[196:199], v[150:153]
	v_mfma_f32_16x16x32_bf16 v[158:161], v[134:137], v[204:207], v[158:161]
	v_mfma_f32_16x16x32_bf16 v[174:177], v[134:137], v[218:221], v[174:177]
	v_mfma_f32_16x16x32_bf16 v[42:45], v[46:49], v[230:233], v[42:45]
	v_mfma_f32_16x16x32_bf16 v[26:29], v[138:141], v[230:233], v[26:29]
	v_mfma_f32_16x16x32_bf16 v[146:149], v[46:49], v[200:203], v[146:149]
	v_mfma_f32_16x16x32_bf16 v[150:153], v[138:141], v[200:203], v[150:153]
	v_mfma_f32_16x16x32_bf16 v[154:157], v[46:49], v[214:217], v[154:157]
	v_mfma_f32_16x16x32_bf16 v[158:161], v[138:141], v[214:217], v[158:161]
	v_mfma_f32_16x16x32_bf16 v[170:173], v[46:49], v[222:225], v[170:173]
	v_mfma_f32_16x16x32_bf16 v[174:177], v[138:141], v[222:225], v[174:177]
	v_mfma_f32_16x16x32_bf16 v[30:33], v[142:145], v[196:199], v[30:33]
	v_mfma_f32_16x16x32_bf16 v[46:49], v[188:191], v[196:199], v[70:73]
	v_mfma_f32_16x16x32_bf16 v[70:73], v[142:145], v[204:207], v[118:121]
	v_mfma_f32_16x16x32_bf16 v[118:121], v[188:191], v[204:207], v[122:125]
	v_mfma_f32_16x16x32_bf16 v[122:125], v[142:145], v[218:221], v[126:129]
	v_mfma_f32_16x16x32_bf16 v[126:129], v[188:191], v[218:221], v[130:133]
	v_mfma_f32_16x16x32_bf16 v[34:37], v[142:145], v[226:229], v[34:37]
	v_mfma_f32_16x16x32_bf16 v[38:41], v[188:191], v[226:229], v[38:41]
	v_mfma_f32_16x16x32_bf16 v[30:33], v[184:187], v[200:203], v[30:33]
	v_mfma_f32_16x16x32_bf16 v[46:49], v[192:195], v[200:203], v[46:49]
	v_mfma_f32_16x16x32_bf16 v[70:73], v[184:187], v[214:217], v[70:73]
	v_mfma_f32_16x16x32_bf16 v[118:121], v[192:195], v[214:217], v[118:121]
	v_mfma_f32_16x16x32_bf16 v[122:125], v[184:187], v[222:225], v[122:125]
	v_mfma_f32_16x16x32_bf16 v[126:129], v[192:195], v[222:225], v[126:129]
	v_mfma_f32_16x16x32_bf16 v[34:37], v[184:187], v[230:233], v[34:37]
	v_mfma_f32_16x16x32_bf16 v[38:41], v[192:195], v[230:233], v[38:41]
	s_barrier
	ds_read_b128 v[130:133], v0
	ds_read_b128 v[134:137], v10
	ds_read_b128 v[138:141], v11
	ds_read_b128 v[142:145], v12
	ds_read_b128 v[180:183], v13
	ds_read_b128 v[184:187], v14
	ds_read_b128 v[188:191], v15
	ds_read_b128 v[192:195], v16
	s_add_u32 s20, s30, 0x18180
	s_addc_u32 s21, s31, 0
	s_mov_b32 m0, s5
	v_lshl_add_u64 v[208:209], s[20:21], 0, v[168:169]
	ds_read_b128 v[196:199], v178
	ds_read_b128 v[200:203], v178 offset:1024
	ds_read_b128 v[204:207], v178 offset:2048
	ds_read_b128 v[214:217], v178 offset:3072
	ds_read_b128 v[218:221], v178 offset:4096
	ds_read_b128 v[222:225], v178 offset:5120
	ds_read_b128 v[226:229], v178 offset:6144
	ds_read_b128 v[230:233], v178 offset:7168
	global_load_lds_dwordx4 v[208:209], off
	v_lshl_add_u64 v[208:209], s[20:21], 0, v[164:165]
	s_mov_b32 m0, s4
	s_nop 0
	global_load_lds_dwordx4 v[208:209], off
	s_waitcnt vmcnt(8)
	s_waitcnt lgkmcnt(0)
	s_barrier
	s_waitcnt lgkmcnt(0)
	v_mfma_f32_16x16x32_bf16 v[74:77], v[130:133], v[196:199], v[74:77]
	v_mfma_f32_16x16x32_bf16 v[74:77], v[134:137], v[200:203], v[74:77]
	v_mfma_f32_16x16x32_bf16 v[78:81], v[138:141], v[196:199], v[78:81]
	v_mfma_f32_16x16x32_bf16 v[78:81], v[142:145], v[200:203], v[78:81]
	v_mfma_f32_16x16x32_bf16 v[82:85], v[130:133], v[204:207], v[82:85]
	v_mfma_f32_16x16x32_bf16 v[82:85], v[134:137], v[214:217], v[82:85]
	v_mfma_f32_16x16x32_bf16 v[86:89], v[138:141], v[204:207], v[86:89]
	v_mfma_f32_16x16x32_bf16 v[86:89], v[142:145], v[214:217], v[86:89]
	v_mfma_f32_16x16x32_bf16 v[90:93], v[130:133], v[218:221], v[90:93]
	v_mfma_f32_16x16x32_bf16 v[90:93], v[134:137], v[222:225], v[90:93]
	v_mfma_f32_16x16x32_bf16 v[94:97], v[138:141], v[218:221], v[94:97]
	v_mfma_f32_16x16x32_bf16 v[94:97], v[142:145], v[222:225], v[94:97]
	v_mfma_f32_16x16x32_bf16 v[98:101], v[130:133], v[226:229], v[98:101]
	v_mfma_f32_16x16x32_bf16 v[98:101], v[134:137], v[230:233], v[98:101]
	v_mfma_f32_16x16x32_bf16 v[102:105], v[138:141], v[226:229], v[102:105]
	v_mfma_f32_16x16x32_bf16 v[102:105], v[142:145], v[230:233], v[102:105]
	v_mfma_f32_16x16x32_bf16 v[106:109], v[180:183], v[196:199], v[106:109]
	v_mfma_f32_16x16x32_bf16 v[106:109], v[184:187], v[200:203], v[106:109]
	v_mfma_f32_16x16x32_bf16 v[110:113], v[188:191], v[196:199], v[110:113]
	v_mfma_f32_16x16x32_bf16 v[110:113], v[192:195], v[200:203], v[110:113]
	v_mfma_f32_16x16x32_bf16 v[114:117], v[180:183], v[204:207], v[114:117]
	v_mfma_f32_16x16x32_bf16 v[114:117], v[184:187], v[214:217], v[114:117]
	v_mfma_f32_16x16x32_bf16 v[50:53], v[188:191], v[204:207], v[50:53]
	v_mfma_f32_16x16x32_bf16 v[50:53], v[192:195], v[214:217], v[50:53]
	v_mfma_f32_16x16x32_bf16 v[54:57], v[180:183], v[218:221], v[54:57]
	v_mfma_f32_16x16x32_bf16 v[54:57], v[184:187], v[222:225], v[54:57]
	v_mfma_f32_16x16x32_bf16 v[58:61], v[188:191], v[218:221], v[58:61]
	v_mfma_f32_16x16x32_bf16 v[58:61], v[192:195], v[222:225], v[58:61]
	v_mfma_f32_16x16x32_bf16 v[62:65], v[180:183], v[226:229], v[62:65]
	v_mfma_f32_16x16x32_bf16 v[62:65], v[184:187], v[230:233], v[62:65]
	v_mfma_f32_16x16x32_bf16 v[66:69], v[188:191], v[226:229], v[66:69]
	v_mfma_f32_16x16x32_bf16 v[66:69], v[192:195], v[230:233], v[66:69]
	s_barrier
; #define PG8_STAGE(bufoff, gbase, voff) do { _Pragma("unroll") for (int _i = 0; _i < 2; ++_i) \
;         __builtin_amdgcn_global_load_lds((const unsigned*)((const char*)(gbase) + (voff)[_i]), (PG8_LAS unsigned*)(lds + (bufoff) + ldsw + _i * 8192), 16, 0, 0); } while (0)
; #define PG8_LDA(dst, b, h) do { _Pragma("unroll") for (int m = 0; m < 4; ++m) _Pragma("unroll") for (int k = 0; k < 2; ++k) dst[m][k] = *(const PG8_LAS bf16x8*)(lds + PG8_SA(b, h) + aoff + m * 2048 + k * 1024); } while (0)
; #define PG8_LDB(dst, b, h) do { _Pragma("unroll") for (int n = 0; n < 2; ++n) _Pragma("unroll") for (int k = 0; k < 2; ++k) dst[n][k] = *(const PG8_LAS bf16x8*)(lds + PG8_SB(b, h) + boff + n * 2048 + k * 1024); } while (0)
; #define PG8_MMA(ai, bj, At, Bt) do { __builtin_amdgcn_s_setprio(1); _Pragma("unroll") for (int m = 0; m < 4; ++m) _Pragma("unroll") for (int n = 0; n < 2; ++n) _Pragma("unroll") for (int k = 0; k < 2; ++k) \
;         acc[ai][bj][m][n] = __builtin_amdgcn_mfma_f32_16x16x32_bf16(Bt[n][k], At[m][k], acc[ai][bj][m][n], 0, 0, 0); __builtin_amdgcn_s_setprio(0); } while (0)
; #define PG8_WAIT_V(n) asm volatile("s_waitcnt vmcnt(" #n ")" ::: "memory")
; #define PG8_WAIT_L(n) asm volatile("s_waitcnt lgkmcnt(" #n ")" ::: "memory")
; #define PG8_BAR __builtin_amdgcn_s_barrier()
; #define PG8_SCHED __builtin_amdgcn_sched_barrier(0)
; template <class Epi, class Sched, bool ALIGN_EPI = false, bool SP2 = false>
; __device__ __forceinline__ void gemm_phase(PG8_LAS unsigned char* lds, const Gemm g, const Sched& S, const Epi& E, const int tid) {
;     ...
;             PG8_LDA(At, 0, 1); PG8_STAGE(PG8_SB(0, 0), b2, voffB); PG8_STAGE(PG8_SB(0, 1), b2 + hstep, voffB); PG8_STAGE(PG8_SA(0, 0), a2, voffA);
;             PG8_WAIT_V(8); PG8_WAIT_L(0); PG8_BAR; PG8_MMA(1, 0, At, B0); PG8_MMA(1, 1, At, B1); PG8_BAR; PG8_SCHED;
;             PG8_LDB(B0, 1, 0); PG8_LDB(B1, 1, 1); PG8_SCHED; PG8_LDA(At, 1, 0); PG8_STAGE(PG8_SA(0, 1), a2 + hstep, voffA);
;             PG8_WAIT_V(8); PG8_WAIT_L(0); PG8_BAR; PG8_MMA(0, 0, At, B0); PG8_MMA(0, 1, At, B1); PG8_BAR; PG8_SCHED;
	s_mov_b64 s[26:27], 0x200
	s_mov_b32 m0, s8
	v_lshl_add_u64 v[208:209], v[2:3], 0, s[26:27]
	s_add_u32 s20, s46, 0x18200
	ds_read_b128 v[196:199], v178 offset:16384
	ds_read_b128 v[200:203], v178 offset:17408
	ds_read_b128 v[204:207], v178 offset:18432
	ds_read_b128 v[214:217], v178 offset:19456
	ds_read_b128 v[218:221], v178 offset:20480
	ds_read_b128 v[222:225], v178 offset:21504
	ds_read_b128 v[226:229], v178 offset:22528
	ds_read_b128 v[230:233], v178 offset:23552
	global_load_lds_dwordx4 v[208:209], off
	v_lshl_add_u64 v[208:209], v[4:5], 0, s[26:27]
	s_mov_b32 m0, s9
	s_addc_u32 s21, s47, 0
	global_load_lds_dwordx4 v[208:209], off
	v_lshl_add_u64 v[208:209], s[20:21], 0, v[166:167]
	s_mov_b32 m0, s14
	s_nop 0
	global_load_lds_dwordx4 v[208:209], off
	v_lshl_add_u64 v[208:209], s[20:21], 0, v[162:163]
	s_mov_b32 m0, s34
	s_nop 0
	global_load_lds_dwordx4 v[208:209], off
	v_lshl_add_u64 v[208:209], v[6:7], 0, s[26:27]
	s_mov_b32 m0, s1
	s_nop 0
	global_load_lds_dwordx4 v[208:209], off
	v_lshl_add_u64 v[208:209], v[8:9], 0, s[26:27]
	s_mov_b32 m0, s35
	s_nop 0
	global_load_lds_dwordx4 v[208:209], off
	s_waitcnt vmcnt(8)
	s_waitcnt lgkmcnt(0)
	s_barrier
	s_waitcnt lgkmcnt(0)
	v_mfma_f32_16x16x32_bf16 v[42:45], v[130:133], v[226:229], v[42:45]
	v_mfma_f32_16x16x32_bf16 v[42:45], v[134:137], v[230:233], v[42:45]
	v_mfma_f32_16x16x32_bf16 v[26:29], v[138:141], v[226:229], v[26:29]
	v_mfma_f32_16x16x32_bf16 v[26:29], v[142:145], v[230:233], v[26:29]
	v_mfma_f32_16x16x32_bf16 v[146:149], v[130:133], v[196:199], v[146:149]
	v_mfma_f32_16x16x32_bf16 v[146:149], v[134:137], v[200:203], v[146:149]
	v_mfma_f32_16x16x32_bf16 v[150:153], v[138:141], v[196:199], v[150:153]
	v_mfma_f32_16x16x32_bf16 v[150:153], v[142:145], v[200:203], v[150:153]
	v_mfma_f32_16x16x32_bf16 v[154:157], v[130:133], v[204:207], v[154:157]
	v_mfma_f32_16x16x32_bf16 v[154:157], v[134:137], v[214:217], v[154:157]
	v_mfma_f32_16x16x32_bf16 v[158:161], v[138:141], v[204:207], v[158:161]
	v_mfma_f32_16x16x32_bf16 v[158:161], v[142:145], v[214:217], v[158:161]
	v_mfma_f32_16x16x32_bf16 v[170:173], v[130:133], v[218:221], v[170:173]
	v_mfma_f32_16x16x32_bf16 v[170:173], v[134:137], v[222:225], v[170:173]
	v_mfma_f32_16x16x32_bf16 v[174:177], v[138:141], v[218:221], v[174:177]
	v_mfma_f32_16x16x32_bf16 v[174:177], v[142:145], v[222:225], v[174:177]
	v_mfma_f32_16x16x32_bf16 v[30:33], v[180:183], v[196:199], v[30:33]
	v_mfma_f32_16x16x32_bf16 v[30:33], v[184:187], v[200:203], v[30:33]
	v_mfma_f32_16x16x32_bf16 v[46:49], v[188:191], v[196:199], v[46:49]
	v_mfma_f32_16x16x32_bf16 v[46:49], v[192:195], v[200:203], v[46:49]
	v_mfma_f32_16x16x32_bf16 v[70:73], v[180:183], v[204:207], v[70:73]
	v_mfma_f32_16x16x32_bf16 v[70:73], v[184:187], v[214:217], v[70:73]
	v_mfma_f32_16x16x32_bf16 v[118:121], v[188:191], v[204:207], v[118:121]
	v_mfma_f32_16x16x32_bf16 v[118:121], v[192:195], v[214:217], v[118:121]
	v_mfma_f32_16x16x32_bf16 v[122:125], v[180:183], v[218:221], v[122:125]
	v_mfma_f32_16x16x32_bf16 v[122:125], v[184:187], v[222:225], v[122:125]
	v_mfma_f32_16x16x32_bf16 v[126:129], v[188:191], v[218:221], v[126:129]
	v_mfma_f32_16x16x32_bf16 v[126:129], v[192:195], v[222:225], v[126:129]
	v_mfma_f32_16x16x32_bf16 v[34:37], v[180:183], v[226:229], v[34:37]
	v_mfma_f32_16x16x32_bf16 v[34:37], v[184:187], v[230:233], v[34:37]
	v_mfma_f32_16x16x32_bf16 v[38:41], v[188:191], v[226:229], v[38:41]
	v_mfma_f32_16x16x32_bf16 v[38:41], v[192:195], v[230:233], v[38:41]
	s_barrier
	ds_read_b128 v[130:133], v17
	ds_read_b128 v[134:137], v18
	ds_read_b128 v[138:141], v19
	ds_read_b128 v[142:145], v20
	ds_read_b128 v[180:183], v21
	ds_read_b128 v[184:187], v22
	ds_read_b128 v[188:191], v23
	ds_read_b128 v[192:195], v24
	s_add_u32 s20, s30, 0x18200
	s_addc_u32 s21, s31, 0
	s_mov_b32 m0, s84
	v_lshl_add_u64 v[208:209], s[20:21], 0, v[168:169]
	ds_read_b128 v[196:199], v178 offset:32768
	ds_read_b128 v[200:203], v178 offset:33792
	ds_read_b128 v[204:207], v178 offset:34816
	ds_read_b128 v[214:217], v178 offset:35840
	ds_read_b128 v[218:221], v178 offset:36864
	ds_read_b128 v[222:225], v178 offset:37888
	ds_read_b128 v[226:229], v178 offset:38912
	ds_read_b128 v[230:233], v178 offset:39936
	global_load_lds_dwordx4 v[208:209], off
	v_lshl_add_u64 v[208:209], s[20:21], 0, v[164:165]
	s_mov_b32 m0, s85
	s_nop 0
	global_load_lds_dwordx4 v[208:209], off
	s_waitcnt vmcnt(8)
	s_waitcnt lgkmcnt(0)
	s_barrier
	s_waitcnt lgkmcnt(0)
	v_mfma_f32_16x16x32_bf16 v[74:77], v[130:133], v[196:199], v[74:77]
	v_mfma_f32_16x16x32_bf16 v[74:77], v[134:137], v[200:203], v[74:77]
	v_mfma_f32_16x16x32_bf16 v[78:81], v[138:141], v[196:199], v[78:81]
	v_mfma_f32_16x16x32_bf16 v[78:81], v[142:145], v[200:203], v[78:81]
	v_mfma_f32_16x16x32_bf16 v[82:85], v[130:133], v[204:207], v[82:85]
	v_mfma_f32_16x16x32_bf16 v[82:85], v[134:137], v[214:217], v[82:85]
	v_mfma_f32_16x16x32_bf16 v[86:89], v[138:141], v[204:207], v[86:89]
	v_mfma_f32_16x16x32_bf16 v[86:89], v[142:145], v[214:217], v[86:89]
	v_mfma_f32_16x16x32_bf16 v[90:93], v[130:133], v[218:221], v[90:93]
	v_mfma_f32_16x16x32_bf16 v[90:93], v[134:137], v[222:225], v[90:93]
	v_mfma_f32_16x16x32_bf16 v[94:97], v[138:141], v[218:221], v[94:97]
	v_mfma_f32_16x16x32_bf16 v[94:97], v[142:145], v[222:225], v[94:97]
	v_mfma_f32_16x16x32_bf16 v[98:101], v[130:133], v[226:229], v[98:101]
	v_mfma_f32_16x16x32_bf16 v[98:101], v[134:137], v[230:233], v[98:101]
	v_mfma_f32_16x16x32_bf16 v[102:105], v[138:141], v[226:229], v[102:105]
	v_mfma_f32_16x16x32_bf16 v[102:105], v[142:145], v[230:233], v[102:105]
	v_mfma_f32_16x16x32_bf16 v[106:109], v[180:183], v[196:199], v[106:109]
	v_mfma_f32_16x16x32_bf16 v[106:109], v[184:187], v[200:203], v[106:109]
	v_mfma_f32_16x16x32_bf16 v[110:113], v[188:191], v[196:199], v[110:113]
	v_mfma_f32_16x16x32_bf16 v[110:113], v[192:195], v[200:203], v[110:113]
	v_mfma_f32_16x16x32_bf16 v[114:117], v[180:183], v[204:207], v[114:117]
	v_mfma_f32_16x16x32_bf16 v[114:117], v[184:187], v[214:217], v[114:117]
	v_mfma_f32_16x16x32_bf16 v[50:53], v[188:191], v[204:207], v[50:53]
	v_mfma_f32_16x16x32_bf16 v[50:53], v[192:195], v[214:217], v[50:53]
	v_mfma_f32_16x16x32_bf16 v[54:57], v[180:183], v[218:221], v[54:57]
	v_mfma_f32_16x16x32_bf16 v[54:57], v[184:187], v[222:225], v[54:57]
	v_mfma_f32_16x16x32_bf16 v[58:61], v[188:191], v[218:221], v[58:61]
	v_mfma_f32_16x16x32_bf16 v[58:61], v[192:195], v[222:225], v[58:61]
	v_mfma_f32_16x16x32_bf16 v[62:65], v[180:183], v[226:229], v[62:65]
	v_mfma_f32_16x16x32_bf16 v[62:65], v[184:187], v[230:233], v[62:65]
	v_mfma_f32_16x16x32_bf16 v[66:69], v[188:191], v[226:229], v[66:69]
	v_mfma_f32_16x16x32_bf16 v[66:69], v[192:195], v[230:233], v[66:69]
	s_barrier
; #define PG8_STAGE(bufoff, gbase, voff) do { _Pragma("unroll") for (int _i = 0; _i < 2; ++_i) \
;         __builtin_amdgcn_global_load_lds((const unsigned*)((const char*)(gbase) + (voff)[_i]), (PG8_LAS unsigned*)(lds + (bufoff) + ldsw + _i * 8192), 16, 0, 0); } while (0)
; #define PG8_LDA(dst, b, h) do { _Pragma("unroll") for (int m = 0; m < 4; ++m) _Pragma("unroll") for (int k = 0; k < 2; ++k) dst[m][k] = *(const PG8_LAS bf16x8*)(lds + PG8_SA(b, h) + aoff + m * 2048 + k * 1024); } while (0)
; #define PG8_LDB(dst, b, h) do { _Pragma("unroll") for (int n = 0; n < 2; ++n) _Pragma("unroll") for (int k = 0; k < 2; ++k) dst[n][k] = *(const PG8_LAS bf16x8*)(lds + PG8_SB(b, h) + boff + n * 2048 + k * 1024); } while (0)
; #define PG8_MMA(ai, bj, At, Bt) do { __builtin_amdgcn_s_setprio(1); _Pragma("unroll") for (int m = 0; m < 4; ++m) _Pragma("unroll") for (int n = 0; n < 2; ++n) _Pragma("unroll") for (int k = 0; k < 2; ++k) \
;         acc[ai][bj][m][n] = __builtin_amdgcn_mfma_f32_16x16x32_bf16(Bt[n][k], At[m][k], acc[ai][bj][m][n], 0, 0, 0); __builtin_amdgcn_s_setprio(0); } while (0)
; #define PG8_BAR __builtin_amdgcn_s_barrier()
; template <class Epi, class Sched, bool ALIGN_EPI = false, bool SP2 = false>
; __device__ __forceinline__ void gemm_phase(PG8_LAS unsigned char* lds, const Gemm g, const Sched& S, const Epi& E, const int tid) {
;     ...
;             PG8_LDB(B0, 0, 0); PG8_LDB(B1, 0, 1); PG8_SCHED; PG8_LDA(At, 0, 0); PG8_STAGE(PG8_SA(1, 1), a1 + hstep, voffA);
;             PG8_WAIT_V(8); PG8_WAIT_L(0); PG8_BAR; PG8_MMA(0, 0, At, B0); PG8_MMA(0, 1, At, B1); PG8_BAR; PG8_SCHED;
;             PG8_LDA(At, 0, 1); PG8_STAGE(PG8_SB(0, 0), b2, voffB); PG8_STAGE(PG8_SB(0, 1), b2 + hstep, voffB); PG8_STAGE(PG8_SA(0, 0), a2, voffA);
;             PG8_WAIT_V(8); PG8_WAIT_L(0); PG8_BAR; PG8_MMA(1, 0, At, B0); PG8_MMA(1, 1, At, B1); PG8_BAR; PG8_SCHED;
;             PG8_LDB(B0, 1, 0); PG8_LDB(B1, 1, 1); PG8_SCHED; PG8_LDA(At, 1, 0); PG8_STAGE(PG8_SA(0, 1), a2 + hstep, voffA);
;             PG8_WAIT_V(8); PG8_WAIT_L(0); PG8_BAR; PG8_MMA(0, 0, At, B0); PG8_MMA(0, 1, At, B1); PG8_BAR; PG8_SCHED;
;             PG8_LDA(At, 1, 1); PG8_STAGE(PG8_SB(1, 0), b3, voffB); PG8_STAGE(PG8_SB(1, 1), b3 + hstep, voffB); PG8_STAGE(PG8_SA(1, 0), a3, voffA);
;             PG8_WAIT_V(8); PG8_WAIT_L(0); PG8_BAR; PG8_MMA(1, 0, At, B0); PG8_MMA(1, 1, At, B1); PG8_BAR; PG8_SCHED;
	s_mov_b64 s[26:27], 0x280
	s_mov_b32 m0, s88
	v_lshl_add_u64 v[2:3], v[2:3], 0, s[26:27]
	s_add_u32 s20, s46, 0x18280
	ds_read_b128 v[196:199], v178 offset:49152
	ds_read_b128 v[200:203], v178 offset:50176
	ds_read_b128 v[204:207], v178 offset:51200
	ds_read_b128 v[214:217], v178 offset:52224
	ds_read_b128 v[218:221], v178 offset:53248
	ds_read_b128 v[222:225], v178 offset:54272
	ds_read_b128 v[226:229], v178 offset:55296
	ds_read_b128 v[230:233], v178 offset:56320
	global_load_lds_dwordx4 v[2:3], off
	v_lshl_add_u64 v[2:3], v[4:5], 0, s[26:27]
	s_mov_b32 m0, s89
	s_addc_u32 s21, s47, 0
	global_load_lds_dwordx4 v[2:3], off
	v_lshl_add_u64 v[2:3], s[20:21], 0, v[166:167]
	s_mov_b32 m0, s28
	s_nop 0
	global_load_lds_dwordx4 v[2:3], off
	v_lshl_add_u64 v[2:3], s[20:21], 0, v[162:163]
	s_mov_b32 m0, s29
	s_nop 0
	global_load_lds_dwordx4 v[2:3], off
	v_lshl_add_u64 v[2:3], v[6:7], 0, s[26:27]
	s_mov_b32 m0, s90
	s_nop 0
	global_load_lds_dwordx4 v[2:3], off
	v_lshl_add_u64 v[2:3], v[8:9], 0, s[26:27]
	s_mov_b32 m0, s91
	s_nop 0
	global_load_lds_dwordx4 v[2:3], off
	s_waitcnt vmcnt(8)
	s_waitcnt lgkmcnt(0)
	s_barrier
	s_waitcnt lgkmcnt(0)
	v_mfma_f32_16x16x32_bf16 v[2:5], v[130:133], v[196:199], v[146:149]
	v_mfma_f32_16x16x32_bf16 v[6:9], v[138:141], v[196:199], v[150:153]
	v_mfma_f32_16x16x32_bf16 v[42:45], v[130:133], v[226:229], v[42:45]
	v_mfma_f32_16x16x32_bf16 v[26:29], v[138:141], v[226:229], v[26:29]
	v_mfma_f32_16x16x32_bf16 v[2:5], v[134:137], v[200:203], v[2:5]
	v_mfma_f32_16x16x32_bf16 v[6:9], v[142:145], v[200:203], v[6:9]
	v_mfma_f32_16x16x32_bf16 v[146:149], v[130:133], v[204:207], v[154:157]
	v_mfma_f32_16x16x32_bf16 v[150:153], v[138:141], v[204:207], v[158:161]
	v_mfma_f32_16x16x32_bf16 v[154:157], v[130:133], v[218:221], v[170:173]
	v_mfma_f32_16x16x32_bf16 v[158:161], v[138:141], v[218:221], v[174:177]
	v_mfma_f32_16x16x32_bf16 v[42:45], v[134:137], v[230:233], v[42:45]
	v_mfma_f32_16x16x32_bf16 v[26:29], v[142:145], v[230:233], v[26:29]
	v_mfma_f32_16x16x32_bf16 v[146:149], v[134:137], v[214:217], v[146:149]
	v_mfma_f32_16x16x32_bf16 v[150:153], v[142:145], v[214:217], v[150:153]
	v_mfma_f32_16x16x32_bf16 v[154:157], v[134:137], v[222:225], v[154:157]
	v_mfma_f32_16x16x32_bf16 v[158:161], v[142:145], v[222:225], v[158:161]
	v_mfma_f32_16x16x32_bf16 v[30:33], v[180:183], v[196:199], v[30:33]
	v_mfma_f32_16x16x32_bf16 v[30:33], v[184:187], v[200:203], v[30:33]
	v_mfma_f32_16x16x32_bf16 v[46:49], v[188:191], v[196:199], v[46:49]
	v_mfma_f32_16x16x32_bf16 v[46:49], v[192:195], v[200:203], v[46:49]
	v_mfma_f32_16x16x32_bf16 v[70:73], v[180:183], v[204:207], v[70:73]
	v_mfma_f32_16x16x32_bf16 v[70:73], v[184:187], v[214:217], v[70:73]
	v_mfma_f32_16x16x32_bf16 v[118:121], v[188:191], v[204:207], v[118:121]
	v_mfma_f32_16x16x32_bf16 v[118:121], v[192:195], v[214:217], v[118:121]
	v_mfma_f32_16x16x32_bf16 v[122:125], v[180:183], v[218:221], v[122:125]
	v_mfma_f32_16x16x32_bf16 v[122:125], v[184:187], v[222:225], v[122:125]
	v_mfma_f32_16x16x32_bf16 v[126:129], v[188:191], v[218:221], v[126:129]
	v_mfma_f32_16x16x32_bf16 v[126:129], v[192:195], v[222:225], v[126:129]
	v_mfma_f32_16x16x32_bf16 v[34:37], v[180:183], v[226:229], v[34:37]
	v_mfma_f32_16x16x32_bf16 v[34:37], v[184:187], v[230:233], v[34:37]
	v_mfma_f32_16x16x32_bf16 v[38:41], v[188:191], v[226:229], v[38:41]
	v_mfma_f32_16x16x32_bf16 v[38:41], v[192:195], v[230:233], v[38:41]
	s_barrier
	ds_read_b128 v[130:133], v0
	ds_read_b128 v[134:137], v10
	ds_read_b128 v[138:141], v11
	ds_read_b128 v[142:145], v12
	ds_read_b128 v[10:13], v13
	ds_read_b128 v[170:173], v14
	ds_read_b128 v[174:177], v15
	ds_read_b128 v[180:183], v16
	s_add_u32 s20, s30, 0x18280
	s_addc_u32 s21, s31, 0
	s_mov_b32 m0, s5
	v_lshl_add_u64 v[14:15], s[20:21], 0, v[168:169]
	ds_read_b128 v[184:187], v178
	ds_read_b128 v[188:191], v178 offset:1024
	ds_read_b128 v[192:195], v178 offset:2048
	ds_read_b128 v[196:199], v178 offset:3072
	ds_read_b128 v[200:203], v178 offset:4096
	ds_read_b128 v[204:207], v178 offset:5120
	ds_read_b128 v[214:217], v178 offset:6144
	ds_read_b128 v[218:221], v178 offset:7168
	global_load_lds_dwordx4 v[14:15], off
	v_lshl_add_u64 v[14:15], s[20:21], 0, v[164:165]
	s_mov_b32 m0, s4
	s_nop 0
	global_load_lds_dwordx4 v[14:15], off
	s_waitcnt vmcnt(8)
	s_waitcnt lgkmcnt(0)
	s_barrier
	s_waitcnt lgkmcnt(0)
	v_mfma_f32_16x16x32_bf16 v[94:97], v[138:141], v[200:203], v[94:97]
	v_mfma_f32_16x16x32_bf16 v[222:225], v[142:145], v[204:207], v[94:97]
	v_mfma_f32_16x16x32_bf16 v[94:97], v[130:133], v[214:217], v[98:101]
	v_mfma_f32_16x16x32_bf16 v[74:77], v[130:133], v[184:187], v[74:77]
	v_mfma_f32_16x16x32_bf16 v[78:81], v[138:141], v[184:187], v[78:81]
	v_mfma_f32_16x16x32_bf16 v[82:85], v[130:133], v[192:195], v[82:85]
	v_mfma_f32_16x16x32_bf16 v[86:89], v[138:141], v[192:195], v[86:89]
	v_mfma_f32_16x16x32_bf16 v[90:93], v[130:133], v[200:203], v[90:93]
	v_mfma_f32_16x16x32_bf16 v[98:101], v[134:137], v[218:221], v[94:97]
	v_mfma_f32_16x16x32_bf16 v[94:97], v[138:141], v[214:217], v[102:105]
	v_mfma_f32_16x16x32_bf16 v[74:77], v[134:137], v[188:191], v[74:77]
	v_mfma_f32_16x16x32_bf16 v[78:81], v[142:145], v[188:191], v[78:81]
	v_mfma_f32_16x16x32_bf16 v[82:85], v[134:137], v[196:199], v[82:85]
	v_mfma_f32_16x16x32_bf16 v[86:89], v[142:145], v[196:199], v[86:89]
	v_mfma_f32_16x16x32_bf16 v[90:93], v[134:137], v[204:207], v[90:93]
	v_mfma_f32_16x16x32_bf16 v[102:105], v[142:145], v[218:221], v[94:97]
	v_mfma_f32_16x16x32_bf16 v[94:97], v[10:13], v[184:187], v[106:109]
	v_mfma_f32_16x16x32_bf16 v[226:229], v[170:173], v[188:191], v[94:97]
	v_mfma_f32_16x16x32_bf16 v[94:97], v[174:177], v[184:187], v[110:113]
	v_mfma_f32_16x16x32_bf16 v[50:53], v[174:177], v[192:195], v[50:53]
	v_mfma_f32_16x16x32_bf16 v[54:57], v[10:13], v[200:203], v[54:57]
	v_mfma_f32_16x16x32_bf16 v[58:61], v[174:177], v[200:203], v[58:61]
	v_mfma_f32_16x16x32_bf16 v[62:65], v[10:13], v[214:217], v[62:65]
	v_mfma_f32_16x16x32_bf16 v[184:187], v[180:183], v[188:191], v[94:97]
	v_mfma_f32_16x16x32_bf16 v[94:97], v[10:13], v[192:195], v[114:117]
	v_mfma_f32_16x16x32_bf16 v[50:53], v[180:183], v[196:199], v[50:53]
	v_mfma_f32_16x16x32_bf16 v[54:57], v[170:173], v[204:207], v[54:57]
	v_mfma_f32_16x16x32_bf16 v[58:61], v[180:183], v[204:207], v[58:61]
	v_mfma_f32_16x16x32_bf16 v[62:65], v[170:173], v[218:221], v[62:65]
	v_mfma_f32_16x16x32_bf16 v[66:69], v[174:177], v[214:217], v[66:69]
	v_mfma_f32_16x16x32_bf16 v[188:191], v[170:173], v[196:199], v[94:97]
	v_mfma_f32_16x16x32_bf16 v[192:195], v[180:183], v[218:221], v[66:69]
	s_barrier
; #define PG8_STAGE(bufoff, gbase, voff) do { _Pragma("unroll") for (int _i = 0; _i < 2; ++_i) \
;         __builtin_amdgcn_global_load_lds((const unsigned*)((const char*)(gbase) + (voff)[_i]), (PG8_LAS unsigned*)(lds + (bufoff) + ldsw + _i * 8192), 16, 0, 0); } while (0)
; #define PG8_LDA(dst, b, h) do { _Pragma("unroll") for (int m = 0; m < 4; ++m) _Pragma("unroll") for (int k = 0; k < 2; ++k) dst[m][k] = *(const PG8_LAS bf16x8*)(lds + PG8_SA(b, h) + aoff + m * 2048 + k * 1024); } while (0)
; #define PG8_LDB(dst, b, h) do { _Pragma("unroll") for (int n = 0; n < 2; ++n) _Pragma("unroll") for (int k = 0; k < 2; ++k) dst[n][k] = *(const PG8_LAS bf16x8*)(lds + PG8_SB(b, h) + boff + n * 2048 + k * 1024); } while (0)
; #define PG8_MMA(ai, bj, At, Bt) do { __builtin_amdgcn_s_setprio(1); _Pragma("unroll") for (int m = 0; m < 4; ++m) _Pragma("unroll") for (int n = 0; n < 2; ++n) _Pragma("unroll") for (int k = 0; k < 2; ++k) \
;         acc[ai][bj][m][n] = __builtin_amdgcn_mfma_f32_16x16x32_bf16(Bt[n][k], At[m][k], acc[ai][bj][m][n], 0, 0, 0); __builtin_amdgcn_s_setprio(0); } while (0)
; #define PG8_WAIT_V(n) asm volatile("s_waitcnt vmcnt(" #n ")" ::: "memory")
; #define PG8_WAIT_L(n) asm volatile("s_waitcnt lgkmcnt(" #n ")" ::: "memory")
; #define PG8_BAR __builtin_amdgcn_s_barrier()
; #define PG8_SCHED __builtin_amdgcn_sched_barrier(0)
; template <class Epi, class Sched, bool ALIGN_EPI = false, bool SP2 = false>
; __device__ __forceinline__ void gemm_phase(PG8_LAS unsigned char* lds, const Gemm g, const Sched& S, const Epi& E, const int tid) {
;     ...
;             PG8_LDA(At, 0, 1); PG8_STAGE(PG8_SB(0, 0), b2, voffB); PG8_STAGE(PG8_SB(0, 1), b2 + hstep, voffB); PG8_STAGE(PG8_SA(0, 0), a2, voffA);
;             PG8_WAIT_V(8); PG8_WAIT_L(0); PG8_BAR; PG8_MMA(1, 0, At, B0); PG8_MMA(1, 1, At, B1); PG8_BAR; PG8_SCHED;
;             PG8_LDB(B0, 1, 0); PG8_LDB(B1, 1, 1); PG8_SCHED; PG8_LDA(At, 1, 0); PG8_STAGE(PG8_SA(0, 1), a2 + hstep, voffA);
	s_mov_b32 m0, s8
	v_lshl_add_u64 v[208:209], s[44:45], 0, v[166:167]
	s_add_u32 s4, s44, 0x18000
	s_nop 0
	ds_read_b128 v[66:69], v178 offset:16384
	ds_read_b128 v[94:97], v178 offset:17408
	ds_read_b128 v[106:109], v178 offset:18432
	ds_read_b128 v[110:113], v178 offset:19456
	ds_read_b128 v[114:117], v178 offset:20480
	ds_read_b128 v[196:199], v178 offset:21504
	ds_read_b128 v[200:203], v178 offset:22528
	ds_read_b128 v[204:207], v178 offset:23552
	global_load_lds_dwordx4 v[208:209], off
	v_lshl_add_u64 v[210:211], s[44:45], 0, v[162:163]
	s_mov_b32 m0, s9
	s_addc_u32 s5, s45, 0
	global_load_lds_dwordx4 v[210:211], off
	v_lshl_add_u64 v[14:15], s[4:5], 0, v[166:167]
	s_mov_b32 m0, s14
	v_lshl_add_u64 v[212:213], s[38:39], 0, v[168:169]
	global_load_lds_dwordx4 v[14:15], off
	v_lshl_add_u64 v[14:15], s[4:5], 0, v[162:163]
	s_mov_b32 m0, s34
	v_lshl_add_u64 v[246:247], s[38:39], 0, v[164:165]
	global_load_lds_dwordx4 v[14:15], off
	s_mov_b32 m0, s1
	s_nop 0
	global_load_lds_dwordx4 v[212:213], off
	s_mov_b32 m0, s35
	s_nop 0
	global_load_lds_dwordx4 v[246:247], off
	s_waitcnt vmcnt(8)
	s_waitcnt lgkmcnt(0)
	s_barrier
	s_waitcnt lgkmcnt(0)
	v_mfma_f32_16x16x32_bf16 v[2:5], v[130:133], v[66:69], v[2:5]
	v_mfma_f32_16x16x32_bf16 v[6:9], v[138:141], v[66:69], v[6:9]
	v_mfma_f32_16x16x32_bf16 v[2:5], v[134:137], v[94:97], v[2:5]
	v_mfma_f32_16x16x32_bf16 v[6:9], v[142:145], v[94:97], v[6:9]
	v_mfma_f32_16x16x32_bf16 v[146:149], v[130:133], v[106:109], v[146:149]
	v_mfma_f32_16x16x32_bf16 v[150:153], v[138:141], v[106:109], v[150:153]
	v_mfma_f32_16x16x32_bf16 v[154:157], v[130:133], v[114:117], v[154:157]
	v_mfma_f32_16x16x32_bf16 v[158:161], v[138:141], v[114:117], v[158:161]
	v_mfma_f32_16x16x32_bf16 v[42:45], v[130:133], v[200:203], v[42:45]
	v_mfma_f32_16x16x32_bf16 v[26:29], v[138:141], v[200:203], v[26:29]
	v_mfma_f32_16x16x32_bf16 v[146:149], v[134:137], v[110:113], v[146:149]
	v_mfma_f32_16x16x32_bf16 v[150:153], v[142:145], v[110:113], v[150:153]
	v_mfma_f32_16x16x32_bf16 v[154:157], v[134:137], v[196:199], v[154:157]
	v_mfma_f32_16x16x32_bf16 v[158:161], v[142:145], v[196:199], v[158:161]
	v_mfma_f32_16x16x32_bf16 v[130:133], v[134:137], v[204:207], v[42:45]
	v_mfma_f32_16x16x32_bf16 v[134:137], v[142:145], v[204:207], v[26:29]
	v_mfma_f32_16x16x32_bf16 v[26:29], v[10:13], v[66:69], v[30:33]
	v_mfma_f32_16x16x32_bf16 v[138:141], v[170:173], v[94:97], v[26:29]
	v_mfma_f32_16x16x32_bf16 v[26:29], v[174:177], v[66:69], v[46:49]
	v_mfma_f32_16x16x32_bf16 v[142:145], v[180:183], v[94:97], v[26:29]
	v_mfma_f32_16x16x32_bf16 v[26:29], v[10:13], v[106:109], v[70:73]
	v_mfma_f32_16x16x32_bf16 v[214:217], v[170:173], v[110:113], v[26:29]
	v_mfma_f32_16x16x32_bf16 v[26:29], v[174:177], v[106:109], v[118:121]
	v_mfma_f32_16x16x32_bf16 v[218:221], v[180:183], v[110:113], v[26:29]
	v_mfma_f32_16x16x32_bf16 v[26:29], v[10:13], v[114:117], v[122:125]
	v_mfma_f32_16x16x32_bf16 v[10:13], v[10:13], v[200:203], v[34:37]
	v_mfma_f32_16x16x32_bf16 v[230:233], v[170:173], v[196:199], v[26:29]
	v_mfma_f32_16x16x32_bf16 v[26:29], v[174:177], v[114:117], v[126:129]
	v_mfma_f32_16x16x32_bf16 v[170:173], v[170:173], v[204:207], v[10:13]
	v_mfma_f32_16x16x32_bf16 v[10:13], v[174:177], v[200:203], v[38:41]
	v_mfma_f32_16x16x32_bf16 v[196:199], v[180:183], v[196:199], v[26:29]
	v_mfma_f32_16x16x32_bf16 v[174:177], v[180:183], v[204:207], v[10:13]
	s_barrier
	s_nop 3
	ds_read_b128 v[10:13], v17
	ds_read_b128 v[14:17], v18
	ds_read_b128 v[34:37], v19
	ds_read_b128 v[38:41], v20
	ds_read_b128 v[180:183], v21
	ds_read_b128 v[200:203], v22
	ds_read_b128 v[204:207], v23
	ds_read_b128 v[234:237], v24
	s_add_u32 s4, s38, 0x18000
	s_addc_u32 s5, s39, 0
	s_mov_b32 m0, s84
	v_lshl_add_u64 v[66:67], s[4:5], 0, v[168:169]
	ds_read_b128 v[18:21], v178 offset:32768
	ds_read_b128 v[22:25], v178 offset:33792
	ds_read_b128 v[26:29], v178 offset:34816
	ds_read_b128 v[30:33], v178 offset:35840
	ds_read_b128 v[42:45], v178 offset:36864
	ds_read_b128 v[46:49], v178 offset:37888
	ds_read_b128 v[238:241], v178 offset:38912
	ds_read_b128 v[242:245], v178 offset:39936
	global_load_lds_dwordx4 v[66:67], off
	v_lshl_add_u64 v[66:67], s[4:5], 0, v[164:165]
	s_mov_b32 m0, s85
	s_nop 0
	global_load_lds_dwordx4 v[66:67], off
	s_waitcnt vmcnt(8)
	s_waitcnt lgkmcnt(0)
	s_barrier
; #define PG8_STAGE(bufoff, gbase, voff) do { _Pragma("unroll") for (int _i = 0; _i < 2; ++_i) \
;         __builtin_amdgcn_global_load_lds((const unsigned*)((const char*)(gbase) + (voff)[_i]), (PG8_LAS unsigned*)(lds + (bufoff) + ldsw + _i * 8192), 16, 0, 0); } while (0)
; #define PG8_LDA(dst, b, h) do { _Pragma("unroll") for (int m = 0; m < 4; ++m) _Pragma("unroll") for (int k = 0; k < 2; ++k) dst[m][k] = *(const PG8_LAS bf16x8*)(lds + PG8_SA(b, h) + aoff + m * 2048 + k * 1024); } while (0)
; #define PG8_MMA(ai, bj, At, Bt) do { __builtin_amdgcn_s_setprio(1); _Pragma("unroll") for (int m = 0; m < 4; ++m) _Pragma("unroll") for (int n = 0; n < 2; ++n) _Pragma("unroll") for (int k = 0; k < 2; ++k) \
;         acc[ai][bj][m][n] = __builtin_amdgcn_mfma_f32_16x16x32_bf16(Bt[n][k], At[m][k], acc[ai][bj][m][n], 0, 0, 0); __builtin_amdgcn_s_setprio(0); } while (0)
; #define PG8_WAIT_V(n) asm volatile("s_waitcnt vmcnt(" #n ")" ::: "memory")
; #define PG8_WAIT_L(n) asm volatile("s_waitcnt lgkmcnt(" #n ")" ::: "memory")
; #define PG8_BAR __builtin_amdgcn_s_barrier()
; #define PG8_SCHED __builtin_amdgcn_sched_barrier(0)
; template <class Epi, class Sched, bool ALIGN_EPI = false, bool SP2 = false>
; __device__ __forceinline__ void gemm_phase(PG8_LAS unsigned char* lds, const Gemm g, const Sched& S, const Epi& E, const int tid) {
;     ...
;             PG8_WAIT_V(8); PG8_WAIT_L(0); PG8_BAR; PG8_MMA(0, 0, At, B0); PG8_MMA(0, 1, At, B1); PG8_BAR; PG8_SCHED;
;             PG8_LDA(At, 1, 1); PG8_STAGE(PG8_SB(1, 0), b3, voffB); PG8_STAGE(PG8_SB(1, 1), b3 + hstep, voffB); PG8_STAGE(PG8_SA(1, 0), a3, voffA);
;             PG8_WAIT_V(8); PG8_WAIT_L(0); PG8_BAR; PG8_MMA(1, 0, At, B0); PG8_MMA(1, 1, At, B1); PG8_BAR; PG8_SCHED;
;     ...
;         if constexpr (ALIGN_EPI) { if (wr == 0) PG8_BAR; }
	s_waitcnt lgkmcnt(0)
	v_mfma_f32_16x16x32_bf16 v[66:69], v[10:13], v[18:21], v[74:77]
	v_mfma_f32_16x16x32_bf16 v[126:129], v[14:17], v[22:25], v[66:69]
	v_mfma_f32_16x16x32_bf16 v[66:69], v[34:37], v[18:21], v[78:81]
	v_mfma_f32_16x16x32_bf16 v[122:125], v[38:41], v[22:25], v[66:69]
	v_mfma_f32_16x16x32_bf16 v[66:69], v[10:13], v[26:29], v[82:85]
	v_mfma_f32_16x16x32_bf16 v[110:113], v[14:17], v[30:33], v[66:69]
	v_mfma_f32_16x16x32_bf16 v[66:69], v[34:37], v[26:29], v[86:89]
	v_mfma_f32_16x16x32_bf16 v[106:109], v[38:41], v[30:33], v[66:69]
	v_mfma_f32_16x16x32_bf16 v[66:69], v[10:13], v[42:45], v[90:93]
	v_mfma_f32_16x16x32_bf16 v[94:97], v[14:17], v[46:49], v[66:69]
	v_mfma_f32_16x16x32_bf16 v[66:69], v[34:37], v[42:45], v[222:225]
	v_mfma_f32_16x16x32_bf16 v[90:93], v[38:41], v[46:49], v[66:69]
	v_mfma_f32_16x16x32_bf16 v[66:69], v[10:13], v[238:241], v[98:101]
	v_mfma_f32_16x16x32_bf16 v[70:73], v[14:17], v[242:245], v[66:69]
	v_mfma_f32_16x16x32_bf16 v[66:69], v[34:37], v[238:241], v[102:105]
	v_mfma_f32_16x16x32_bf16 v[66:69], v[38:41], v[242:245], v[66:69]
	v_mfma_f32_16x16x32_bf16 v[74:77], v[180:183], v[18:21], v[226:229]
	v_mfma_f32_16x16x32_bf16 v[18:21], v[204:207], v[18:21], v[184:187]
	v_mfma_f32_16x16x32_bf16 v[114:117], v[234:237], v[22:25], v[18:21]
	v_mfma_f32_16x16x32_bf16 v[18:21], v[180:183], v[26:29], v[188:191]
	v_mfma_f32_16x16x32_bf16 v[102:105], v[200:203], v[30:33], v[18:21]
	v_mfma_f32_16x16x32_bf16 v[18:21], v[204:207], v[26:29], v[50:53]
	v_mfma_f32_16x16x32_bf16 v[98:101], v[234:237], v[30:33], v[18:21]
	v_mfma_f32_16x16x32_bf16 v[18:21], v[180:183], v[42:45], v[54:57]
	v_mfma_f32_16x16x32_bf16 v[86:89], v[200:203], v[46:49], v[18:21]
	v_mfma_f32_16x16x32_bf16 v[18:21], v[204:207], v[42:45], v[58:61]
	v_mfma_f32_16x16x32_bf16 v[82:85], v[234:237], v[46:49], v[18:21]
	v_mfma_f32_16x16x32_bf16 v[18:21], v[180:183], v[238:241], v[62:65]
	v_mfma_f32_16x16x32_bf16 v[54:57], v[200:203], v[242:245], v[18:21]
	v_mfma_f32_16x16x32_bf16 v[18:21], v[204:207], v[238:241], v[192:195]
	v_mfma_f32_16x16x32_bf16 v[118:121], v[200:203], v[22:25], v[74:77]
	v_mfma_f32_16x16x32_bf16 v[50:53], v[234:237], v[242:245], v[18:21]
	s_barrier
	s_mov_b32 m0, s88
	v_lshl_add_u64 v[26:27], v[208:209], 0, s[12:13]
	s_add_u32 s4, s44, 0x18080
	s_nop 0
	ds_read_b128 v[18:21], v178 offset:49152
	ds_read_b128 v[22:25], v178 offset:50176
	ds_read_b128 v[184:187], v178 offset:51200
	ds_read_b128 v[188:191], v178 offset:52224
	ds_read_b128 v[192:195], v178 offset:53248
	ds_read_b128 v[222:225], v178 offset:54272
	ds_read_b128 v[226:229], v178 offset:55296
	ds_read_b128 v[238:241], v178 offset:56320
	global_load_lds_dwordx4 v[26:27], off
	v_lshl_add_u64 v[26:27], v[210:211], 0, s[12:13]
	s_mov_b32 m0, s89
	s_addc_u32 s5, s45, 0
	global_load_lds_dwordx4 v[26:27], off
	v_lshl_add_u64 v[26:27], s[4:5], 0, v[166:167]
	s_mov_b32 m0, s28
	s_nop 0
	global_load_lds_dwordx4 v[26:27], off
	v_lshl_add_u64 v[26:27], s[4:5], 0, v[162:163]
	s_mov_b32 m0, s29
	s_nop 0
	global_load_lds_dwordx4 v[26:27], off
	v_lshl_add_u64 v[26:27], v[212:213], 0, s[12:13]
	s_mov_b32 m0, s90
	s_nop 0
	global_load_lds_dwordx4 v[26:27], off
	v_lshl_add_u64 v[26:27], v[246:247], 0, s[12:13]
	s_mov_b32 m0, s91
	s_nop 0
	global_load_lds_dwordx4 v[26:27], off
	s_waitcnt vmcnt(8)
	s_waitcnt lgkmcnt(0)
	s_barrier
	s_waitcnt lgkmcnt(0)
	v_mfma_f32_16x16x32_bf16 v[2:5], v[10:13], v[18:21], v[2:5]
	v_mfma_f32_16x16x32_bf16 v[78:81], v[14:17], v[22:25], v[2:5]
	v_mfma_f32_16x16x32_bf16 v[2:5], v[34:37], v[18:21], v[6:9]
	v_mfma_f32_16x16x32_bf16 v[74:77], v[38:41], v[22:25], v[2:5]
	v_mfma_f32_16x16x32_bf16 v[2:5], v[10:13], v[184:187], v[146:149]
	v_mfma_f32_16x16x32_bf16 v[46:49], v[14:17], v[188:191], v[2:5]
	v_mfma_f32_16x16x32_bf16 v[2:5], v[34:37], v[184:187], v[150:153]
	v_mfma_f32_16x16x32_bf16 v[42:45], v[38:41], v[188:191], v[2:5]
	v_mfma_f32_16x16x32_bf16 v[2:5], v[10:13], v[192:195], v[154:157]
	v_mfma_f32_16x16x32_bf16 v[30:33], v[14:17], v[222:225], v[2:5]
	v_mfma_f32_16x16x32_bf16 v[2:5], v[34:37], v[192:195], v[158:161]
	v_mfma_f32_16x16x32_bf16 v[26:29], v[38:41], v[222:225], v[2:5]
	v_mfma_f32_16x16x32_bf16 v[2:5], v[10:13], v[226:229], v[130:133]
	v_mfma_f32_16x16x32_bf16 v[14:17], v[14:17], v[238:241], v[2:5]
	v_mfma_f32_16x16x32_bf16 v[2:5], v[34:37], v[226:229], v[134:137]
	v_mfma_f32_16x16x32_bf16 v[10:13], v[38:41], v[238:241], v[2:5]
	v_mfma_f32_16x16x32_bf16 v[2:5], v[180:183], v[18:21], v[138:141]
	v_mfma_f32_16x16x32_bf16 v[62:65], v[200:203], v[22:25], v[2:5]
	v_mfma_f32_16x16x32_bf16 v[2:5], v[204:207], v[18:21], v[142:145]
	v_mfma_f32_16x16x32_bf16 v[58:61], v[234:237], v[22:25], v[2:5]
	v_mfma_f32_16x16x32_bf16 v[2:5], v[180:183], v[184:187], v[214:217]
	v_mfma_f32_16x16x32_bf16 v[38:41], v[200:203], v[188:191], v[2:5]
	v_mfma_f32_16x16x32_bf16 v[2:5], v[204:207], v[184:187], v[218:221]
	v_mfma_f32_16x16x32_bf16 v[34:37], v[234:237], v[188:191], v[2:5]
	v_mfma_f32_16x16x32_bf16 v[2:5], v[180:183], v[192:195], v[230:233]
	v_mfma_f32_16x16x32_bf16 v[22:25], v[200:203], v[222:225], v[2:5]
	v_mfma_f32_16x16x32_bf16 v[2:5], v[204:207], v[192:195], v[196:199]
	v_mfma_f32_16x16x32_bf16 v[18:21], v[234:237], v[222:225], v[2:5]
	v_mfma_f32_16x16x32_bf16 v[2:5], v[180:183], v[226:229], v[170:173]
	v_mfma_f32_16x16x32_bf16 v[6:9], v[200:203], v[238:241], v[2:5]
	v_mfma_f32_16x16x32_bf16 v[2:5], v[204:207], v[226:229], v[174:177]
	v_mfma_f32_16x16x32_bf16 v[2:5], v[234:237], v[238:241], v[2:5]
	s_barrier
	s_andn2_b64 vcc, exec, s[40:41]
	s_cbranch_vccnz .LBB0_390
	s_barrier

; #define PG8_STAGE(bufoff, gbase, voff) do { _Pragma("unroll") for (int _i = 0; _i < 2; ++_i) \
;         __builtin_amdgcn_global_load_lds((const unsigned*)((const char*)(gbase) + (voff)[_i]), (PG8_LAS unsigned*)(lds + (bufoff) + ldsw + _i * 8192), 16, 0, 0); } while (0)
; #define PG8_LDA(dst, b, h) do { _Pragma("unroll") for (int m = 0; m < 4; ++m) _Pragma("unroll") for (int k = 0; k < 2; ++k) dst[m][k] = *(const PG8_LAS bf16x8*)(lds + PG8_SA(b, h) + aoff + m * 2048 + k * 1024); } while (0)
; #define PG8_LDB(dst, b, h) do { _Pragma("unroll") for (int n = 0; n < 2; ++n) _Pragma("unroll") for (int k = 0; k < 2; ++k) dst[n][k] = *(const PG8_LAS bf16x8*)(lds + PG8_SB(b, h) + boff + n * 2048 + k * 1024); } while (0)
; #define PG8_MMA(ai, bj, At, Bt) do { __builtin_amdgcn_s_setprio(1); _Pragma("unroll") for (int m = 0; m < 4; ++m) _Pragma("unroll") for (int n = 0; n < 2; ++n) _Pragma("unroll") for (int k = 0; k < 2; ++k) \
;         acc[ai][bj][m][n] = __builtin_amdgcn_mfma_f32_16x16x32_bf16(Bt[n][k], At[m][k], acc[ai][bj][m][n], 0, 0, 0); __builtin_amdgcn_s_setprio(0); } while (0)
; #define PG8_WAIT_V(n) asm volatile("s_waitcnt vmcnt(" #n ")" ::: "memory")
; #define PG8_WAIT_L(n) asm volatile("s_waitcnt lgkmcnt(" #n ")" ::: "memory")
; #define PG8_BAR __builtin_amdgcn_s_barrier()
; #define PG8_SCHED __builtin_amdgcn_sched_barrier(0)
; template <class Epi, class Sched, bool ALIGN_EPI = false, bool SP2 = false>
; __device__ __forceinline__ void gemm_phase(PG8_LAS unsigned char* lds, const Gemm g, const Sched& S, const Epi& E, const int tid) {
;     ...
;             const bool last = (t == nt - 2);
;             const char* a1 = cA + (size_t)(t + 1) * kstep;
;             const char* a2 = last ? nA : cA + (size_t)(t + 2) * kstep; const char* b2 = last ? nB : cB + (size_t)(t + 2) * kstep;
;             const char* a3 = a2 + kstep; const char* b3 = b2 + kstep;
;             if (last && has_next) S.a_ready(nxt);
;             if constexpr (SP2) {
;             PG8_LDB(B0, 0, 0); PG8_LDB(B1, 0, 1); PG8_SCHED; PG8_LDA(At, 0, 0); PG8_STAGE(PG8_SA(1, 1), a1 + hstep, voffA);
;             PG8_WAIT_V(8); PG8_WAIT_L(0); PG8_BAR; PG8_MMA(0, 0, At, B0); PG8_MMA(0, 1, At, B1); PG8_BAR; PG8_SCHED;
;             PG8_LDA(At, 0, 1); PG8_STAGE(PG8_SB(0, 0), b2, voffB); PG8_STAGE(PG8_SB(0, 1), b2 + hstep, voffB); PG8_STAGE(PG8_SA(0, 0), a2, voffA);
.LBB0_499:
	v_or_b32_e32 v140, 0x10000, v145
	v_add_u32_e32 v146, 0x10400, v145
	v_add_u32_e32 v150, 0x10800, v145
	v_add_u32_e32 v154, 0x10c00, v145
	v_or_b32_e32 v158, 0x14000, v145
	v_add_u32_e32 v162, 0x14400, v145
	v_add_u32_e32 v166, 0x14800, v145
	v_add_u32_e32 v170, 0x14c00, v145
	ds_read_b128 v[140:143], v140
	ds_read_b128 v[146:149], v146
	ds_read_b128 v[150:153], v150
	ds_read_b128 v[154:157], v154
	ds_read_b128 v[158:161], v158
	ds_read_b128 v[162:165], v162
	ds_read_b128 v[166:169], v166
	ds_read_b128 v[170:173], v170
	s_add_u32 s88, s86, 0xfffc0080
	s_addc_u32 s89, s87, -1
	s_cmp_eq_u32 s96, 12
	s_cselect_b32 s91, s39, s89
	s_cselect_b32 s90, s43, s88
	s_cselect_b32 s89, s41, s85
	s_cselect_b32 s88, s50, s51
	v_lshl_add_u64 v[178:179], s[86:87], 0, v[136:137]
	s_add_i32 m0, s0, 0xc000
	ds_read_b128 v[174:177], v144
	ds_read_b128 v[184:187], v144 offset:1024
	ds_read_b128 v[188:191], v144 offset:2048
	ds_read_b128 v[192:195], v144 offset:3072
	ds_read_b128 v[196:199], v144 offset:4096
	ds_read_b128 v[200:203], v144 offset:5120
	ds_read_b128 v[204:207], v144 offset:6144
	ds_read_b128 v[214:217], v144 offset:7168
	global_load_lds_dwordx4 v[178:179], off
	v_lshl_add_u64 v[178:179], s[86:87], 0, v[138:139]
	s_add_i32 m0, s0, 0xe000
	s_nop 0
	global_load_lds_dwordx4 v[178:179], off
	s_waitcnt vmcnt(8)
	s_waitcnt lgkmcnt(0)
	s_barrier
	s_waitcnt lgkmcnt(0)
	v_mfma_f32_16x16x32_bf16 v[126:129], v[140:143], v[174:177], v[126:129]
	v_mfma_f32_16x16x32_bf16 v[126:129], v[146:149], v[184:187], v[126:129]
	v_mfma_f32_16x16x32_bf16 v[122:125], v[150:153], v[174:177], v[122:125]
	v_mfma_f32_16x16x32_bf16 v[122:125], v[154:157], v[184:187], v[122:125]
	v_mfma_f32_16x16x32_bf16 v[114:117], v[140:143], v[188:191], v[114:117]
	v_mfma_f32_16x16x32_bf16 v[114:117], v[146:149], v[192:195], v[114:117]
	v_mfma_f32_16x16x32_bf16 v[106:109], v[150:153], v[188:191], v[106:109]
	v_mfma_f32_16x16x32_bf16 v[106:109], v[154:157], v[192:195], v[106:109]
	v_mfma_f32_16x16x32_bf16 v[98:101], v[140:143], v[196:199], v[98:101]
	v_mfma_f32_16x16x32_bf16 v[98:101], v[146:149], v[200:203], v[98:101]
	v_mfma_f32_16x16x32_bf16 v[90:93], v[150:153], v[196:199], v[90:93]
	v_mfma_f32_16x16x32_bf16 v[90:93], v[154:157], v[200:203], v[90:93]
	v_mfma_f32_16x16x32_bf16 v[82:85], v[140:143], v[204:207], v[82:85]
	v_mfma_f32_16x16x32_bf16 v[82:85], v[146:149], v[214:217], v[82:85]
	v_mfma_f32_16x16x32_bf16 v[74:77], v[150:153], v[204:207], v[74:77]
	v_mfma_f32_16x16x32_bf16 v[74:77], v[154:157], v[214:217], v[74:77]
	v_mfma_f32_16x16x32_bf16 v[118:121], v[158:161], v[174:177], v[118:121]
	v_mfma_f32_16x16x32_bf16 v[118:121], v[162:165], v[184:187], v[118:121]
	v_mfma_f32_16x16x32_bf16 v[110:113], v[166:169], v[174:177], v[110:113]
	v_mfma_f32_16x16x32_bf16 v[110:113], v[170:173], v[184:187], v[110:113]
	v_mfma_f32_16x16x32_bf16 v[102:105], v[158:161], v[188:191], v[102:105]
	v_mfma_f32_16x16x32_bf16 v[102:105], v[162:165], v[192:195], v[102:105]
	v_mfma_f32_16x16x32_bf16 v[94:97], v[166:169], v[188:191], v[94:97]
	v_mfma_f32_16x16x32_bf16 v[94:97], v[170:173], v[192:195], v[94:97]
	v_mfma_f32_16x16x32_bf16 v[86:89], v[158:161], v[196:199], v[86:89]
	v_mfma_f32_16x16x32_bf16 v[86:89], v[162:165], v[200:203], v[86:89]
	v_mfma_f32_16x16x32_bf16 v[78:81], v[166:169], v[196:199], v[78:81]
	v_mfma_f32_16x16x32_bf16 v[78:81], v[170:173], v[200:203], v[78:81]
	v_mfma_f32_16x16x32_bf16 v[70:73], v[158:161], v[204:207], v[70:73]
	v_mfma_f32_16x16x32_bf16 v[70:73], v[162:165], v[214:217], v[70:73]
	v_mfma_f32_16x16x32_bf16 v[66:69], v[166:169], v[204:207], v[66:69]
	v_mfma_f32_16x16x32_bf16 v[66:69], v[170:173], v[214:217], v[66:69]
	s_barrier
	s_mov_b32 m0, s1
	v_lshl_add_u64 v[178:179], s[88:89], 0, v[0:1]
	s_add_u32 s92, s88, 0x40000
	ds_read_b128 v[174:177], v144 offset:16384
	ds_read_b128 v[184:187], v144 offset:17408
	ds_read_b128 v[188:191], v144 offset:18432
	ds_read_b128 v[192:195], v144 offset:19456
	ds_read_b128 v[196:199], v144 offset:20480
	ds_read_b128 v[200:203], v144 offset:21504
	ds_read_b128 v[204:207], v144 offset:22528
	ds_read_b128 v[214:217], v144 offset:23552
	global_load_lds_dwordx4 v[178:179], off
	v_lshl_add_u64 v[180:181], s[88:89], 0, v[134:135]
	s_mov_b32 m0, s2
	s_addc_u32 s93, s89, 0
	global_load_lds_dwordx4 v[180:181], off
	v_lshl_add_u64 v[182:183], s[92:93], 0, v[0:1]
	s_mov_b32 m0, s4
	v_lshl_add_u64 v[218:219], s[90:91], 0, v[132:133]
	global_load_lds_dwordx4 v[182:183], off
	v_lshl_add_u64 v[182:183], s[92:93], 0, v[134:135]
	s_mov_b32 m0, s5
	s_nop 0
	global_load_lds_dwordx4 v[182:183], off
	v_lshl_add_u64 v[182:183], s[90:91], 0, v[130:131]
	s_mov_b32 m0, s0
	s_nop 0
	global_load_lds_dwordx4 v[182:183], off
	s_mov_b32 m0, s6
	s_nop 0
	global_load_lds_dwordx4 v[218:219], off
	s_waitcnt vmcnt(8)
	s_waitcnt lgkmcnt(0)
	s_barrier
; #define PG8_STAGE(bufoff, gbase, voff) do { _Pragma("unroll") for (int _i = 0; _i < 2; ++_i) \
;         __builtin_amdgcn_global_load_lds((const unsigned*)((const char*)(gbase) + (voff)[_i]), (PG8_LAS unsigned*)(lds + (bufoff) + ldsw + _i * 8192), 16, 0, 0); } while (0)
; #define PG8_LDA(dst, b, h) do { _Pragma("unroll") for (int m = 0; m < 4; ++m) _Pragma("unroll") for (int k = 0; k < 2; ++k) dst[m][k] = *(const PG8_LAS bf16x8*)(lds + PG8_SA(b, h) + aoff + m * 2048 + k * 1024); } while (0)
; #define PG8_LDB(dst, b, h) do { _Pragma("unroll") for (int n = 0; n < 2; ++n) _Pragma("unroll") for (int k = 0; k < 2; ++k) dst[n][k] = *(const PG8_LAS bf16x8*)(lds + PG8_SB(b, h) + boff + n * 2048 + k * 1024); } while (0)
; #define PG8_MMA(ai, bj, At, Bt) do { __builtin_amdgcn_s_setprio(1); _Pragma("unroll") for (int m = 0; m < 4; ++m) _Pragma("unroll") for (int n = 0; n < 2; ++n) _Pragma("unroll") for (int k = 0; k < 2; ++k) \
;         acc[ai][bj][m][n] = __builtin_amdgcn_mfma_f32_16x16x32_bf16(Bt[n][k], At[m][k], acc[ai][bj][m][n], 0, 0, 0); __builtin_amdgcn_s_setprio(0); } while (0)
; #define PG8_WAIT_V(n) asm volatile("s_waitcnt vmcnt(" #n ")" ::: "memory")
; #define PG8_WAIT_L(n) asm volatile("s_waitcnt lgkmcnt(" #n ")" ::: "memory")
; #define PG8_BAR __builtin_amdgcn_s_barrier()
; #define PG8_SCHED __builtin_amdgcn_sched_barrier(0)
; template <class Epi, class Sched, bool ALIGN_EPI = false, bool SP2 = false>
; __device__ __forceinline__ void gemm_phase(PG8_LAS unsigned char* lds, const Gemm g, const Sched& S, const Epi& E, const int tid) {
;     ...
;             PG8_WAIT_V(8); PG8_WAIT_L(0); PG8_BAR; PG8_MMA(1, 0, At, B0); PG8_MMA(1, 1, At, B1); PG8_BAR; PG8_SCHED;
;             PG8_LDB(B0, 1, 0); PG8_LDB(B1, 1, 1); PG8_SCHED; PG8_LDA(At, 1, 0); PG8_STAGE(PG8_SA(0, 1), a2 + hstep, voffA);
;             PG8_WAIT_V(8); PG8_WAIT_L(0); PG8_BAR; PG8_MMA(0, 0, At, B0); PG8_MMA(0, 1, At, B1); PG8_BAR; PG8_SCHED;
	s_waitcnt lgkmcnt(0)
	v_mfma_f32_16x16x32_bf16 v[62:65], v[140:143], v[174:177], v[62:65]
	v_mfma_f32_16x16x32_bf16 v[62:65], v[146:149], v[184:187], v[62:65]
	v_mfma_f32_16x16x32_bf16 v[58:61], v[150:153], v[174:177], v[58:61]
	v_mfma_f32_16x16x32_bf16 v[58:61], v[154:157], v[184:187], v[58:61]
	v_mfma_f32_16x16x32_bf16 v[50:53], v[140:143], v[188:191], v[50:53]
	v_mfma_f32_16x16x32_bf16 v[50:53], v[146:149], v[192:195], v[50:53]
	v_mfma_f32_16x16x32_bf16 v[42:45], v[150:153], v[188:191], v[42:45]
	v_mfma_f32_16x16x32_bf16 v[42:45], v[154:157], v[192:195], v[42:45]
	v_mfma_f32_16x16x32_bf16 v[34:37], v[140:143], v[196:199], v[34:37]
	v_mfma_f32_16x16x32_bf16 v[34:37], v[146:149], v[200:203], v[34:37]
	v_mfma_f32_16x16x32_bf16 v[26:29], v[150:153], v[196:199], v[26:29]
	v_mfma_f32_16x16x32_bf16 v[26:29], v[154:157], v[200:203], v[26:29]
	v_mfma_f32_16x16x32_bf16 v[18:21], v[140:143], v[204:207], v[18:21]
	v_mfma_f32_16x16x32_bf16 v[18:21], v[146:149], v[214:217], v[18:21]
	v_mfma_f32_16x16x32_bf16 v[10:13], v[150:153], v[204:207], v[10:13]
	v_mfma_f32_16x16x32_bf16 v[10:13], v[154:157], v[214:217], v[10:13]
	v_mfma_f32_16x16x32_bf16 v[54:57], v[158:161], v[174:177], v[54:57]
	v_mfma_f32_16x16x32_bf16 v[54:57], v[162:165], v[184:187], v[54:57]
	v_mfma_f32_16x16x32_bf16 v[46:49], v[166:169], v[174:177], v[46:49]
	v_mfma_f32_16x16x32_bf16 v[46:49], v[170:173], v[184:187], v[46:49]
	v_mfma_f32_16x16x32_bf16 v[38:41], v[158:161], v[188:191], v[38:41]
	v_mfma_f32_16x16x32_bf16 v[38:41], v[162:165], v[192:195], v[38:41]
	v_mfma_f32_16x16x32_bf16 v[30:33], v[166:169], v[188:191], v[30:33]
	v_mfma_f32_16x16x32_bf16 v[30:33], v[170:173], v[192:195], v[30:33]
	v_mfma_f32_16x16x32_bf16 v[22:25], v[158:161], v[196:199], v[22:25]
	v_mfma_f32_16x16x32_bf16 v[22:25], v[162:165], v[200:203], v[22:25]
	v_mfma_f32_16x16x32_bf16 v[14:17], v[166:169], v[196:199], v[14:17]
	v_mfma_f32_16x16x32_bf16 v[14:17], v[170:173], v[200:203], v[14:17]
	v_mfma_f32_16x16x32_bf16 v[6:9], v[158:161], v[204:207], v[6:9]
	v_mfma_f32_16x16x32_bf16 v[6:9], v[162:165], v[214:217], v[6:9]
	v_mfma_f32_16x16x32_bf16 v[2:5], v[166:169], v[204:207], v[2:5]
	v_mfma_f32_16x16x32_bf16 v[2:5], v[170:173], v[214:217], v[2:5]
	s_barrier
	v_or_b32_e32 v140, 0x18000, v145
	v_add_u32_e32 v146, 0x18400, v145
	v_add_u32_e32 v150, 0x18800, v145
	v_add_u32_e32 v154, 0x18c00, v145
	v_or_b32_e32 v158, 0x1c000, v145
	v_add_u32_e32 v162, 0x1c400, v145
	v_add_u32_e32 v166, 0x1c800, v145
	v_add_u32_e32 v170, 0x1cc00, v145
	ds_read_b128 v[140:143], v140
	ds_read_b128 v[146:149], v146
	ds_read_b128 v[150:153], v150
	ds_read_b128 v[154:157], v154
	ds_read_b128 v[158:161], v158
	ds_read_b128 v[162:165], v162
	ds_read_b128 v[166:169], v166
	ds_read_b128 v[170:173], v170
	s_add_u32 s90, s90, 0x40000
	s_addc_u32 s91, s91, 0
	s_mov_b32 m0, s8
	v_lshl_add_u64 v[220:221], s[90:91], 0, v[130:131]
	ds_read_b128 v[174:177], v144 offset:32768
	ds_read_b128 v[184:187], v144 offset:33792
	ds_read_b128 v[188:191], v144 offset:34816
	ds_read_b128 v[192:195], v144 offset:35840
	ds_read_b128 v[196:199], v144 offset:36864
	ds_read_b128 v[200:203], v144 offset:37888
	ds_read_b128 v[204:207], v144 offset:38912
	ds_read_b128 v[214:217], v144 offset:39936
	global_load_lds_dwordx4 v[220:221], off
	v_lshl_add_u64 v[220:221], s[90:91], 0, v[132:133]
	s_mov_b32 m0, s9
	s_nop 0
	global_load_lds_dwordx4 v[220:221], off
	s_waitcnt vmcnt(8)
	s_waitcnt lgkmcnt(0)
	s_barrier
	s_waitcnt lgkmcnt(0)
	v_mfma_f32_16x16x32_bf16 v[126:129], v[140:143], v[174:177], v[126:129]
	v_mfma_f32_16x16x32_bf16 v[126:129], v[146:149], v[184:187], v[126:129]
	v_mfma_f32_16x16x32_bf16 v[122:125], v[150:153], v[174:177], v[122:125]
	v_mfma_f32_16x16x32_bf16 v[122:125], v[154:157], v[184:187], v[122:125]
	v_mfma_f32_16x16x32_bf16 v[114:117], v[140:143], v[188:191], v[114:117]
	v_mfma_f32_16x16x32_bf16 v[114:117], v[146:149], v[192:195], v[114:117]
	v_mfma_f32_16x16x32_bf16 v[106:109], v[150:153], v[188:191], v[106:109]
	v_mfma_f32_16x16x32_bf16 v[106:109], v[154:157], v[192:195], v[106:109]
	v_mfma_f32_16x16x32_bf16 v[98:101], v[140:143], v[196:199], v[98:101]
	v_mfma_f32_16x16x32_bf16 v[98:101], v[146:149], v[200:203], v[98:101]
	v_mfma_f32_16x16x32_bf16 v[90:93], v[150:153], v[196:199], v[90:93]
	v_mfma_f32_16x16x32_bf16 v[90:93], v[154:157], v[200:203], v[90:93]
	v_mfma_f32_16x16x32_bf16 v[82:85], v[140:143], v[204:207], v[82:85]
	v_mfma_f32_16x16x32_bf16 v[82:85], v[146:149], v[214:217], v[82:85]
	v_mfma_f32_16x16x32_bf16 v[74:77], v[150:153], v[204:207], v[74:77]
	v_mfma_f32_16x16x32_bf16 v[74:77], v[154:157], v[214:217], v[74:77]
	v_mfma_f32_16x16x32_bf16 v[118:121], v[158:161], v[174:177], v[118:121]
	v_mfma_f32_16x16x32_bf16 v[118:121], v[162:165], v[184:187], v[118:121]
	v_mfma_f32_16x16x32_bf16 v[110:113], v[166:169], v[174:177], v[110:113]
	v_mfma_f32_16x16x32_bf16 v[110:113], v[170:173], v[184:187], v[110:113]
	v_mfma_f32_16x16x32_bf16 v[102:105], v[158:161], v[188:191], v[102:105]
	v_mfma_f32_16x16x32_bf16 v[102:105], v[162:165], v[192:195], v[102:105]
	v_mfma_f32_16x16x32_bf16 v[94:97], v[166:169], v[188:191], v[94:97]
	v_mfma_f32_16x16x32_bf16 v[94:97], v[170:173], v[192:195], v[94:97]
	v_mfma_f32_16x16x32_bf16 v[86:89], v[158:161], v[196:199], v[86:89]
	v_mfma_f32_16x16x32_bf16 v[86:89], v[162:165], v[200:203], v[86:89]
	v_mfma_f32_16x16x32_bf16 v[78:81], v[166:169], v[196:199], v[78:81]
	v_mfma_f32_16x16x32_bf16 v[78:81], v[170:173], v[200:203], v[78:81]
	v_mfma_f32_16x16x32_bf16 v[70:73], v[158:161], v[204:207], v[70:73]
	v_mfma_f32_16x16x32_bf16 v[70:73], v[162:165], v[214:217], v[70:73]
	v_mfma_f32_16x16x32_bf16 v[66:69], v[166:169], v[204:207], v[66:69]
	v_mfma_f32_16x16x32_bf16 v[66:69], v[170:173], v[214:217], v[66:69]
	s_barrier
; #define PG8_STAGE(bufoff, gbase, voff) do { _Pragma("unroll") for (int _i = 0; _i < 2; ++_i) \
;         __builtin_amdgcn_global_load_lds((const unsigned*)((const char*)(gbase) + (voff)[_i]), (PG8_LAS unsigned*)(lds + (bufoff) + ldsw + _i * 8192), 16, 0, 0); } while (0)
; #define PG8_LDA(dst, b, h) do { _Pragma("unroll") for (int m = 0; m < 4; ++m) _Pragma("unroll") for (int k = 0; k < 2; ++k) dst[m][k] = *(const PG8_LAS bf16x8*)(lds + PG8_SA(b, h) + aoff + m * 2048 + k * 1024); } while (0)
; #define PG8_MMA(ai, bj, At, Bt) do { __builtin_amdgcn_s_setprio(1); _Pragma("unroll") for (int m = 0; m < 4; ++m) _Pragma("unroll") for (int n = 0; n < 2; ++n) _Pragma("unroll") for (int k = 0; k < 2; ++k) \
;         acc[ai][bj][m][n] = __builtin_amdgcn_mfma_f32_16x16x32_bf16(Bt[n][k], At[m][k], acc[ai][bj][m][n], 0, 0, 0); __builtin_amdgcn_s_setprio(0); } while (0)
; #define PG8_WAIT_V(n) asm volatile("s_waitcnt vmcnt(" #n ")" ::: "memory")
; #define PG8_WAIT_L(n) asm volatile("s_waitcnt lgkmcnt(" #n ")" ::: "memory")
; #define PG8_BAR __builtin_amdgcn_s_barrier()
; #define PG8_SCHED __builtin_amdgcn_sched_barrier(0)
; template <class Epi, class Sched, bool ALIGN_EPI = false, bool SP2 = false>
; __device__ __forceinline__ void gemm_phase(PG8_LAS unsigned char* lds, const Gemm g, const Sched& S, const Epi& E, const int tid) {
;     ...
;             PG8_LDA(At, 1, 1); PG8_STAGE(PG8_SB(1, 0), b3, voffB); PG8_STAGE(PG8_SB(1, 1), b3 + hstep, voffB); PG8_STAGE(PG8_SA(1, 0), a3, voffA);
;             PG8_WAIT_V(8); PG8_WAIT_L(0); PG8_BAR; PG8_MMA(1, 0, At, B0); PG8_MMA(1, 1, At, B1); PG8_BAR; PG8_SCHED;
;     ...
;         if constexpr (ALIGN_EPI) { if (wr == 0) PG8_BAR; }
	s_mov_b32 m0, s17
	v_lshl_add_u64 v[178:179], v[178:179], 0, s[12:13]
	s_add_u32 s88, s88, 0x40080
	ds_read_b128 v[174:177], v144 offset:49152
	ds_read_b128 v[184:187], v144 offset:50176
	ds_read_b128 v[188:191], v144 offset:51200
	ds_read_b128 v[192:195], v144 offset:52224
	ds_read_b128 v[196:199], v144 offset:53248
	ds_read_b128 v[200:203], v144 offset:54272
	ds_read_b128 v[204:207], v144 offset:55296
	ds_read_b128 v[214:217], v144 offset:56320
	global_load_lds_dwordx4 v[178:179], off
	v_lshl_add_u64 v[178:179], v[180:181], 0, s[12:13]
	s_mov_b32 m0, s20
	s_addc_u32 s89, s89, 0
	global_load_lds_dwordx4 v[178:179], off
	v_lshl_add_u64 v[178:179], s[88:89], 0, v[0:1]
	s_mov_b32 m0, s26
	s_nop 0
	global_load_lds_dwordx4 v[178:179], off
	v_lshl_add_u64 v[178:179], s[88:89], 0, v[134:135]
	s_mov_b32 m0, s27
	s_nop 0
	global_load_lds_dwordx4 v[178:179], off
	v_lshl_add_u64 v[178:179], v[182:183], 0, s[12:13]
	s_mov_b32 m0, s21
	s_nop 0
	global_load_lds_dwordx4 v[178:179], off
	v_lshl_add_u64 v[178:179], v[218:219], 0, s[12:13]
	s_mov_b32 m0, s24
	s_nop 0
	global_load_lds_dwordx4 v[178:179], off
	s_waitcnt vmcnt(8)
	s_waitcnt lgkmcnt(0)
	s_barrier
	s_waitcnt lgkmcnt(0)
	v_mfma_f32_16x16x32_bf16 v[62:65], v[140:143], v[174:177], v[62:65]
	v_mfma_f32_16x16x32_bf16 v[62:65], v[146:149], v[184:187], v[62:65]
	v_mfma_f32_16x16x32_bf16 v[58:61], v[150:153], v[174:177], v[58:61]
	v_mfma_f32_16x16x32_bf16 v[58:61], v[154:157], v[184:187], v[58:61]
	v_mfma_f32_16x16x32_bf16 v[50:53], v[140:143], v[188:191], v[50:53]
	v_mfma_f32_16x16x32_bf16 v[50:53], v[146:149], v[192:195], v[50:53]
	v_mfma_f32_16x16x32_bf16 v[42:45], v[150:153], v[188:191], v[42:45]
	v_mfma_f32_16x16x32_bf16 v[42:45], v[154:157], v[192:195], v[42:45]
	v_mfma_f32_16x16x32_bf16 v[34:37], v[140:143], v[196:199], v[34:37]
	v_mfma_f32_16x16x32_bf16 v[34:37], v[146:149], v[200:203], v[34:37]
	v_mfma_f32_16x16x32_bf16 v[26:29], v[150:153], v[196:199], v[26:29]
	v_mfma_f32_16x16x32_bf16 v[26:29], v[154:157], v[200:203], v[26:29]
	v_mfma_f32_16x16x32_bf16 v[18:21], v[140:143], v[204:207], v[18:21]
	v_mfma_f32_16x16x32_bf16 v[18:21], v[146:149], v[214:217], v[18:21]
	v_mfma_f32_16x16x32_bf16 v[10:13], v[150:153], v[204:207], v[10:13]
	v_mfma_f32_16x16x32_bf16 v[10:13], v[154:157], v[214:217], v[10:13]
	v_mfma_f32_16x16x32_bf16 v[54:57], v[158:161], v[174:177], v[54:57]
	v_mfma_f32_16x16x32_bf16 v[54:57], v[162:165], v[184:187], v[54:57]
	v_mfma_f32_16x16x32_bf16 v[46:49], v[166:169], v[174:177], v[46:49]
	v_mfma_f32_16x16x32_bf16 v[46:49], v[170:173], v[184:187], v[46:49]
	v_mfma_f32_16x16x32_bf16 v[38:41], v[158:161], v[188:191], v[38:41]
	v_mfma_f32_16x16x32_bf16 v[38:41], v[162:165], v[192:195], v[38:41]
	v_mfma_f32_16x16x32_bf16 v[30:33], v[166:169], v[188:191], v[30:33]
	v_mfma_f32_16x16x32_bf16 v[30:33], v[170:173], v[192:195], v[30:33]
	v_mfma_f32_16x16x32_bf16 v[22:25], v[158:161], v[196:199], v[22:25]
	v_mfma_f32_16x16x32_bf16 v[22:25], v[162:165], v[200:203], v[22:25]
	v_mfma_f32_16x16x32_bf16 v[14:17], v[166:169], v[196:199], v[14:17]
	v_mfma_f32_16x16x32_bf16 v[14:17], v[170:173], v[200:203], v[14:17]
	v_mfma_f32_16x16x32_bf16 v[6:9], v[158:161], v[204:207], v[6:9]
	v_mfma_f32_16x16x32_bf16 v[6:9], v[162:165], v[214:217], v[6:9]
	v_mfma_f32_16x16x32_bf16 v[2:5], v[166:169], v[204:207], v[2:5]
	v_mfma_f32_16x16x32_bf16 v[2:5], v[170:173], v[214:217], v[2:5]
	s_barrier
	s_add_i32 s96, s96, 2
	s_add_u32 s86, s86, 0x100
	s_addc_u32 s87, s87, 0
	s_add_u32 s51, s51, 0x100
	s_addc_u32 s85, s85, 0
	s_cmp_gt_u32 s96, 13
	s_cbranch_scc0 .LBB0_499
	s_and_b64 vcc, exec, s[14:15]
	s_cbranch_vccz .LBB0_502
	s_barrier

; #define PG8_STAGE(bufoff, gbase, voff) do { _Pragma("unroll") for (int _i = 0; _i < 2; ++_i) \
;         __builtin_amdgcn_global_load_lds((const unsigned*)((const char*)(gbase) + (voff)[_i]), (PG8_LAS unsigned*)(lds + (bufoff) + ldsw + _i * 8192), 16, 0, 0); } while (0)
; #define PG8_LDA(dst, b, h) do { _Pragma("unroll") for (int m = 0; m < 4; ++m) _Pragma("unroll") for (int k = 0; k < 2; ++k) dst[m][k] = *(const PG8_LAS bf16x8*)(lds + PG8_SA(b, h) + aoff + m * 2048 + k * 1024); } while (0)
; #define PG8_LDB(dst, b, h) do { _Pragma("unroll") for (int n = 0; n < 2; ++n) _Pragma("unroll") for (int k = 0; k < 2; ++k) dst[n][k] = *(const PG8_LAS bf16x8*)(lds + PG8_SB(b, h) + boff + n * 2048 + k * 1024); } while (0)
; #define PG8_MMA(ai, bj, At, Bt) do { __builtin_amdgcn_s_setprio(1); _Pragma("unroll") for (int m = 0; m < 4; ++m) _Pragma("unroll") for (int n = 0; n < 2; ++n) _Pragma("unroll") for (int k = 0; k < 2; ++k) \
;         acc[ai][bj][m][n] = __builtin_amdgcn_mfma_f32_16x16x32_bf16(Bt[n][k], At[m][k], acc[ai][bj][m][n], 0, 0, 0); __builtin_amdgcn_s_setprio(0); } while (0)
; #define PG8_WAIT_V(n) asm volatile("s_waitcnt vmcnt(" #n ")" ::: "memory")
; #define PG8_WAIT_L(n) asm volatile("s_waitcnt lgkmcnt(" #n ")" ::: "memory")
; #define PG8_BAR __builtin_amdgcn_s_barrier()
; #define PG8_SCHED __builtin_amdgcn_sched_barrier(0)
; template <class Epi, class Sched, bool ALIGN_EPI = false, bool SP2 = false>
; __device__ __forceinline__ void gemm_phase(PG8_LAS unsigned char* lds, const Gemm g, const Sched& S, const Epi& E, const int tid) {
;     ...
;             const bool last = (t == nt - 2);
;             const char* a1 = cA + (size_t)(t + 1) * kstep;
;             const char* a2 = last ? nA : cA + (size_t)(t + 2) * kstep; const char* b2 = last ? nB : cB + (size_t)(t + 2) * kstep;
;             const char* a3 = a2 + kstep; const char* b3 = b2 + kstep;
;             if (last && has_next) S.a_ready(nxt);
;             if constexpr (SP2) {
;             PG8_LDB(B0, 0, 0); PG8_LDB(B1, 0, 1); PG8_SCHED; PG8_LDA(At, 0, 0); PG8_STAGE(PG8_SA(1, 1), a1 + hstep, voffA);
;             PG8_WAIT_V(8); PG8_WAIT_L(0); PG8_BAR; PG8_MMA(0, 0, At, B0); PG8_MMA(0, 1, At, B1); PG8_BAR; PG8_SCHED;
;             PG8_LDA(At, 0, 1); PG8_STAGE(PG8_SB(0, 0), b2, voffB); PG8_STAGE(PG8_SB(0, 1), b2 + hstep, voffB); PG8_STAGE(PG8_SA(0, 0), a2, voffA);
.LBB0_684:
	v_or_b32_e32 v130, 0x10000, v177
	v_add_u32_e32 v134, 0x10400, v177
	v_add_u32_e32 v138, 0x10800, v177
	v_add_u32_e32 v142, 0x10c00, v177
	v_or_b32_e32 v146, 0x14000, v177
	v_add_u32_e32 v157, 0x14400, v177
	ds_read_b128 v[130:133], v130
	ds_read_b128 v[134:137], v134
	ds_read_b128 v[138:141], v138
	ds_read_b128 v[142:145], v142
	ds_read_b128 v[146:149], v146
	ds_read_b128 v[164:167], v157
	v_add_u32_e32 v157, 0x14800, v177
	v_add_u32_e32 v172, 0x14c00, v177
	s_add_i32 s92, s88, 2
	ds_read_b128 v[168:171], v157
	ds_read_b128 v[172:175], v172
	s_add_u32 s93, s86, 0x80
	s_addc_u32 s89, s87, 0
	s_cmp_eq_u32 s20, s88
	s_cselect_b32 s88, s38, s93
	s_cselect_b32 s89, s39, s89
	s_cselect_b32 s95, s85, vcc_hi
	s_cselect_b32 s94, s84, vcc_lo
	v_lshl_add_u64 v[178:179], s[86:87], 0, v[160:161]
	s_add_i32 m0, s17, 0xc000
	ds_read_b128 v[184:187], v176
	ds_read_b128 v[188:191], v176 offset:1024
	ds_read_b128 v[192:195], v176 offset:2048
	ds_read_b128 v[196:199], v176 offset:3072
	ds_read_b128 v[200:203], v176 offset:4096
	ds_read_b128 v[204:207], v176 offset:5120
	ds_read_b128 v[214:217], v176 offset:6144
	ds_read_b128 v[218:221], v176 offset:7168
	global_load_lds_dwordx4 v[178:179], off
	v_lshl_add_u64 v[178:179], s[86:87], 0, v[162:163]
	s_add_i32 m0, s17, 0xe000
	s_nop 0
	global_load_lds_dwordx4 v[178:179], off
	s_waitcnt vmcnt(8)
	s_waitcnt lgkmcnt(0)
	s_barrier
	s_waitcnt lgkmcnt(0)
	v_mfma_f32_16x16x32_bf16 v[126:129], v[130:133], v[184:187], v[126:129]
	v_mfma_f32_16x16x32_bf16 v[126:129], v[134:137], v[188:191], v[126:129]
	v_mfma_f32_16x16x32_bf16 v[122:125], v[138:141], v[184:187], v[122:125]
	v_mfma_f32_16x16x32_bf16 v[122:125], v[142:145], v[188:191], v[122:125]
	v_mfma_f32_16x16x32_bf16 v[110:113], v[130:133], v[192:195], v[110:113]
	v_mfma_f32_16x16x32_bf16 v[110:113], v[134:137], v[196:199], v[110:113]
	v_mfma_f32_16x16x32_bf16 v[106:109], v[138:141], v[192:195], v[106:109]
	v_mfma_f32_16x16x32_bf16 v[106:109], v[142:145], v[196:199], v[106:109]
	v_mfma_f32_16x16x32_bf16 v[94:97], v[130:133], v[200:203], v[94:97]
	v_mfma_f32_16x16x32_bf16 v[94:97], v[134:137], v[204:207], v[94:97]
	v_mfma_f32_16x16x32_bf16 v[90:93], v[138:141], v[200:203], v[90:93]
	v_mfma_f32_16x16x32_bf16 v[90:93], v[142:145], v[204:207], v[90:93]
	v_mfma_f32_16x16x32_bf16 v[78:81], v[130:133], v[214:217], v[78:81]
	v_mfma_f32_16x16x32_bf16 v[78:81], v[134:137], v[218:221], v[78:81]
	v_mfma_f32_16x16x32_bf16 v[74:77], v[138:141], v[214:217], v[74:77]
	v_mfma_f32_16x16x32_bf16 v[74:77], v[142:145], v[218:221], v[74:77]
	v_mfma_f32_16x16x32_bf16 v[118:121], v[146:149], v[184:187], v[118:121]
	v_mfma_f32_16x16x32_bf16 v[118:121], v[164:167], v[188:191], v[118:121]
	v_mfma_f32_16x16x32_bf16 v[114:117], v[168:171], v[184:187], v[114:117]
	v_mfma_f32_16x16x32_bf16 v[114:117], v[172:175], v[188:191], v[114:117]
	v_mfma_f32_16x16x32_bf16 v[102:105], v[146:149], v[192:195], v[102:105]
	v_mfma_f32_16x16x32_bf16 v[102:105], v[164:167], v[196:199], v[102:105]
	v_mfma_f32_16x16x32_bf16 v[98:101], v[168:171], v[192:195], v[98:101]
	v_mfma_f32_16x16x32_bf16 v[98:101], v[172:175], v[196:199], v[98:101]
	v_mfma_f32_16x16x32_bf16 v[86:89], v[146:149], v[200:203], v[86:89]
	v_mfma_f32_16x16x32_bf16 v[86:89], v[164:167], v[204:207], v[86:89]
	v_mfma_f32_16x16x32_bf16 v[82:85], v[168:171], v[200:203], v[82:85]
	v_mfma_f32_16x16x32_bf16 v[82:85], v[172:175], v[204:207], v[82:85]
	v_mfma_f32_16x16x32_bf16 v[70:73], v[146:149], v[214:217], v[70:73]
	v_mfma_f32_16x16x32_bf16 v[70:73], v[164:167], v[218:221], v[70:73]
	v_mfma_f32_16x16x32_bf16 v[66:69], v[168:171], v[214:217], v[66:69]
	v_mfma_f32_16x16x32_bf16 v[66:69], v[172:175], v[218:221], v[66:69]
	s_barrier
	s_mov_b32 m0, s26
	v_lshl_add_u64 v[178:179], s[94:95], 0, v[0:1]
	v_lshl_add_u64 v[180:181], s[94:95], 0, v[150:151]
	s_add_u32 s94, s94, s40
	ds_read_b128 v[184:187], v176 offset:16384
	ds_read_b128 v[188:191], v176 offset:17408
	ds_read_b128 v[192:195], v176 offset:18432
	ds_read_b128 v[196:199], v176 offset:19456
	ds_read_b128 v[200:203], v176 offset:20480
	ds_read_b128 v[204:207], v176 offset:21504
	ds_read_b128 v[214:217], v176 offset:22528
	ds_read_b128 v[218:221], v176 offset:23552
	global_load_lds_dwordx4 v[178:179], off
	s_mov_b32 m0, s27
	s_addc_u32 s95, s95, 0
	global_load_lds_dwordx4 v[180:181], off
	v_lshl_add_u64 v[182:183], s[94:95], 0, v[0:1]
	s_mov_b32 m0, s34
	v_lshl_add_u64 v[222:223], s[94:95], 0, v[150:151]
	global_load_lds_dwordx4 v[182:183], off
	s_mov_b32 m0, s35
	v_lshl_add_u64 v[224:225], s[88:89], 0, v[154:155]
	global_load_lds_dwordx4 v[222:223], off
	s_mov_b32 m0, s17
	v_lshl_add_u64 v[226:227], s[88:89], 0, v[152:153]
	global_load_lds_dwordx4 v[224:225], off
	s_mov_b32 m0, s50
	s_nop 0
	global_load_lds_dwordx4 v[226:227], off
	s_waitcnt vmcnt(8)
	s_waitcnt lgkmcnt(0)
	s_barrier
; #define PG8_STAGE(bufoff, gbase, voff) do { _Pragma("unroll") for (int _i = 0; _i < 2; ++_i) \
;         __builtin_amdgcn_global_load_lds((const unsigned*)((const char*)(gbase) + (voff)[_i]), (PG8_LAS unsigned*)(lds + (bufoff) + ldsw + _i * 8192), 16, 0, 0); } while (0)
; #define PG8_LDA(dst, b, h) do { _Pragma("unroll") for (int m = 0; m < 4; ++m) _Pragma("unroll") for (int k = 0; k < 2; ++k) dst[m][k] = *(const PG8_LAS bf16x8*)(lds + PG8_SA(b, h) + aoff + m * 2048 + k * 1024); } while (0)
; #define PG8_LDB(dst, b, h) do { _Pragma("unroll") for (int n = 0; n < 2; ++n) _Pragma("unroll") for (int k = 0; k < 2; ++k) dst[n][k] = *(const PG8_LAS bf16x8*)(lds + PG8_SB(b, h) + boff + n * 2048 + k * 1024); } while (0)
; #define PG8_MMA(ai, bj, At, Bt) do { __builtin_amdgcn_s_setprio(1); _Pragma("unroll") for (int m = 0; m < 4; ++m) _Pragma("unroll") for (int n = 0; n < 2; ++n) _Pragma("unroll") for (int k = 0; k < 2; ++k) \
;         acc[ai][bj][m][n] = __builtin_amdgcn_mfma_f32_16x16x32_bf16(Bt[n][k], At[m][k], acc[ai][bj][m][n], 0, 0, 0); __builtin_amdgcn_s_setprio(0); } while (0)
; #define PG8_WAIT_V(n) asm volatile("s_waitcnt vmcnt(" #n ")" ::: "memory")
; #define PG8_WAIT_L(n) asm volatile("s_waitcnt lgkmcnt(" #n ")" ::: "memory")
; #define PG8_BAR __builtin_amdgcn_s_barrier()
; #define PG8_SCHED __builtin_amdgcn_sched_barrier(0)
; template <class Epi, class Sched, bool ALIGN_EPI = false, bool SP2 = false>
; __device__ __forceinline__ void gemm_phase(PG8_LAS unsigned char* lds, const Gemm g, const Sched& S, const Epi& E, const int tid) {
;     ...
;             PG8_WAIT_V(8); PG8_WAIT_L(0); PG8_BAR; PG8_MMA(1, 0, At, B0); PG8_MMA(1, 1, At, B1); PG8_BAR; PG8_SCHED;
;             PG8_LDB(B0, 1, 0); PG8_LDB(B1, 1, 1); PG8_SCHED; PG8_LDA(At, 1, 0); PG8_STAGE(PG8_SA(0, 1), a2 + hstep, voffA);
;             PG8_WAIT_V(8); PG8_WAIT_L(0); PG8_BAR; PG8_MMA(0, 0, At, B0); PG8_MMA(0, 1, At, B1); PG8_BAR; PG8_SCHED;
	s_waitcnt lgkmcnt(0)
	v_mfma_f32_16x16x32_bf16 v[62:65], v[130:133], v[184:187], v[62:65]
	v_mfma_f32_16x16x32_bf16 v[62:65], v[134:137], v[188:191], v[62:65]
	v_mfma_f32_16x16x32_bf16 v[58:61], v[138:141], v[184:187], v[58:61]
	v_mfma_f32_16x16x32_bf16 v[58:61], v[142:145], v[188:191], v[58:61]
	v_mfma_f32_16x16x32_bf16 v[46:49], v[130:133], v[192:195], v[46:49]
	v_mfma_f32_16x16x32_bf16 v[46:49], v[134:137], v[196:199], v[46:49]
	v_mfma_f32_16x16x32_bf16 v[42:45], v[138:141], v[192:195], v[42:45]
	v_mfma_f32_16x16x32_bf16 v[42:45], v[142:145], v[196:199], v[42:45]
	v_mfma_f32_16x16x32_bf16 v[30:33], v[130:133], v[200:203], v[30:33]
	v_mfma_f32_16x16x32_bf16 v[30:33], v[134:137], v[204:207], v[30:33]
	v_mfma_f32_16x16x32_bf16 v[26:29], v[138:141], v[200:203], v[26:29]
	v_mfma_f32_16x16x32_bf16 v[26:29], v[142:145], v[204:207], v[26:29]
	v_mfma_f32_16x16x32_bf16 v[14:17], v[130:133], v[214:217], v[14:17]
	v_mfma_f32_16x16x32_bf16 v[14:17], v[134:137], v[218:221], v[14:17]
	v_mfma_f32_16x16x32_bf16 v[10:13], v[138:141], v[214:217], v[10:13]
	v_mfma_f32_16x16x32_bf16 v[10:13], v[142:145], v[218:221], v[10:13]
	v_mfma_f32_16x16x32_bf16 v[54:57], v[146:149], v[184:187], v[54:57]
	v_mfma_f32_16x16x32_bf16 v[54:57], v[164:167], v[188:191], v[54:57]
	v_mfma_f32_16x16x32_bf16 v[50:53], v[168:171], v[184:187], v[50:53]
	v_mfma_f32_16x16x32_bf16 v[50:53], v[172:175], v[188:191], v[50:53]
	v_mfma_f32_16x16x32_bf16 v[38:41], v[146:149], v[192:195], v[38:41]
	v_mfma_f32_16x16x32_bf16 v[38:41], v[164:167], v[196:199], v[38:41]
	v_mfma_f32_16x16x32_bf16 v[34:37], v[168:171], v[192:195], v[34:37]
	v_mfma_f32_16x16x32_bf16 v[34:37], v[172:175], v[196:199], v[34:37]
	v_mfma_f32_16x16x32_bf16 v[22:25], v[146:149], v[200:203], v[22:25]
	v_mfma_f32_16x16x32_bf16 v[22:25], v[164:167], v[204:207], v[22:25]
	v_mfma_f32_16x16x32_bf16 v[18:21], v[168:171], v[200:203], v[18:21]
	v_mfma_f32_16x16x32_bf16 v[18:21], v[172:175], v[204:207], v[18:21]
	v_mfma_f32_16x16x32_bf16 v[6:9], v[146:149], v[214:217], v[6:9]
	v_mfma_f32_16x16x32_bf16 v[6:9], v[164:167], v[218:221], v[6:9]
	v_mfma_f32_16x16x32_bf16 v[2:5], v[168:171], v[214:217], v[2:5]
	v_mfma_f32_16x16x32_bf16 v[2:5], v[172:175], v[218:221], v[2:5]
	s_barrier
	v_or_b32_e32 v130, 0x18000, v177
	v_add_u32_e32 v134, 0x18400, v177
	v_add_u32_e32 v138, 0x18800, v177
	v_add_u32_e32 v142, 0x18c00, v177
	v_or_b32_e32 v146, 0x1c000, v177
	v_add_u32_e32 v157, 0x1c400, v177
	ds_read_b128 v[130:133], v130
	ds_read_b128 v[134:137], v134
	ds_read_b128 v[138:141], v138
	ds_read_b128 v[142:145], v142
	ds_read_b128 v[146:149], v146
	ds_read_b128 v[164:167], v157
	v_add_u32_e32 v157, 0x1c800, v177
	v_add_u32_e32 v172, 0x1cc00, v177
	ds_read_b128 v[168:171], v157
	ds_read_b128 v[172:175], v172
	s_add_u32 s88, s88, s40
	s_addc_u32 s89, s89, 0
	s_mov_b32 m0, s51
	v_lshl_add_u64 v[228:229], s[88:89], 0, v[154:155]
	ds_read_b128 v[184:187], v176 offset:32768
	ds_read_b128 v[188:191], v176 offset:33792
	ds_read_b128 v[192:195], v176 offset:34816
	ds_read_b128 v[196:199], v176 offset:35840
	ds_read_b128 v[200:203], v176 offset:36864
	ds_read_b128 v[204:207], v176 offset:37888
	ds_read_b128 v[214:217], v176 offset:38912
	ds_read_b128 v[218:221], v176 offset:39936
	global_load_lds_dwordx4 v[228:229], off
	v_lshl_add_u64 v[228:229], s[88:89], 0, v[152:153]
	s_mov_b32 m0, s90
	s_nop 0
	global_load_lds_dwordx4 v[228:229], off
	s_waitcnt vmcnt(8)
	s_waitcnt lgkmcnt(0)
	s_barrier
	s_waitcnt lgkmcnt(0)
	v_mfma_f32_16x16x32_bf16 v[126:129], v[130:133], v[184:187], v[126:129]
	v_mfma_f32_16x16x32_bf16 v[126:129], v[134:137], v[188:191], v[126:129]
	v_mfma_f32_16x16x32_bf16 v[122:125], v[138:141], v[184:187], v[122:125]
	v_mfma_f32_16x16x32_bf16 v[122:125], v[142:145], v[188:191], v[122:125]
	v_mfma_f32_16x16x32_bf16 v[110:113], v[130:133], v[192:195], v[110:113]
	v_mfma_f32_16x16x32_bf16 v[110:113], v[134:137], v[196:199], v[110:113]
	v_mfma_f32_16x16x32_bf16 v[106:109], v[138:141], v[192:195], v[106:109]
	v_mfma_f32_16x16x32_bf16 v[106:109], v[142:145], v[196:199], v[106:109]
	v_mfma_f32_16x16x32_bf16 v[94:97], v[130:133], v[200:203], v[94:97]
	v_mfma_f32_16x16x32_bf16 v[94:97], v[134:137], v[204:207], v[94:97]
	v_mfma_f32_16x16x32_bf16 v[90:93], v[138:141], v[200:203], v[90:93]
	v_mfma_f32_16x16x32_bf16 v[90:93], v[142:145], v[204:207], v[90:93]
	v_mfma_f32_16x16x32_bf16 v[78:81], v[130:133], v[214:217], v[78:81]
	v_mfma_f32_16x16x32_bf16 v[78:81], v[134:137], v[218:221], v[78:81]
	v_mfma_f32_16x16x32_bf16 v[74:77], v[138:141], v[214:217], v[74:77]
	v_mfma_f32_16x16x32_bf16 v[74:77], v[142:145], v[218:221], v[74:77]
	v_mfma_f32_16x16x32_bf16 v[118:121], v[146:149], v[184:187], v[118:121]
	v_mfma_f32_16x16x32_bf16 v[118:121], v[164:167], v[188:191], v[118:121]
	v_mfma_f32_16x16x32_bf16 v[114:117], v[168:171], v[184:187], v[114:117]
	v_mfma_f32_16x16x32_bf16 v[114:117], v[172:175], v[188:191], v[114:117]
	v_mfma_f32_16x16x32_bf16 v[102:105], v[146:149], v[192:195], v[102:105]
	v_mfma_f32_16x16x32_bf16 v[102:105], v[164:167], v[196:199], v[102:105]
	v_mfma_f32_16x16x32_bf16 v[98:101], v[168:171], v[192:195], v[98:101]
	v_mfma_f32_16x16x32_bf16 v[98:101], v[172:175], v[196:199], v[98:101]
	v_mfma_f32_16x16x32_bf16 v[86:89], v[146:149], v[200:203], v[86:89]
	v_mfma_f32_16x16x32_bf16 v[86:89], v[164:167], v[204:207], v[86:89]
	v_mfma_f32_16x16x32_bf16 v[82:85], v[168:171], v[200:203], v[82:85]
	v_mfma_f32_16x16x32_bf16 v[82:85], v[172:175], v[204:207], v[82:85]
	v_mfma_f32_16x16x32_bf16 v[70:73], v[146:149], v[214:217], v[70:73]
	v_mfma_f32_16x16x32_bf16 v[70:73], v[164:167], v[218:221], v[70:73]
	v_mfma_f32_16x16x32_bf16 v[66:69], v[168:171], v[214:217], v[66:69]
	v_mfma_f32_16x16x32_bf16 v[66:69], v[172:175], v[218:221], v[66:69]
	s_barrier
; #define PG8_STAGE(bufoff, gbase, voff) do { _Pragma("unroll") for (int _i = 0; _i < 2; ++_i) \
;         __builtin_amdgcn_global_load_lds((const unsigned*)((const char*)(gbase) + (voff)[_i]), (PG8_LAS unsigned*)(lds + (bufoff) + ldsw + _i * 8192), 16, 0, 0); } while (0)
; #define PG8_LDA(dst, b, h) do { _Pragma("unroll") for (int m = 0; m < 4; ++m) _Pragma("unroll") for (int k = 0; k < 2; ++k) dst[m][k] = *(const PG8_LAS bf16x8*)(lds + PG8_SA(b, h) + aoff + m * 2048 + k * 1024); } while (0)
; #define PG8_MMA(ai, bj, At, Bt) do { __builtin_amdgcn_s_setprio(1); _Pragma("unroll") for (int m = 0; m < 4; ++m) _Pragma("unroll") for (int n = 0; n < 2; ++n) _Pragma("unroll") for (int k = 0; k < 2; ++k) \
;         acc[ai][bj][m][n] = __builtin_amdgcn_mfma_f32_16x16x32_bf16(Bt[n][k], At[m][k], acc[ai][bj][m][n], 0, 0, 0); __builtin_amdgcn_s_setprio(0); } while (0)
; #define PG8_WAIT_V(n) asm volatile("s_waitcnt vmcnt(" #n ")" ::: "memory")
; #define PG8_WAIT_L(n) asm volatile("s_waitcnt lgkmcnt(" #n ")" ::: "memory")
; #define PG8_BAR __builtin_amdgcn_s_barrier()
; #define PG8_SCHED __builtin_amdgcn_sched_barrier(0)
; template <class Epi, class Sched, bool ALIGN_EPI = false, bool SP2 = false>
; __device__ __forceinline__ void gemm_phase(PG8_LAS unsigned char* lds, const Gemm g, const Sched& S, const Epi& E, const int tid) {
;     ...
;             PG8_LDA(At, 1, 1); PG8_STAGE(PG8_SB(1, 0), b3, voffB); PG8_STAGE(PG8_SB(1, 1), b3 + hstep, voffB); PG8_STAGE(PG8_SA(1, 0), a3, voffA);
;             PG8_WAIT_V(8); PG8_WAIT_L(0); PG8_BAR; PG8_MMA(1, 0, At, B0); PG8_MMA(1, 1, At, B1); PG8_BAR; PG8_SCHED;
	s_mov_b32 m0, s91
	v_lshl_add_u64 v[178:179], v[178:179], 0, s[12:13]
	ds_read_b128 v[184:187], v176 offset:49152
	ds_read_b128 v[188:191], v176 offset:50176
	ds_read_b128 v[192:195], v176 offset:51200
	ds_read_b128 v[196:199], v176 offset:52224
	ds_read_b128 v[200:203], v176 offset:53248
	ds_read_b128 v[204:207], v176 offset:54272
	ds_read_b128 v[214:217], v176 offset:55296
	ds_read_b128 v[218:221], v176 offset:56320
	global_load_lds_dwordx4 v[178:179], off
	v_lshl_add_u64 v[178:179], v[180:181], 0, s[12:13]
	s_mov_b32 m0, s28
	s_nop 0
	global_load_lds_dwordx4 v[178:179], off
	v_lshl_add_u64 v[178:179], v[182:183], 0, s[12:13]
	s_mov_b32 m0, s97
	s_nop 0
	global_load_lds_dwordx4 v[178:179], off
	v_lshl_add_u64 v[178:179], v[222:223], 0, s[12:13]
	s_mov_b32 m0, s15
	s_nop 0
	global_load_lds_dwordx4 v[178:179], off
	v_lshl_add_u64 v[178:179], v[224:225], 0, s[12:13]
	s_mov_b32 m0, s29
	s_nop 0
	global_load_lds_dwordx4 v[178:179], off
	v_lshl_add_u64 v[178:179], v[226:227], 0, s[12:13]
	s_mov_b32 m0, s96
	s_nop 0
	global_load_lds_dwordx4 v[178:179], off
	s_waitcnt vmcnt(8)
	s_waitcnt lgkmcnt(0)
	s_barrier
	s_waitcnt lgkmcnt(0)
	v_mfma_f32_16x16x32_bf16 v[62:65], v[130:133], v[184:187], v[62:65]
	v_mfma_f32_16x16x32_bf16 v[62:65], v[134:137], v[188:191], v[62:65]
	v_mfma_f32_16x16x32_bf16 v[58:61], v[138:141], v[184:187], v[58:61]
	v_mfma_f32_16x16x32_bf16 v[58:61], v[142:145], v[188:191], v[58:61]
	v_mfma_f32_16x16x32_bf16 v[46:49], v[130:133], v[192:195], v[46:49]
	v_mfma_f32_16x16x32_bf16 v[46:49], v[134:137], v[196:199], v[46:49]
	v_mfma_f32_16x16x32_bf16 v[42:45], v[138:141], v[192:195], v[42:45]
	v_mfma_f32_16x16x32_bf16 v[42:45], v[142:145], v[196:199], v[42:45]
	v_mfma_f32_16x16x32_bf16 v[30:33], v[130:133], v[200:203], v[30:33]
	v_mfma_f32_16x16x32_bf16 v[30:33], v[134:137], v[204:207], v[30:33]
	v_mfma_f32_16x16x32_bf16 v[26:29], v[138:141], v[200:203], v[26:29]
	v_mfma_f32_16x16x32_bf16 v[26:29], v[142:145], v[204:207], v[26:29]
	v_mfma_f32_16x16x32_bf16 v[14:17], v[130:133], v[214:217], v[14:17]
	v_mfma_f32_16x16x32_bf16 v[14:17], v[134:137], v[218:221], v[14:17]
	v_mfma_f32_16x16x32_bf16 v[10:13], v[138:141], v[214:217], v[10:13]
	v_mfma_f32_16x16x32_bf16 v[10:13], v[142:145], v[218:221], v[10:13]
	v_mfma_f32_16x16x32_bf16 v[54:57], v[146:149], v[184:187], v[54:57]
	v_mfma_f32_16x16x32_bf16 v[54:57], v[164:167], v[188:191], v[54:57]
	v_mfma_f32_16x16x32_bf16 v[50:53], v[168:171], v[184:187], v[50:53]
	v_mfma_f32_16x16x32_bf16 v[50:53], v[172:175], v[188:191], v[50:53]
	v_mfma_f32_16x16x32_bf16 v[38:41], v[146:149], v[192:195], v[38:41]
	v_mfma_f32_16x16x32_bf16 v[38:41], v[164:167], v[196:199], v[38:41]
	v_mfma_f32_16x16x32_bf16 v[34:37], v[168:171], v[192:195], v[34:37]
	v_mfma_f32_16x16x32_bf16 v[34:37], v[172:175], v[196:199], v[34:37]
	v_mfma_f32_16x16x32_bf16 v[22:25], v[146:149], v[200:203], v[22:25]
	v_mfma_f32_16x16x32_bf16 v[22:25], v[164:167], v[204:207], v[22:25]
	v_mfma_f32_16x16x32_bf16 v[18:21], v[168:171], v[200:203], v[18:21]
	v_mfma_f32_16x16x32_bf16 v[18:21], v[172:175], v[204:207], v[18:21]
	v_mfma_f32_16x16x32_bf16 v[6:9], v[146:149], v[214:217], v[6:9]
	v_mfma_f32_16x16x32_bf16 v[6:9], v[164:167], v[218:221], v[6:9]
	v_mfma_f32_16x16x32_bf16 v[2:5], v[168:171], v[214:217], v[2:5]
	v_mfma_f32_16x16x32_bf16 v[2:5], v[172:175], v[218:221], v[2:5]
	s_barrier
	s_add_u32 s86, s86, 0x100
	s_addc_u32 s87, s87, 0
	s_add_u32 vcc_lo, vcc_lo, 0x100
	s_addc_u32 vcc_hi, vcc_hi, 0
	s_cmp_ge_u32 s92, s2
	s_mov_b32 s88, s92
	s_cbranch_scc0 .LBB0_684
	s_and_b64 vcc, exec, s[30:31]
	s_cbranch_vccz .LBB0_687
	s_barrier

; #define PG8_STAGE(bufoff, gbase, voff) do { _Pragma("unroll") for (int _i = 0; _i < 2; ++_i) \
;         __builtin_amdgcn_global_load_lds((const unsigned*)((const char*)(gbase) + (voff)[_i]), (PG8_LAS unsigned*)(lds + (bufoff) + ldsw + _i * 8192), 16, 0, 0); } while (0)
; #define PG8_LDA(dst, b, h) do { _Pragma("unroll") for (int m = 0; m < 4; ++m) _Pragma("unroll") for (int k = 0; k < 2; ++k) dst[m][k] = *(const PG8_LAS bf16x8*)(lds + PG8_SA(b, h) + aoff + m * 2048 + k * 1024); } while (0)
; #define PG8_LDB(dst, b, h) do { _Pragma("unroll") for (int n = 0; n < 2; ++n) _Pragma("unroll") for (int k = 0; k < 2; ++k) dst[n][k] = *(const PG8_LAS bf16x8*)(lds + PG8_SB(b, h) + boff + n * 2048 + k * 1024); } while (0)
; #define PG8_MMA(ai, bj, At, Bt) do { __builtin_amdgcn_s_setprio(1); _Pragma("unroll") for (int m = 0; m < 4; ++m) _Pragma("unroll") for (int n = 0; n < 2; ++n) _Pragma("unroll") for (int k = 0; k < 2; ++k) \
;         acc[ai][bj][m][n] = __builtin_amdgcn_mfma_f32_16x16x32_bf16(Bt[n][k], At[m][k], acc[ai][bj][m][n], 0, 0, 0); __builtin_amdgcn_s_setprio(0); } while (0)
; #define PG8_WAIT_V(n) asm volatile("s_waitcnt vmcnt(" #n ")" ::: "memory")
; #define PG8_WAIT_L(n) asm volatile("s_waitcnt lgkmcnt(" #n ")" ::: "memory")
; template <class Epi, class Sched, bool ALIGN_EPI = false, bool SP2 = false>
; __device__ __forceinline__ void gemm_phase(PG8_LAS unsigned char* lds, const Gemm g, const Sched& S, const Epi& E, const int tid) {
;     ...
;             const bool last = (t == nt - 2);
;             const char* a1 = cA + (size_t)(t + 1) * kstep;
;             const char* a2 = last ? nA : cA + (size_t)(t + 2) * kstep; const char* b2 = last ? nB : cB + (size_t)(t + 2) * kstep;
;             const char* a3 = a2 + kstep; const char* b3 = b2 + kstep;
;             if (last && has_next) S.a_ready(nxt);
;             if constexpr (SP2) {
;             PG8_LDB(B0, 0, 0); PG8_LDB(B1, 0, 1); PG8_SCHED; PG8_LDA(At, 0, 0); PG8_STAGE(PG8_SA(1, 1), a1 + hstep, voffA);
;             PG8_WAIT_V(8); PG8_WAIT_L(0); PG8_BAR; PG8_MMA(0, 0, At, B0); PG8_MMA(0, 1, At, B1); PG8_BAR; PG8_SCHED;
;             PG8_LDA(At, 0, 1); PG8_STAGE(PG8_SB(0, 0), b2, voffB); PG8_STAGE(PG8_SB(0, 1), b2 + hstep, voffB); PG8_STAGE(PG8_SA(0, 0), a2, voffA);
;             PG8_WAIT_V(8); PG8_WAIT_L(0); PG8_BAR; PG8_MMA(1, 0, At, B0); PG8_MMA(1, 1, At, B1); PG8_BAR; PG8_SCHED;
.LBB0_695:
	s_add_i32 s42, s41, 2
	s_mov_b32 s43, s7
	s_or_b32 s6, s41, 1
	s_lshl_b64 s[44:45], s[42:43], 7
	v_or_b32_e32 v138, 0x10000, v137
	v_add_u32_e32 v142, 0x10400, v137
	v_add_u32_e32 v146, 0x10800, v137
	v_add_u32_e32 v150, 0x10c00, v137
	v_or_b32_e32 v154, 0x14000, v137
	v_add_u32_e32 v158, 0x14400, v137
	v_add_u32_e32 v162, 0x14800, v137
	v_add_u32_e32 v166, 0x14c00, v137
	s_cmp_lg_u32 s41, s35
	ds_read_b128 v[138:141], v138
	ds_read_b128 v[142:145], v142
	ds_read_b128 v[146:149], v146
	ds_read_b128 v[150:153], v150
	ds_read_b128 v[154:157], v154
	ds_read_b128 v[158:161], v158
	ds_read_b128 v[162:165], v162
	ds_read_b128 v[166:169], v166
	s_cselect_b32 s43, s44, 0
	s_cselect_b32 s41, s45, 0
	s_add_u32 s44, s36, s43
	s_addc_u32 s45, s37, s41
	s_add_u32 s46, s30, s43
	s_addc_u32 s47, s31, s41
	s_lshl_b64 s[50:51], s[6:7], 7
	s_add_u32 s50, s38, s50
	s_addc_u32 s51, s39, s51
	v_lshl_add_u64 v[178:179], s[50:51], 0, v[134:135]
	s_add_i32 m0, s4, 0xc000
	ds_read_b128 v[170:173], v136
	ds_read_b128 v[174:177], v136 offset:1024
	ds_read_b128 v[184:187], v136 offset:2048
	ds_read_b128 v[188:191], v136 offset:3072
	ds_read_b128 v[192:195], v136 offset:4096
	ds_read_b128 v[196:199], v136 offset:5120
	ds_read_b128 v[200:203], v136 offset:6144
	ds_read_b128 v[204:207], v136 offset:7168
	global_load_lds_dwordx4 v[178:179], off
	v_lshl_add_u64 v[178:179], s[50:51], 0, v[132:133]
	s_add_i32 m0, s4, 0xe000
	s_nop 0
	global_load_lds_dwordx4 v[178:179], off
	s_waitcnt vmcnt(8)
	s_waitcnt lgkmcnt(0)
	s_barrier
	s_waitcnt lgkmcnt(0)
	v_mfma_f32_16x16x32_bf16 v[126:129], v[138:141], v[170:173], v[126:129]
	v_mfma_f32_16x16x32_bf16 v[126:129], v[142:145], v[174:177], v[126:129]
	v_mfma_f32_16x16x32_bf16 v[122:125], v[146:149], v[170:173], v[122:125]
	v_mfma_f32_16x16x32_bf16 v[122:125], v[150:153], v[174:177], v[122:125]
	v_mfma_f32_16x16x32_bf16 v[118:121], v[138:141], v[184:187], v[118:121]
	v_mfma_f32_16x16x32_bf16 v[118:121], v[142:145], v[188:191], v[118:121]
	v_mfma_f32_16x16x32_bf16 v[114:117], v[146:149], v[184:187], v[114:117]
	v_mfma_f32_16x16x32_bf16 v[114:117], v[150:153], v[188:191], v[114:117]
	v_mfma_f32_16x16x32_bf16 v[106:109], v[138:141], v[192:195], v[106:109]
	v_mfma_f32_16x16x32_bf16 v[106:109], v[142:145], v[196:199], v[106:109]
	v_mfma_f32_16x16x32_bf16 v[98:101], v[146:149], v[192:195], v[98:101]
	v_mfma_f32_16x16x32_bf16 v[98:101], v[150:153], v[196:199], v[98:101]
	v_mfma_f32_16x16x32_bf16 v[90:93], v[138:141], v[200:203], v[90:93]
	v_mfma_f32_16x16x32_bf16 v[90:93], v[142:145], v[204:207], v[90:93]
	v_mfma_f32_16x16x32_bf16 v[82:85], v[146:149], v[200:203], v[82:85]
	v_mfma_f32_16x16x32_bf16 v[82:85], v[150:153], v[204:207], v[82:85]
	v_mfma_f32_16x16x32_bf16 v[110:113], v[154:157], v[170:173], v[110:113]
	v_mfma_f32_16x16x32_bf16 v[110:113], v[158:161], v[174:177], v[110:113]
	v_mfma_f32_16x16x32_bf16 v[102:105], v[162:165], v[170:173], v[102:105]
	v_mfma_f32_16x16x32_bf16 v[102:105], v[166:169], v[174:177], v[102:105]
	v_mfma_f32_16x16x32_bf16 v[94:97], v[154:157], v[184:187], v[94:97]
	v_mfma_f32_16x16x32_bf16 v[94:97], v[158:161], v[188:191], v[94:97]
	v_mfma_f32_16x16x32_bf16 v[86:89], v[162:165], v[184:187], v[86:89]
	v_mfma_f32_16x16x32_bf16 v[86:89], v[166:169], v[188:191], v[86:89]
	v_mfma_f32_16x16x32_bf16 v[78:81], v[154:157], v[192:195], v[78:81]
	v_mfma_f32_16x16x32_bf16 v[78:81], v[158:161], v[196:199], v[78:81]
	v_mfma_f32_16x16x32_bf16 v[74:77], v[162:165], v[192:195], v[74:77]
	v_mfma_f32_16x16x32_bf16 v[74:77], v[166:169], v[196:199], v[74:77]
	v_mfma_f32_16x16x32_bf16 v[70:73], v[154:157], v[200:203], v[70:73]
	v_mfma_f32_16x16x32_bf16 v[70:73], v[158:161], v[204:207], v[70:73]
	v_mfma_f32_16x16x32_bf16 v[66:69], v[162:165], v[200:203], v[66:69]
	v_mfma_f32_16x16x32_bf16 v[66:69], v[166:169], v[204:207], v[66:69]
	s_barrier
	s_mov_b32 m0, s0
	v_lshl_add_u64 v[178:179], s[46:47], 0, v[0:1]
	v_lshl_add_u64 v[180:181], s[46:47], 0, v[130:131]
	s_add_u32 s46, s46, s40
	ds_read_b128 v[170:173], v136 offset:16384
	ds_read_b128 v[174:177], v136 offset:17408
	ds_read_b128 v[184:187], v136 offset:18432
	ds_read_b128 v[188:191], v136 offset:19456
	ds_read_b128 v[192:195], v136 offset:20480
	ds_read_b128 v[196:199], v136 offset:21504
	ds_read_b128 v[200:203], v136 offset:22528
	ds_read_b128 v[204:207], v136 offset:23552
	global_load_lds_dwordx4 v[178:179], off
	s_mov_b32 m0, s1
	s_addc_u32 s47, s47, 0
	global_load_lds_dwordx4 v[180:181], off
	v_lshl_add_u64 v[182:183], s[46:47], 0, v[0:1]
	s_mov_b32 m0, s5
	v_lshl_add_u64 v[214:215], s[46:47], 0, v[130:131]
	global_load_lds_dwordx4 v[182:183], off
	s_mov_b32 m0, s8
	v_lshl_add_u64 v[216:217], s[44:45], 0, v[134:135]
	global_load_lds_dwordx4 v[214:215], off
	s_mov_b32 m0, s4
	v_lshl_add_u64 v[218:219], s[44:45], 0, v[132:133]
	global_load_lds_dwordx4 v[216:217], off
	s_mov_b32 m0, s9
	s_nop 0
	global_load_lds_dwordx4 v[218:219], off
	s_waitcnt vmcnt(8)
	s_waitcnt lgkmcnt(0)
	s_barrier
; #define PG8_STAGE(bufoff, gbase, voff) do { _Pragma("unroll") for (int _i = 0; _i < 2; ++_i) \
;         __builtin_amdgcn_global_load_lds((const unsigned*)((const char*)(gbase) + (voff)[_i]), (PG8_LAS unsigned*)(lds + (bufoff) + ldsw + _i * 8192), 16, 0, 0); } while (0)
; #define PG8_LDA(dst, b, h) do { _Pragma("unroll") for (int m = 0; m < 4; ++m) _Pragma("unroll") for (int k = 0; k < 2; ++k) dst[m][k] = *(const PG8_LAS bf16x8*)(lds + PG8_SA(b, h) + aoff + m * 2048 + k * 1024); } while (0)
; #define PG8_LDB(dst, b, h) do { _Pragma("unroll") for (int n = 0; n < 2; ++n) _Pragma("unroll") for (int k = 0; k < 2; ++k) dst[n][k] = *(const PG8_LAS bf16x8*)(lds + PG8_SB(b, h) + boff + n * 2048 + k * 1024); } while (0)
; #define PG8_MMA(ai, bj, At, Bt) do { __builtin_amdgcn_s_setprio(1); _Pragma("unroll") for (int m = 0; m < 4; ++m) _Pragma("unroll") for (int n = 0; n < 2; ++n) _Pragma("unroll") for (int k = 0; k < 2; ++k) \
;         acc[ai][bj][m][n] = __builtin_amdgcn_mfma_f32_16x16x32_bf16(Bt[n][k], At[m][k], acc[ai][bj][m][n], 0, 0, 0); __builtin_amdgcn_s_setprio(0); } while (0)
; #define PG8_WAIT_V(n) asm volatile("s_waitcnt vmcnt(" #n ")" ::: "memory")
; #define PG8_WAIT_L(n) asm volatile("s_waitcnt lgkmcnt(" #n ")" ::: "memory")
; #define PG8_BAR __builtin_amdgcn_s_barrier()
; #define PG8_SCHED __builtin_amdgcn_sched_barrier(0)
; template <class Epi, class Sched, bool ALIGN_EPI = false, bool SP2 = false>
; __device__ __forceinline__ void gemm_phase(PG8_LAS unsigned char* lds, const Gemm g, const Sched& S, const Epi& E, const int tid) {
;     ...
;             PG8_WAIT_V(8); PG8_WAIT_L(0); PG8_BAR; PG8_MMA(1, 0, At, B0); PG8_MMA(1, 1, At, B1); PG8_BAR; PG8_SCHED;
;             PG8_LDB(B0, 1, 0); PG8_LDB(B1, 1, 1); PG8_SCHED; PG8_LDA(At, 1, 0); PG8_STAGE(PG8_SA(0, 1), a2 + hstep, voffA);
;             PG8_WAIT_V(8); PG8_WAIT_L(0); PG8_BAR; PG8_MMA(0, 0, At, B0); PG8_MMA(0, 1, At, B1); PG8_BAR; PG8_SCHED;
	s_waitcnt lgkmcnt(0)
	v_mfma_f32_16x16x32_bf16 v[62:65], v[138:141], v[170:173], v[62:65]
	v_mfma_f32_16x16x32_bf16 v[62:65], v[142:145], v[174:177], v[62:65]
	v_mfma_f32_16x16x32_bf16 v[58:61], v[146:149], v[170:173], v[58:61]
	v_mfma_f32_16x16x32_bf16 v[58:61], v[150:153], v[174:177], v[58:61]
	v_mfma_f32_16x16x32_bf16 v[54:57], v[138:141], v[184:187], v[54:57]
	v_mfma_f32_16x16x32_bf16 v[54:57], v[142:145], v[188:191], v[54:57]
	v_mfma_f32_16x16x32_bf16 v[50:53], v[146:149], v[184:187], v[50:53]
	v_mfma_f32_16x16x32_bf16 v[50:53], v[150:153], v[188:191], v[50:53]
	v_mfma_f32_16x16x32_bf16 v[38:41], v[138:141], v[192:195], v[38:41]
	v_mfma_f32_16x16x32_bf16 v[38:41], v[142:145], v[196:199], v[38:41]
	v_mfma_f32_16x16x32_bf16 v[34:37], v[146:149], v[192:195], v[34:37]
	v_mfma_f32_16x16x32_bf16 v[34:37], v[150:153], v[196:199], v[34:37]
	v_mfma_f32_16x16x32_bf16 v[22:25], v[138:141], v[200:203], v[22:25]
	v_mfma_f32_16x16x32_bf16 v[22:25], v[142:145], v[204:207], v[22:25]
	v_mfma_f32_16x16x32_bf16 v[18:21], v[146:149], v[200:203], v[18:21]
	v_mfma_f32_16x16x32_bf16 v[18:21], v[150:153], v[204:207], v[18:21]
	v_mfma_f32_16x16x32_bf16 v[46:49], v[154:157], v[170:173], v[46:49]
	v_mfma_f32_16x16x32_bf16 v[46:49], v[158:161], v[174:177], v[46:49]
	v_mfma_f32_16x16x32_bf16 v[42:45], v[162:165], v[170:173], v[42:45]
	v_mfma_f32_16x16x32_bf16 v[42:45], v[166:169], v[174:177], v[42:45]
	v_mfma_f32_16x16x32_bf16 v[30:33], v[154:157], v[184:187], v[30:33]
	v_mfma_f32_16x16x32_bf16 v[30:33], v[158:161], v[188:191], v[30:33]
	v_mfma_f32_16x16x32_bf16 v[26:29], v[162:165], v[184:187], v[26:29]
	v_mfma_f32_16x16x32_bf16 v[26:29], v[166:169], v[188:191], v[26:29]
	v_mfma_f32_16x16x32_bf16 v[14:17], v[154:157], v[192:195], v[14:17]
	v_mfma_f32_16x16x32_bf16 v[14:17], v[158:161], v[196:199], v[14:17]
	v_mfma_f32_16x16x32_bf16 v[10:13], v[162:165], v[192:195], v[10:13]
	v_mfma_f32_16x16x32_bf16 v[10:13], v[166:169], v[196:199], v[10:13]
	v_mfma_f32_16x16x32_bf16 v[6:9], v[154:157], v[200:203], v[6:9]
	v_mfma_f32_16x16x32_bf16 v[6:9], v[158:161], v[204:207], v[6:9]
	v_mfma_f32_16x16x32_bf16 v[2:5], v[162:165], v[200:203], v[2:5]
	v_mfma_f32_16x16x32_bf16 v[2:5], v[166:169], v[204:207], v[2:5]
	s_barrier
	v_or_b32_e32 v138, 0x18000, v137
	v_add_u32_e32 v142, 0x18400, v137
	v_add_u32_e32 v146, 0x18800, v137
	v_add_u32_e32 v150, 0x18c00, v137
	v_or_b32_e32 v154, 0x1c000, v137
	v_add_u32_e32 v158, 0x1c400, v137
	v_add_u32_e32 v162, 0x1c800, v137
	v_add_u32_e32 v166, 0x1cc00, v137
	ds_read_b128 v[138:141], v138
	ds_read_b128 v[142:145], v142
	ds_read_b128 v[146:149], v146
	ds_read_b128 v[150:153], v150
	ds_read_b128 v[154:157], v154
	ds_read_b128 v[158:161], v158
	ds_read_b128 v[162:165], v162
	ds_read_b128 v[166:169], v166
	s_add_u32 s44, s44, s40
	s_addc_u32 s45, s45, 0
	s_mov_b32 m0, s14
	v_lshl_add_u64 v[220:221], s[44:45], 0, v[134:135]
	ds_read_b128 v[170:173], v136 offset:32768
	ds_read_b128 v[174:177], v136 offset:33792
	ds_read_b128 v[184:187], v136 offset:34816
	ds_read_b128 v[188:191], v136 offset:35840
	ds_read_b128 v[192:195], v136 offset:36864
	ds_read_b128 v[196:199], v136 offset:37888
	ds_read_b128 v[200:203], v136 offset:38912
	ds_read_b128 v[204:207], v136 offset:39936
	global_load_lds_dwordx4 v[220:221], off
	v_lshl_add_u64 v[220:221], s[44:45], 0, v[132:133]
	s_mov_b32 m0, s15
	s_nop 0
	global_load_lds_dwordx4 v[220:221], off
	s_waitcnt vmcnt(8)
	s_waitcnt lgkmcnt(0)
	s_barrier
	s_waitcnt lgkmcnt(0)
	v_mfma_f32_16x16x32_bf16 v[126:129], v[138:141], v[170:173], v[126:129]
	v_mfma_f32_16x16x32_bf16 v[126:129], v[142:145], v[174:177], v[126:129]
	v_mfma_f32_16x16x32_bf16 v[122:125], v[146:149], v[170:173], v[122:125]
	v_mfma_f32_16x16x32_bf16 v[122:125], v[150:153], v[174:177], v[122:125]
	v_mfma_f32_16x16x32_bf16 v[118:121], v[138:141], v[184:187], v[118:121]
	v_mfma_f32_16x16x32_bf16 v[118:121], v[142:145], v[188:191], v[118:121]
	v_mfma_f32_16x16x32_bf16 v[114:117], v[146:149], v[184:187], v[114:117]
	v_mfma_f32_16x16x32_bf16 v[114:117], v[150:153], v[188:191], v[114:117]
	v_mfma_f32_16x16x32_bf16 v[106:109], v[138:141], v[192:195], v[106:109]
	v_mfma_f32_16x16x32_bf16 v[106:109], v[142:145], v[196:199], v[106:109]
	v_mfma_f32_16x16x32_bf16 v[98:101], v[146:149], v[192:195], v[98:101]
	v_mfma_f32_16x16x32_bf16 v[98:101], v[150:153], v[196:199], v[98:101]
	v_mfma_f32_16x16x32_bf16 v[90:93], v[138:141], v[200:203], v[90:93]
	v_mfma_f32_16x16x32_bf16 v[90:93], v[142:145], v[204:207], v[90:93]
	v_mfma_f32_16x16x32_bf16 v[82:85], v[146:149], v[200:203], v[82:85]
	v_mfma_f32_16x16x32_bf16 v[82:85], v[150:153], v[204:207], v[82:85]
	v_mfma_f32_16x16x32_bf16 v[110:113], v[154:157], v[170:173], v[110:113]
	v_mfma_f32_16x16x32_bf16 v[110:113], v[158:161], v[174:177], v[110:113]
	v_mfma_f32_16x16x32_bf16 v[102:105], v[162:165], v[170:173], v[102:105]
	v_mfma_f32_16x16x32_bf16 v[102:105], v[166:169], v[174:177], v[102:105]
	v_mfma_f32_16x16x32_bf16 v[94:97], v[154:157], v[184:187], v[94:97]
	v_mfma_f32_16x16x32_bf16 v[94:97], v[158:161], v[188:191], v[94:97]
	v_mfma_f32_16x16x32_bf16 v[86:89], v[162:165], v[184:187], v[86:89]
	v_mfma_f32_16x16x32_bf16 v[86:89], v[166:169], v[188:191], v[86:89]
	v_mfma_f32_16x16x32_bf16 v[78:81], v[154:157], v[192:195], v[78:81]
	v_mfma_f32_16x16x32_bf16 v[78:81], v[158:161], v[196:199], v[78:81]
	v_mfma_f32_16x16x32_bf16 v[74:77], v[162:165], v[192:195], v[74:77]
	v_mfma_f32_16x16x32_bf16 v[74:77], v[166:169], v[196:199], v[74:77]
	v_mfma_f32_16x16x32_bf16 v[70:73], v[154:157], v[200:203], v[70:73]
	v_mfma_f32_16x16x32_bf16 v[70:73], v[158:161], v[204:207], v[70:73]
	v_mfma_f32_16x16x32_bf16 v[66:69], v[162:165], v[200:203], v[66:69]
	v_mfma_f32_16x16x32_bf16 v[66:69], v[166:169], v[204:207], v[66:69]
	s_barrier
; #define PG8_STAGE(bufoff, gbase, voff) do { _Pragma("unroll") for (int _i = 0; _i < 2; ++_i) \
;         __builtin_amdgcn_global_load_lds((const unsigned*)((const char*)(gbase) + (voff)[_i]), (PG8_LAS unsigned*)(lds + (bufoff) + ldsw + _i * 8192), 16, 0, 0); } while (0)
; #define PG8_LDA(dst, b, h) do { _Pragma("unroll") for (int m = 0; m < 4; ++m) _Pragma("unroll") for (int k = 0; k < 2; ++k) dst[m][k] = *(const PG8_LAS bf16x8*)(lds + PG8_SA(b, h) + aoff + m * 2048 + k * 1024); } while (0)
; #define PG8_MMA(ai, bj, At, Bt) do { __builtin_amdgcn_s_setprio(1); _Pragma("unroll") for (int m = 0; m < 4; ++m) _Pragma("unroll") for (int n = 0; n < 2; ++n) _Pragma("unroll") for (int k = 0; k < 2; ++k) \
;         acc[ai][bj][m][n] = __builtin_amdgcn_mfma_f32_16x16x32_bf16(Bt[n][k], At[m][k], acc[ai][bj][m][n], 0, 0, 0); __builtin_amdgcn_s_setprio(0); } while (0)
; #define PG8_WAIT_V(n) asm volatile("s_waitcnt vmcnt(" #n ")" ::: "memory")
; #define PG8_WAIT_L(n) asm volatile("s_waitcnt lgkmcnt(" #n ")" ::: "memory")
; #define PG8_BAR __builtin_amdgcn_s_barrier()
; #define PG8_SCHED __builtin_amdgcn_sched_barrier(0)
; template <class Epi, class Sched, bool ALIGN_EPI = false, bool SP2 = false>
; __device__ __forceinline__ void gemm_phase(PG8_LAS unsigned char* lds, const Gemm g, const Sched& S, const Epi& E, const int tid) {
;     ...
;             PG8_LDA(At, 1, 1); PG8_STAGE(PG8_SB(1, 0), b3, voffB); PG8_STAGE(PG8_SB(1, 1), b3 + hstep, voffB); PG8_STAGE(PG8_SA(1, 0), a3, voffA);
;             PG8_WAIT_V(8); PG8_WAIT_L(0); PG8_BAR; PG8_MMA(1, 0, At, B0); PG8_MMA(1, 1, At, B1); PG8_BAR; PG8_SCHED;
	s_mov_b32 m0, s24
	v_lshl_add_u64 v[178:179], v[178:179], 0, s[12:13]
	ds_read_b128 v[170:173], v136 offset:49152
	ds_read_b128 v[174:177], v136 offset:50176
	ds_read_b128 v[184:187], v136 offset:51200
	ds_read_b128 v[188:191], v136 offset:52224
	ds_read_b128 v[192:195], v136 offset:53248
	ds_read_b128 v[196:199], v136 offset:54272
	ds_read_b128 v[200:203], v136 offset:55296
	ds_read_b128 v[204:207], v136 offset:56320
	global_load_lds_dwordx4 v[178:179], off
	v_lshl_add_u64 v[178:179], v[180:181], 0, s[12:13]
	s_mov_b32 m0, s26
	s_nop 0
	global_load_lds_dwordx4 v[178:179], off
	v_lshl_add_u64 v[178:179], v[182:183], 0, s[12:13]
	s_mov_b32 m0, s29
	s_nop 0
	global_load_lds_dwordx4 v[178:179], off
	v_lshl_add_u64 v[178:179], v[214:215], 0, s[12:13]
	s_mov_b32 m0, s34
	s_nop 0
	global_load_lds_dwordx4 v[178:179], off
	v_lshl_add_u64 v[178:179], v[216:217], 0, s[12:13]
	s_mov_b32 m0, s27
	s_nop 0
	global_load_lds_dwordx4 v[178:179], off
	v_lshl_add_u64 v[178:179], v[218:219], 0, s[12:13]
	s_mov_b32 m0, s28
	s_nop 0
	global_load_lds_dwordx4 v[178:179], off
	s_waitcnt vmcnt(8)
	s_waitcnt lgkmcnt(0)
	s_barrier
	s_waitcnt lgkmcnt(0)
	v_mfma_f32_16x16x32_bf16 v[62:65], v[138:141], v[170:173], v[62:65]
	v_mfma_f32_16x16x32_bf16 v[62:65], v[142:145], v[174:177], v[62:65]
	v_mfma_f32_16x16x32_bf16 v[58:61], v[146:149], v[170:173], v[58:61]
	v_mfma_f32_16x16x32_bf16 v[58:61], v[150:153], v[174:177], v[58:61]
	v_mfma_f32_16x16x32_bf16 v[54:57], v[138:141], v[184:187], v[54:57]
	v_mfma_f32_16x16x32_bf16 v[54:57], v[142:145], v[188:191], v[54:57]
	v_mfma_f32_16x16x32_bf16 v[50:53], v[146:149], v[184:187], v[50:53]
	v_mfma_f32_16x16x32_bf16 v[50:53], v[150:153], v[188:191], v[50:53]
	v_mfma_f32_16x16x32_bf16 v[38:41], v[138:141], v[192:195], v[38:41]
	v_mfma_f32_16x16x32_bf16 v[38:41], v[142:145], v[196:199], v[38:41]
	v_mfma_f32_16x16x32_bf16 v[34:37], v[146:149], v[192:195], v[34:37]
	v_mfma_f32_16x16x32_bf16 v[34:37], v[150:153], v[196:199], v[34:37]
	v_mfma_f32_16x16x32_bf16 v[22:25], v[138:141], v[200:203], v[22:25]
	v_mfma_f32_16x16x32_bf16 v[22:25], v[142:145], v[204:207], v[22:25]
	v_mfma_f32_16x16x32_bf16 v[18:21], v[146:149], v[200:203], v[18:21]
	v_mfma_f32_16x16x32_bf16 v[18:21], v[150:153], v[204:207], v[18:21]
	v_mfma_f32_16x16x32_bf16 v[46:49], v[154:157], v[170:173], v[46:49]
	v_mfma_f32_16x16x32_bf16 v[46:49], v[158:161], v[174:177], v[46:49]
	v_mfma_f32_16x16x32_bf16 v[42:45], v[162:165], v[170:173], v[42:45]
	v_mfma_f32_16x16x32_bf16 v[42:45], v[166:169], v[174:177], v[42:45]
	v_mfma_f32_16x16x32_bf16 v[30:33], v[154:157], v[184:187], v[30:33]
	v_mfma_f32_16x16x32_bf16 v[30:33], v[158:161], v[188:191], v[30:33]
	v_mfma_f32_16x16x32_bf16 v[26:29], v[162:165], v[184:187], v[26:29]
	v_mfma_f32_16x16x32_bf16 v[26:29], v[166:169], v[188:191], v[26:29]
	v_mfma_f32_16x16x32_bf16 v[14:17], v[154:157], v[192:195], v[14:17]
	v_mfma_f32_16x16x32_bf16 v[14:17], v[158:161], v[196:199], v[14:17]
	v_mfma_f32_16x16x32_bf16 v[10:13], v[162:165], v[192:195], v[10:13]
	v_mfma_f32_16x16x32_bf16 v[10:13], v[166:169], v[196:199], v[10:13]
	v_mfma_f32_16x16x32_bf16 v[6:9], v[154:157], v[200:203], v[6:9]
	v_mfma_f32_16x16x32_bf16 v[6:9], v[158:161], v[204:207], v[6:9]
	v_mfma_f32_16x16x32_bf16 v[2:5], v[162:165], v[200:203], v[2:5]
	v_mfma_f32_16x16x32_bf16 v[2:5], v[166:169], v[204:207], v[2:5]
	s_barrier
	s_cmp_ge_u32 s42, s21
	s_mov_b32 s41, s42
	s_cbranch_scc0 .LBB0_695
	v_readlane_b32 s26, v254, 47
	v_readlane_b32 s28, v254, 49
	s_cmpk_lt_u32 s2, 0x100
	v_readlane_b32 s27, v254, 48
	v_readlane_b32 s29, v254, 50
	s_cbranch_scc0 .LBB0_698
	s_barrier

; #define PG8_STAGE(bufoff, gbase, voff) do { _Pragma("unroll") for (int _i = 0; _i < 2; ++_i) \
;         __builtin_amdgcn_global_load_lds((const unsigned*)((const char*)(gbase) + (voff)[_i]), (PG8_LAS unsigned*)(lds + (bufoff) + ldsw + _i * 8192), 16, 0, 0); } while (0)
; #define PG8_LDA(dst, b, h) do { _Pragma("unroll") for (int m = 0; m < 4; ++m) _Pragma("unroll") for (int k = 0; k < 2; ++k) dst[m][k] = *(const PG8_LAS bf16x8*)(lds + PG8_SA(b, h) + aoff + m * 2048 + k * 1024); } while (0)
; #define PG8_LDB(dst, b, h) do { _Pragma("unroll") for (int n = 0; n < 2; ++n) _Pragma("unroll") for (int k = 0; k < 2; ++k) dst[n][k] = *(const PG8_LAS bf16x8*)(lds + PG8_SB(b, h) + boff + n * 2048 + k * 1024); } while (0)
; #define PG8_MMA(ai, bj, At, Bt) do { __builtin_amdgcn_s_setprio(1); _Pragma("unroll") for (int m = 0; m < 4; ++m) _Pragma("unroll") for (int n = 0; n < 2; ++n) _Pragma("unroll") for (int k = 0; k < 2; ++k) \
;         acc[ai][bj][m][n] = __builtin_amdgcn_mfma_f32_16x16x32_bf16(Bt[n][k], At[m][k], acc[ai][bj][m][n], 0, 0, 0); __builtin_amdgcn_s_setprio(0); } while (0)
; #define PG8_WAIT_V(n) asm volatile("s_waitcnt vmcnt(" #n ")" ::: "memory")
; #define PG8_WAIT_L(n) asm volatile("s_waitcnt lgkmcnt(" #n ")" ::: "memory")
; template <class Epi, class Sched, bool ALIGN_EPI = false, bool SP2 = false>
; __device__ __forceinline__ void gemm_phase(PG8_LAS unsigned char* lds, const Gemm g, const Sched& S, const Epi& E, const int tid) {
;     ...
;             const bool last = (t == nt - 2);
;             const char* a1 = cA + (size_t)(t + 1) * kstep;
;             const char* a2 = last ? nA : cA + (size_t)(t + 2) * kstep; const char* b2 = last ? nB : cB + (size_t)(t + 2) * kstep;
;             const char* a3 = a2 + kstep; const char* b3 = b2 + kstep;
;             if (last && has_next) S.a_ready(nxt);
;             if constexpr (SP2) {
;             PG8_LDB(B0, 0, 0); PG8_LDB(B1, 0, 1); PG8_SCHED; PG8_LDA(At, 0, 0); PG8_STAGE(PG8_SA(1, 1), a1 + hstep, voffA);
;             PG8_WAIT_V(8); PG8_WAIT_L(0); PG8_BAR; PG8_MMA(0, 0, At, B0); PG8_MMA(0, 1, At, B1); PG8_BAR; PG8_SCHED;
;             PG8_LDA(At, 0, 1); PG8_STAGE(PG8_SB(0, 0), b2, voffB); PG8_STAGE(PG8_SB(0, 1), b2 + hstep, voffB); PG8_STAGE(PG8_SA(0, 0), a2, voffA);
;             PG8_WAIT_V(8); PG8_WAIT_L(0); PG8_BAR; PG8_MMA(1, 0, At, B0); PG8_MMA(1, 1, At, B1); PG8_BAR; PG8_SCHED;
.LBB0_713:
	v_or_b32_e32 v142, 0x10000, v141
	v_add_u32_e32 v146, 0x10400, v141
	v_add_u32_e32 v150, 0x10800, v141
	v_add_u32_e32 v154, 0x10c00, v141
	v_or_b32_e32 v158, 0x14000, v141
	v_add_u32_e32 v162, 0x14400, v141
	v_add_u32_e32 v166, 0x14800, v141
	v_add_u32_e32 v170, 0x14c00, v141
	ds_read_b128 v[142:145], v142
	ds_read_b128 v[146:149], v146
	ds_read_b128 v[150:153], v150
	ds_read_b128 v[154:157], v154
	ds_read_b128 v[158:161], v158
	ds_read_b128 v[162:165], v162
	ds_read_b128 v[166:169], v166
	ds_read_b128 v[170:173], v170
	s_add_u32 s84, s30, 0xfffc0080
	s_addc_u32 s85, s31, -1
	s_cmp_eq_u32 s43, 12
	s_cselect_b32 s87, s5, s85
	s_cselect_b32 s86, s15, s84
	s_cselect_b32 s85, s20, s41
	s_cselect_b32 s84, s21, s24
	v_lshl_add_u64 v[178:179], s[30:31], 0, v[136:137]
	s_add_i32 m0, s1, 0xc000
	ds_read_b128 v[174:177], v140
	ds_read_b128 v[184:187], v140 offset:1024
	ds_read_b128 v[188:191], v140 offset:2048
	ds_read_b128 v[192:195], v140 offset:3072
	ds_read_b128 v[196:199], v140 offset:4096
	ds_read_b128 v[200:203], v140 offset:5120
	ds_read_b128 v[204:207], v140 offset:6144
	ds_read_b128 v[214:217], v140 offset:7168
	global_load_lds_dwordx4 v[178:179], off
	v_lshl_add_u64 v[178:179], s[30:31], 0, v[138:139]
	s_add_i32 m0, s1, 0xe000
	s_nop 0
	global_load_lds_dwordx4 v[178:179], off
	s_waitcnt vmcnt(8)
	s_waitcnt lgkmcnt(0)
	s_barrier
	s_waitcnt lgkmcnt(0)
	v_mfma_f32_16x16x32_bf16 v[126:129], v[142:145], v[174:177], v[126:129]
	v_mfma_f32_16x16x32_bf16 v[126:129], v[146:149], v[184:187], v[126:129]
	v_mfma_f32_16x16x32_bf16 v[118:121], v[150:153], v[174:177], v[118:121]
	v_mfma_f32_16x16x32_bf16 v[118:121], v[154:157], v[184:187], v[118:121]
	v_mfma_f32_16x16x32_bf16 v[110:113], v[142:145], v[188:191], v[110:113]
	v_mfma_f32_16x16x32_bf16 v[110:113], v[146:149], v[192:195], v[110:113]
	v_mfma_f32_16x16x32_bf16 v[102:105], v[150:153], v[188:191], v[102:105]
	v_mfma_f32_16x16x32_bf16 v[102:105], v[154:157], v[192:195], v[102:105]
	v_mfma_f32_16x16x32_bf16 v[94:97], v[142:145], v[196:199], v[94:97]
	v_mfma_f32_16x16x32_bf16 v[94:97], v[146:149], v[200:203], v[94:97]
	v_mfma_f32_16x16x32_bf16 v[86:89], v[150:153], v[196:199], v[86:89]
	v_mfma_f32_16x16x32_bf16 v[86:89], v[154:157], v[200:203], v[86:89]
	v_mfma_f32_16x16x32_bf16 v[78:81], v[142:145], v[204:207], v[78:81]
	v_mfma_f32_16x16x32_bf16 v[78:81], v[146:149], v[214:217], v[78:81]
	v_mfma_f32_16x16x32_bf16 v[70:73], v[150:153], v[204:207], v[70:73]
	v_mfma_f32_16x16x32_bf16 v[70:73], v[154:157], v[214:217], v[70:73]
	v_mfma_f32_16x16x32_bf16 v[122:125], v[158:161], v[174:177], v[122:125]
	v_mfma_f32_16x16x32_bf16 v[122:125], v[162:165], v[184:187], v[122:125]
	v_mfma_f32_16x16x32_bf16 v[114:117], v[166:169], v[174:177], v[114:117]
	v_mfma_f32_16x16x32_bf16 v[114:117], v[170:173], v[184:187], v[114:117]
	v_mfma_f32_16x16x32_bf16 v[106:109], v[158:161], v[188:191], v[106:109]
	v_mfma_f32_16x16x32_bf16 v[106:109], v[162:165], v[192:195], v[106:109]
	v_mfma_f32_16x16x32_bf16 v[98:101], v[166:169], v[188:191], v[98:101]
	v_mfma_f32_16x16x32_bf16 v[98:101], v[170:173], v[192:195], v[98:101]
	v_mfma_f32_16x16x32_bf16 v[90:93], v[158:161], v[196:199], v[90:93]
	v_mfma_f32_16x16x32_bf16 v[90:93], v[162:165], v[200:203], v[90:93]
	v_mfma_f32_16x16x32_bf16 v[82:85], v[166:169], v[196:199], v[82:85]
	v_mfma_f32_16x16x32_bf16 v[82:85], v[170:173], v[200:203], v[82:85]
	v_mfma_f32_16x16x32_bf16 v[74:77], v[158:161], v[204:207], v[74:77]
	v_mfma_f32_16x16x32_bf16 v[74:77], v[162:165], v[214:217], v[74:77]
	v_mfma_f32_16x16x32_bf16 v[66:69], v[166:169], v[204:207], v[66:69]
	v_mfma_f32_16x16x32_bf16 v[66:69], v[170:173], v[214:217], v[66:69]
	s_barrier
	s_mov_b32 m0, s6
	v_lshl_add_u64 v[178:179], s[84:85], 0, v[0:1]
	s_add_u32 s92, s84, 0x40000
	ds_read_b128 v[174:177], v140 offset:16384
	ds_read_b128 v[184:187], v140 offset:17408
	ds_read_b128 v[188:191], v140 offset:18432
	ds_read_b128 v[192:195], v140 offset:19456
	ds_read_b128 v[196:199], v140 offset:20480
	ds_read_b128 v[200:203], v140 offset:21504
	ds_read_b128 v[204:207], v140 offset:22528
	ds_read_b128 v[214:217], v140 offset:23552
	global_load_lds_dwordx4 v[178:179], off
	v_lshl_add_u64 v[180:181], s[84:85], 0, v[130:131]
	s_mov_b32 m0, s8
	s_addc_u32 s93, s85, 0
	global_load_lds_dwordx4 v[180:181], off
	v_lshl_add_u64 v[182:183], s[92:93], 0, v[0:1]
	s_mov_b32 m0, s9
	v_lshl_add_u64 v[218:219], s[86:87], 0, v[132:133]
	global_load_lds_dwordx4 v[182:183], off
	v_lshl_add_u64 v[182:183], s[92:93], 0, v[130:131]
	s_mov_b32 m0, s14
	s_nop 0
	global_load_lds_dwordx4 v[182:183], off
	v_lshl_add_u64 v[182:183], s[86:87], 0, v[134:135]
	s_mov_b32 m0, s1
	s_nop 0
	global_load_lds_dwordx4 v[182:183], off
	s_mov_b32 m0, s34
	s_nop 0
	global_load_lds_dwordx4 v[218:219], off
	s_waitcnt vmcnt(8)
	s_waitcnt lgkmcnt(0)
	s_barrier
; #define PG8_STAGE(bufoff, gbase, voff) do { _Pragma("unroll") for (int _i = 0; _i < 2; ++_i) \
;         __builtin_amdgcn_global_load_lds((const unsigned*)((const char*)(gbase) + (voff)[_i]), (PG8_LAS unsigned*)(lds + (bufoff) + ldsw + _i * 8192), 16, 0, 0); } while (0)
; #define PG8_LDA(dst, b, h) do { _Pragma("unroll") for (int m = 0; m < 4; ++m) _Pragma("unroll") for (int k = 0; k < 2; ++k) dst[m][k] = *(const PG8_LAS bf16x8*)(lds + PG8_SA(b, h) + aoff + m * 2048 + k * 1024); } while (0)
; #define PG8_LDB(dst, b, h) do { _Pragma("unroll") for (int n = 0; n < 2; ++n) _Pragma("unroll") for (int k = 0; k < 2; ++k) dst[n][k] = *(const PG8_LAS bf16x8*)(lds + PG8_SB(b, h) + boff + n * 2048 + k * 1024); } while (0)
; #define PG8_MMA(ai, bj, At, Bt) do { __builtin_amdgcn_s_setprio(1); _Pragma("unroll") for (int m = 0; m < 4; ++m) _Pragma("unroll") for (int n = 0; n < 2; ++n) _Pragma("unroll") for (int k = 0; k < 2; ++k) \
;         acc[ai][bj][m][n] = __builtin_amdgcn_mfma_f32_16x16x32_bf16(Bt[n][k], At[m][k], acc[ai][bj][m][n], 0, 0, 0); __builtin_amdgcn_s_setprio(0); } while (0)
; #define PG8_WAIT_V(n) asm volatile("s_waitcnt vmcnt(" #n ")" ::: "memory")
; #define PG8_WAIT_L(n) asm volatile("s_waitcnt lgkmcnt(" #n ")" ::: "memory")
; #define PG8_BAR __builtin_amdgcn_s_barrier()
; #define PG8_SCHED __builtin_amdgcn_sched_barrier(0)
; template <class Epi, class Sched, bool ALIGN_EPI = false, bool SP2 = false>
; __device__ __forceinline__ void gemm_phase(PG8_LAS unsigned char* lds, const Gemm g, const Sched& S, const Epi& E, const int tid) {
;     ...
;             PG8_WAIT_V(8); PG8_WAIT_L(0); PG8_BAR; PG8_MMA(1, 0, At, B0); PG8_MMA(1, 1, At, B1); PG8_BAR; PG8_SCHED;
;             PG8_LDB(B0, 1, 0); PG8_LDB(B1, 1, 1); PG8_SCHED; PG8_LDA(At, 1, 0); PG8_STAGE(PG8_SA(0, 1), a2 + hstep, voffA);
;             PG8_WAIT_V(8); PG8_WAIT_L(0); PG8_BAR; PG8_MMA(0, 0, At, B0); PG8_MMA(0, 1, At, B1); PG8_BAR; PG8_SCHED;
	s_waitcnt lgkmcnt(0)
	v_mfma_f32_16x16x32_bf16 v[62:65], v[142:145], v[174:177], v[62:65]
	v_mfma_f32_16x16x32_bf16 v[62:65], v[146:149], v[184:187], v[62:65]
	v_mfma_f32_16x16x32_bf16 v[54:57], v[150:153], v[174:177], v[54:57]
	v_mfma_f32_16x16x32_bf16 v[54:57], v[154:157], v[184:187], v[54:57]
	v_mfma_f32_16x16x32_bf16 v[46:49], v[142:145], v[188:191], v[46:49]
	v_mfma_f32_16x16x32_bf16 v[46:49], v[146:149], v[192:195], v[46:49]
	v_mfma_f32_16x16x32_bf16 v[38:41], v[150:153], v[188:191], v[38:41]
	v_mfma_f32_16x16x32_bf16 v[38:41], v[154:157], v[192:195], v[38:41]
	v_mfma_f32_16x16x32_bf16 v[30:33], v[142:145], v[196:199], v[30:33]
	v_mfma_f32_16x16x32_bf16 v[30:33], v[146:149], v[200:203], v[30:33]
	v_mfma_f32_16x16x32_bf16 v[22:25], v[150:153], v[196:199], v[22:25]
	v_mfma_f32_16x16x32_bf16 v[22:25], v[154:157], v[200:203], v[22:25]
	v_mfma_f32_16x16x32_bf16 v[14:17], v[142:145], v[204:207], v[14:17]
	v_mfma_f32_16x16x32_bf16 v[14:17], v[146:149], v[214:217], v[14:17]
	v_mfma_f32_16x16x32_bf16 v[6:9], v[150:153], v[204:207], v[6:9]
	v_mfma_f32_16x16x32_bf16 v[6:9], v[154:157], v[214:217], v[6:9]
	v_mfma_f32_16x16x32_bf16 v[58:61], v[158:161], v[174:177], v[58:61]
	v_mfma_f32_16x16x32_bf16 v[58:61], v[162:165], v[184:187], v[58:61]
	v_mfma_f32_16x16x32_bf16 v[50:53], v[166:169], v[174:177], v[50:53]
	v_mfma_f32_16x16x32_bf16 v[50:53], v[170:173], v[184:187], v[50:53]
	v_mfma_f32_16x16x32_bf16 v[42:45], v[158:161], v[188:191], v[42:45]
	v_mfma_f32_16x16x32_bf16 v[42:45], v[162:165], v[192:195], v[42:45]
	v_mfma_f32_16x16x32_bf16 v[34:37], v[166:169], v[188:191], v[34:37]
	v_mfma_f32_16x16x32_bf16 v[34:37], v[170:173], v[192:195], v[34:37]
	v_mfma_f32_16x16x32_bf16 v[26:29], v[158:161], v[196:199], v[26:29]
	v_mfma_f32_16x16x32_bf16 v[26:29], v[162:165], v[200:203], v[26:29]
	v_mfma_f32_16x16x32_bf16 v[18:21], v[166:169], v[196:199], v[18:21]
	v_mfma_f32_16x16x32_bf16 v[18:21], v[170:173], v[200:203], v[18:21]
	v_mfma_f32_16x16x32_bf16 v[10:13], v[158:161], v[204:207], v[10:13]
	v_mfma_f32_16x16x32_bf16 v[10:13], v[162:165], v[214:217], v[10:13]
	v_mfma_f32_16x16x32_bf16 v[2:5], v[166:169], v[204:207], v[2:5]
	v_mfma_f32_16x16x32_bf16 v[2:5], v[170:173], v[214:217], v[2:5]
	s_barrier
	v_or_b32_e32 v142, 0x18000, v141
	v_add_u32_e32 v146, 0x18400, v141
	v_add_u32_e32 v150, 0x18800, v141
	v_add_u32_e32 v154, 0x18c00, v141
	v_or_b32_e32 v158, 0x1c000, v141
	v_add_u32_e32 v162, 0x1c400, v141
	v_add_u32_e32 v166, 0x1c800, v141
	v_add_u32_e32 v170, 0x1cc00, v141
	ds_read_b128 v[142:145], v142
	ds_read_b128 v[146:149], v146
	ds_read_b128 v[150:153], v150
	ds_read_b128 v[154:157], v154
	ds_read_b128 v[158:161], v158
	ds_read_b128 v[162:165], v162
	ds_read_b128 v[166:169], v166
	ds_read_b128 v[170:173], v170
	s_add_u32 s86, s86, 0x40000
	s_addc_u32 s87, s87, 0
	s_mov_b32 m0, s35
	v_lshl_add_u64 v[220:221], s[86:87], 0, v[134:135]
	ds_read_b128 v[174:177], v140 offset:32768
	ds_read_b128 v[184:187], v140 offset:33792
	ds_read_b128 v[188:191], v140 offset:34816
	ds_read_b128 v[192:195], v140 offset:35840
	ds_read_b128 v[196:199], v140 offset:36864
	ds_read_b128 v[200:203], v140 offset:37888
	ds_read_b128 v[204:207], v140 offset:38912
	ds_read_b128 v[214:217], v140 offset:39936
	global_load_lds_dwordx4 v[220:221], off
	v_lshl_add_u64 v[220:221], s[86:87], 0, v[132:133]
	s_mov_b32 m0, s88
	s_nop 0
	global_load_lds_dwordx4 v[220:221], off
	s_waitcnt vmcnt(8)
	s_waitcnt lgkmcnt(0)
	s_barrier
	s_waitcnt lgkmcnt(0)
	v_mfma_f32_16x16x32_bf16 v[126:129], v[142:145], v[174:177], v[126:129]
	v_mfma_f32_16x16x32_bf16 v[126:129], v[146:149], v[184:187], v[126:129]
	v_mfma_f32_16x16x32_bf16 v[118:121], v[150:153], v[174:177], v[118:121]
	v_mfma_f32_16x16x32_bf16 v[118:121], v[154:157], v[184:187], v[118:121]
	v_mfma_f32_16x16x32_bf16 v[110:113], v[142:145], v[188:191], v[110:113]
	v_mfma_f32_16x16x32_bf16 v[110:113], v[146:149], v[192:195], v[110:113]
	v_mfma_f32_16x16x32_bf16 v[102:105], v[150:153], v[188:191], v[102:105]
	v_mfma_f32_16x16x32_bf16 v[102:105], v[154:157], v[192:195], v[102:105]
	v_mfma_f32_16x16x32_bf16 v[94:97], v[142:145], v[196:199], v[94:97]
	v_mfma_f32_16x16x32_bf16 v[94:97], v[146:149], v[200:203], v[94:97]
	v_mfma_f32_16x16x32_bf16 v[86:89], v[150:153], v[196:199], v[86:89]
	v_mfma_f32_16x16x32_bf16 v[86:89], v[154:157], v[200:203], v[86:89]
	v_mfma_f32_16x16x32_bf16 v[78:81], v[142:145], v[204:207], v[78:81]
	v_mfma_f32_16x16x32_bf16 v[78:81], v[146:149], v[214:217], v[78:81]
	v_mfma_f32_16x16x32_bf16 v[70:73], v[150:153], v[204:207], v[70:73]
	v_mfma_f32_16x16x32_bf16 v[70:73], v[154:157], v[214:217], v[70:73]
	v_mfma_f32_16x16x32_bf16 v[122:125], v[158:161], v[174:177], v[122:125]
	v_mfma_f32_16x16x32_bf16 v[122:125], v[162:165], v[184:187], v[122:125]
	v_mfma_f32_16x16x32_bf16 v[114:117], v[166:169], v[174:177], v[114:117]
	v_mfma_f32_16x16x32_bf16 v[114:117], v[170:173], v[184:187], v[114:117]
	v_mfma_f32_16x16x32_bf16 v[106:109], v[158:161], v[188:191], v[106:109]
	v_mfma_f32_16x16x32_bf16 v[106:109], v[162:165], v[192:195], v[106:109]
	v_mfma_f32_16x16x32_bf16 v[98:101], v[166:169], v[188:191], v[98:101]
	v_mfma_f32_16x16x32_bf16 v[98:101], v[170:173], v[192:195], v[98:101]
	v_mfma_f32_16x16x32_bf16 v[90:93], v[158:161], v[196:199], v[90:93]
	v_mfma_f32_16x16x32_bf16 v[90:93], v[162:165], v[200:203], v[90:93]
	v_mfma_f32_16x16x32_bf16 v[82:85], v[166:169], v[196:199], v[82:85]
	v_mfma_f32_16x16x32_bf16 v[82:85], v[170:173], v[200:203], v[82:85]
	v_mfma_f32_16x16x32_bf16 v[74:77], v[158:161], v[204:207], v[74:77]
	v_mfma_f32_16x16x32_bf16 v[74:77], v[162:165], v[214:217], v[74:77]
	v_mfma_f32_16x16x32_bf16 v[66:69], v[166:169], v[204:207], v[66:69]
	v_mfma_f32_16x16x32_bf16 v[66:69], v[170:173], v[214:217], v[66:69]
	s_barrier
; #define PG8_STAGE(bufoff, gbase, voff) do { _Pragma("unroll") for (int _i = 0; _i < 2; ++_i) \
;         __builtin_amdgcn_global_load_lds((const unsigned*)((const char*)(gbase) + (voff)[_i]), (PG8_LAS unsigned*)(lds + (bufoff) + ldsw + _i * 8192), 16, 0, 0); } while (0)
; #define PG8_LDA(dst, b, h) do { _Pragma("unroll") for (int m = 0; m < 4; ++m) _Pragma("unroll") for (int k = 0; k < 2; ++k) dst[m][k] = *(const PG8_LAS bf16x8*)(lds + PG8_SA(b, h) + aoff + m * 2048 + k * 1024); } while (0)
; #define PG8_MMA(ai, bj, At, Bt) do { __builtin_amdgcn_s_setprio(1); _Pragma("unroll") for (int m = 0; m < 4; ++m) _Pragma("unroll") for (int n = 0; n < 2; ++n) _Pragma("unroll") for (int k = 0; k < 2; ++k) \
;         acc[ai][bj][m][n] = __builtin_amdgcn_mfma_f32_16x16x32_bf16(Bt[n][k], At[m][k], acc[ai][bj][m][n], 0, 0, 0); __builtin_amdgcn_s_setprio(0); } while (0)
; #define PG8_WAIT_V(n) asm volatile("s_waitcnt vmcnt(" #n ")" ::: "memory")
; #define PG8_WAIT_L(n) asm volatile("s_waitcnt lgkmcnt(" #n ")" ::: "memory")
; #define PG8_BAR __builtin_amdgcn_s_barrier()
; #define PG8_SCHED __builtin_amdgcn_sched_barrier(0)
; template <class Epi, class Sched, bool ALIGN_EPI = false, bool SP2 = false>
; __device__ __forceinline__ void gemm_phase(PG8_LAS unsigned char* lds, const Gemm g, const Sched& S, const Epi& E, const int tid) {
;     ...
;             PG8_LDA(At, 1, 1); PG8_STAGE(PG8_SB(1, 0), b3, voffB); PG8_STAGE(PG8_SB(1, 1), b3 + hstep, voffB); PG8_STAGE(PG8_SA(1, 0), a3, voffA);
;             PG8_WAIT_V(8); PG8_WAIT_L(0); PG8_BAR; PG8_MMA(1, 0, At, B0); PG8_MMA(1, 1, At, B1); PG8_BAR; PG8_SCHED;
	s_mov_b32 m0, s0
	v_lshl_add_u64 v[178:179], v[178:179], 0, s[12:13]
	s_add_u32 s84, s84, 0x40080
	ds_read_b128 v[174:177], v140 offset:49152
	ds_read_b128 v[184:187], v140 offset:50176
	ds_read_b128 v[188:191], v140 offset:51200
	ds_read_b128 v[192:195], v140 offset:52224
	ds_read_b128 v[196:199], v140 offset:53248
	ds_read_b128 v[200:203], v140 offset:54272
	ds_read_b128 v[204:207], v140 offset:55296
	ds_read_b128 v[214:217], v140 offset:56320
	global_load_lds_dwordx4 v[178:179], off
	v_lshl_add_u64 v[178:179], v[180:181], 0, s[12:13]
	s_mov_b32 m0, s17
	s_addc_u32 s85, s85, 0
	global_load_lds_dwordx4 v[178:179], off
	v_lshl_add_u64 v[178:179], s[84:85], 0, v[0:1]
	s_mov_b32 m0, s51
	s_nop 0
	global_load_lds_dwordx4 v[178:179], off
	v_lshl_add_u64 v[178:179], s[84:85], 0, v[130:131]
	s_mov_b32 m0, s26
	s_nop 0
	global_load_lds_dwordx4 v[178:179], off
	v_lshl_add_u64 v[178:179], v[182:183], 0, s[12:13]
	s_mov_b32 m0, s91
	s_nop 0
	global_load_lds_dwordx4 v[178:179], off
	v_lshl_add_u64 v[178:179], v[218:219], 0, s[12:13]
	s_mov_b32 m0, s50
	s_nop 0
	global_load_lds_dwordx4 v[178:179], off
	s_waitcnt vmcnt(8)
	s_waitcnt lgkmcnt(0)
	s_barrier
	s_waitcnt lgkmcnt(0)
	v_mfma_f32_16x16x32_bf16 v[62:65], v[142:145], v[174:177], v[62:65]
	v_mfma_f32_16x16x32_bf16 v[62:65], v[146:149], v[184:187], v[62:65]
	v_mfma_f32_16x16x32_bf16 v[54:57], v[150:153], v[174:177], v[54:57]
	v_mfma_f32_16x16x32_bf16 v[54:57], v[154:157], v[184:187], v[54:57]
	v_mfma_f32_16x16x32_bf16 v[46:49], v[142:145], v[188:191], v[46:49]
	v_mfma_f32_16x16x32_bf16 v[46:49], v[146:149], v[192:195], v[46:49]
	v_mfma_f32_16x16x32_bf16 v[38:41], v[150:153], v[188:191], v[38:41]
	v_mfma_f32_16x16x32_bf16 v[38:41], v[154:157], v[192:195], v[38:41]
	v_mfma_f32_16x16x32_bf16 v[30:33], v[142:145], v[196:199], v[30:33]
	v_mfma_f32_16x16x32_bf16 v[30:33], v[146:149], v[200:203], v[30:33]
	v_mfma_f32_16x16x32_bf16 v[22:25], v[150:153], v[196:199], v[22:25]
	v_mfma_f32_16x16x32_bf16 v[22:25], v[154:157], v[200:203], v[22:25]
	v_mfma_f32_16x16x32_bf16 v[14:17], v[142:145], v[204:207], v[14:17]
	v_mfma_f32_16x16x32_bf16 v[14:17], v[146:149], v[214:217], v[14:17]
	v_mfma_f32_16x16x32_bf16 v[6:9], v[150:153], v[204:207], v[6:9]
	v_mfma_f32_16x16x32_bf16 v[6:9], v[154:157], v[214:217], v[6:9]
	v_mfma_f32_16x16x32_bf16 v[58:61], v[158:161], v[174:177], v[58:61]
	v_mfma_f32_16x16x32_bf16 v[58:61], v[162:165], v[184:187], v[58:61]
	v_mfma_f32_16x16x32_bf16 v[50:53], v[166:169], v[174:177], v[50:53]
	v_mfma_f32_16x16x32_bf16 v[50:53], v[170:173], v[184:187], v[50:53]
	v_mfma_f32_16x16x32_bf16 v[42:45], v[158:161], v[188:191], v[42:45]
	v_mfma_f32_16x16x32_bf16 v[42:45], v[162:165], v[192:195], v[42:45]
	v_mfma_f32_16x16x32_bf16 v[34:37], v[166:169], v[188:191], v[34:37]
	v_mfma_f32_16x16x32_bf16 v[34:37], v[170:173], v[192:195], v[34:37]
	v_mfma_f32_16x16x32_bf16 v[26:29], v[158:161], v[196:199], v[26:29]
	v_mfma_f32_16x16x32_bf16 v[26:29], v[162:165], v[200:203], v[26:29]
	v_mfma_f32_16x16x32_bf16 v[18:21], v[166:169], v[196:199], v[18:21]
	v_mfma_f32_16x16x32_bf16 v[18:21], v[170:173], v[200:203], v[18:21]
	v_mfma_f32_16x16x32_bf16 v[10:13], v[158:161], v[204:207], v[10:13]
	v_mfma_f32_16x16x32_bf16 v[10:13], v[162:165], v[214:217], v[10:13]
	v_mfma_f32_16x16x32_bf16 v[2:5], v[166:169], v[204:207], v[2:5]
	v_mfma_f32_16x16x32_bf16 v[2:5], v[170:173], v[214:217], v[2:5]
	s_barrier
	s_add_i32 s43, s43, 2
	s_add_u32 s30, s30, 0x100
	s_addc_u32 s31, s31, 0
	s_add_u32 s24, s24, 0x100
	s_addc_u32 s41, s41, 0
	s_cmp_gt_u32 s43, 13
	s_cbranch_scc0 .LBB0_713
	s_and_b64 vcc, exec, s[38:39]
	s_cbranch_vccz .LBB0_716
	s_barrier
